# speedup vs baseline: 1.0008x; 1.0008x over previous
; #define STAGE(Pp, BASE, br, kt) do { const u16* _g = (BASE) + ((long)(br) * K + (long)(kt) * BK); \
;     __builtin_amdgcn_global_load_lds((const unsigned*)(_g + voff0), (unsigned*)((char*)(Pp) + tb16), 16, 0, 0); \
;     __builtin_amdgcn_global_load_lds((const unsigned*)(_g + voff1), (unsigned*)((char*)(Pp) + tb16 + 8192), 16, 0, 0); } while (0)
; #define LDA(dst, b, h) _Pragma("unroll") for (int m = 0; m < 4; ++m) _Pragma("unroll") for (int k = 0; k < 2; ++k) \
;     dst[m][k] = *reinterpret_cast<const bf16x8*>((const char*)shm + aB + (((b) * 2 + (h)) * 16384 + (m * 2 + k) * 1024))
; #define LDB(dst, b, h) _Pragma("unroll") for (int n = 0; n < 2; ++n) _Pragma("unroll") for (int k = 0; k < 2; ++k) \
;     dst[n][k] = *reinterpret_cast<const bf16x8*>((const char*)shm + bB + (((b) * 2 + (h)) * 16384 + (n * 2 + k) * 1024))
; #define WAIT_V(n) asm volatile("s_waitcnt vmcnt(" #n ")" ::: "memory")
; #define WAIT_L(n) asm volatile("s_waitcnt lgkmcnt(" #n ")" ::: "memory")
; #define BAR __builtin_amdgcn_s_barrier()
; #define SCHED __builtin_amdgcn_sched_barrier(0)
; template <int MODE> ...
;     ...
;       LDB(B0, 0, 0); LDB(B1, 0, 1); LDA(At, 0, 0); STAGE(SA(1, 1), A, brow + HALF, t + 1);
;       WAIT_L(0); BAR; MMA2(0, 0, 0, 1); BAR; SCHED;
;       LDA(At, 0, 1); STAGE(SB(0, 0), Bt, bcol, t + 2); STAGE(SB(0, 1), Bt, bcol + HALF, t + 2); STAGE(SA(0, 0), A, brow, t + 2);
;       WAIT_V(6); WAIT_L(0); BAR; MMA2(1, 0, 1, 1); BAR; SCHED;
.LBB0_154:
	s_add_u32 m0, s32, 0xc000
	s_add_u32 s88, s74, s40
	s_addc_u32 s89, s75, s41
	global_load_lds_dwordx4 v142, s[88:89]
	s_add_u32 m0, s32, 0xe000
	s_nop 0
	global_load_lds_dwordx4 v144, s[88:89]
	ds_read_b128 v[170:173], v149
	ds_read_b128 v[174:177], v149 offset:1024
	ds_read_b128 v[178:181], v149 offset:2048
	ds_read_b128 v[182:185], v149 offset:3072
	ds_read_b128 v[186:189], v149 offset:16384
	ds_read_b128 v[190:193], v149 offset:17408
	ds_read_b128 v[194:197], v149 offset:18432
	ds_read_b128 v[198:201], v149 offset:19456
	ds_read_b128 v[202:205], v151
	ds_read_b128 v[206:209], v151 offset:1024
	ds_read_b128 v[210:213], v151 offset:2048
	ds_read_b128 v[214:217], v151 offset:3072
	ds_read_b128 v[218:221], v151 offset:4096
	ds_read_b128 v[222:225], v151 offset:5120
	ds_read_b128 v[226:229], v151 offset:6144
	ds_read_b128 v[230:233], v151 offset:7168
	s_waitcnt vmcnt(8)
	s_waitcnt lgkmcnt(0)
	s_setprio 1
	s_barrier
	v_mfma_f32_16x16x32_bf16 v[124:127], v[202:205], v[170:173], v[124:127]
	v_mfma_f32_16x16x32_bf16 v[120:123], v[202:205], v[178:181], v[120:123]
	v_mfma_f32_16x16x32_bf16 v[116:119], v[210:213], v[170:173], v[116:119]
	v_mfma_f32_16x16x32_bf16 v[112:115], v[210:213], v[178:181], v[112:115]
	v_mfma_f32_16x16x32_bf16 v[108:111], v[218:221], v[170:173], v[108:111]
	v_mfma_f32_16x16x32_bf16 v[104:107], v[218:221], v[178:181], v[104:107]
	v_mfma_f32_16x16x32_bf16 v[100:103], v[226:229], v[170:173], v[100:103]
	v_mfma_f32_16x16x32_bf16 v[96:99], v[226:229], v[178:181], v[96:99]
	v_mfma_f32_16x16x32_bf16 v[92:95], v[202:205], v[186:189], v[92:95]
	v_mfma_f32_16x16x32_bf16 v[88:91], v[202:205], v[194:197], v[88:91]
	v_mfma_f32_16x16x32_bf16 v[84:87], v[210:213], v[186:189], v[84:87]
	v_mfma_f32_16x16x32_bf16 v[80:83], v[210:213], v[194:197], v[80:83]
	v_mfma_f32_16x16x32_bf16 v[76:79], v[218:221], v[186:189], v[76:79]
	v_mfma_f32_16x16x32_bf16 v[72:75], v[218:221], v[194:197], v[72:75]
	v_mfma_f32_16x16x32_bf16 v[68:71], v[226:229], v[186:189], v[68:71]
	v_mfma_f32_16x16x32_bf16 v[64:67], v[226:229], v[194:197], v[64:67]
	v_mfma_f32_16x16x32_bf16 v[124:127], v[206:209], v[174:177], v[124:127]
	v_mfma_f32_16x16x32_bf16 v[120:123], v[206:209], v[182:185], v[120:123]
	v_mfma_f32_16x16x32_bf16 v[116:119], v[214:217], v[174:177], v[116:119]
	v_mfma_f32_16x16x32_bf16 v[112:115], v[214:217], v[182:185], v[112:115]
	v_mfma_f32_16x16x32_bf16 v[108:111], v[222:225], v[174:177], v[108:111]
	v_mfma_f32_16x16x32_bf16 v[104:107], v[222:225], v[182:185], v[104:107]
	v_mfma_f32_16x16x32_bf16 v[100:103], v[230:233], v[174:177], v[100:103]
	v_mfma_f32_16x16x32_bf16 v[96:99], v[230:233], v[182:185], v[96:99]
	v_mfma_f32_16x16x32_bf16 v[92:95], v[206:209], v[190:193], v[92:95]
	v_mfma_f32_16x16x32_bf16 v[88:91], v[206:209], v[198:201], v[88:91]
	v_mfma_f32_16x16x32_bf16 v[84:87], v[214:217], v[190:193], v[84:87]
	v_mfma_f32_16x16x32_bf16 v[80:83], v[214:217], v[198:201], v[80:83]
	v_mfma_f32_16x16x32_bf16 v[76:79], v[222:225], v[190:193], v[76:79]
	v_mfma_f32_16x16x32_bf16 v[72:75], v[222:225], v[198:201], v[72:75]
	v_mfma_f32_16x16x32_bf16 v[68:71], v[230:233], v[190:193], v[68:71]
	v_mfma_f32_16x16x32_bf16 v[64:67], v[230:233], v[198:201], v[64:67]
	s_barrier
	s_setprio 0
	s_add_u32 m0, s32, 0x10000
	s_add_u32 s88, s74, s42
	s_addc_u32 s89, s75, s43
	global_load_lds_dwordx4 v138, s[88:89]
	s_add_u32 m0, s32, 0x12000
	s_add_u32 s90, s74, s44
	s_addc_u32 s91, s75, s45
	global_load_lds_dwordx4 v140, s[88:89]
	s_add_u32 m0, s32, 0x14000
	s_add_u32 s92, s74, s48
	s_addc_u32 s93, s75, s49
	global_load_lds_dwordx4 v138, s[90:91]
	s_add_u32 m0, s32, 0x16000
	s_nop 0
	global_load_lds_dwordx4 v140, s[90:91]
	s_mov_b32 m0, s32
	s_nop 0
	global_load_lds_dwordx4 v142, s[92:93]
	s_add_u32 m0, s32, 0x2000
	s_nop 0
	global_load_lds_dwordx4 v144, s[92:93]
	ds_read_b128 v[202:205], v151 offset:16384
	ds_read_b128 v[206:209], v151 offset:17408
	ds_read_b128 v[210:213], v151 offset:18432
	ds_read_b128 v[214:217], v151 offset:19456
	ds_read_b128 v[218:221], v151 offset:20480
	ds_read_b128 v[222:225], v151 offset:21504
	ds_read_b128 v[226:229], v151 offset:22528
	ds_read_b128 v[230:233], v151 offset:23552
	s_waitcnt vmcnt(8)
	s_waitcnt lgkmcnt(0)
	s_setprio 1
	s_barrier
	v_mfma_f32_16x16x32_bf16 v[60:63], v[202:205], v[170:173], v[60:63]
	v_mfma_f32_16x16x32_bf16 v[56:59], v[202:205], v[178:181], v[56:59]
	v_mfma_f32_16x16x32_bf16 v[52:55], v[210:213], v[170:173], v[52:55]
	v_mfma_f32_16x16x32_bf16 v[48:51], v[210:213], v[178:181], v[48:51]
	v_mfma_f32_16x16x32_bf16 v[44:47], v[218:221], v[170:173], v[44:47]
	v_mfma_f32_16x16x32_bf16 v[40:43], v[218:221], v[178:181], v[40:43]
	v_mfma_f32_16x16x32_bf16 v[36:39], v[226:229], v[170:173], v[36:39]
	v_mfma_f32_16x16x32_bf16 v[32:35], v[226:229], v[178:181], v[32:35]
	v_mfma_f32_16x16x32_bf16 v[28:31], v[202:205], v[186:189], v[28:31]
	v_mfma_f32_16x16x32_bf16 v[24:27], v[202:205], v[194:197], v[24:27]
	v_mfma_f32_16x16x32_bf16 v[20:23], v[210:213], v[186:189], v[20:23]
	v_mfma_f32_16x16x32_bf16 v[16:19], v[210:213], v[194:197], v[16:19]
	v_mfma_f32_16x16x32_bf16 v[12:15], v[218:221], v[186:189], v[12:15]
	v_mfma_f32_16x16x32_bf16 v[8:11], v[218:221], v[194:197], v[8:11]
	v_mfma_f32_16x16x32_bf16 v[4:7], v[226:229], v[186:189], v[4:7]
	v_mfma_f32_16x16x32_bf16 v[0:3], v[226:229], v[194:197], v[0:3]
	v_mfma_f32_16x16x32_bf16 v[60:63], v[206:209], v[174:177], v[60:63]
	v_mfma_f32_16x16x32_bf16 v[56:59], v[206:209], v[182:185], v[56:59]
	v_mfma_f32_16x16x32_bf16 v[52:55], v[214:217], v[174:177], v[52:55]
	v_mfma_f32_16x16x32_bf16 v[48:51], v[214:217], v[182:185], v[48:51]
	v_mfma_f32_16x16x32_bf16 v[44:47], v[222:225], v[174:177], v[44:47]
	v_mfma_f32_16x16x32_bf16 v[40:43], v[222:225], v[182:185], v[40:43]
	v_mfma_f32_16x16x32_bf16 v[36:39], v[230:233], v[174:177], v[36:39]
	v_mfma_f32_16x16x32_bf16 v[32:35], v[230:233], v[182:185], v[32:35]
	v_mfma_f32_16x16x32_bf16 v[28:31], v[206:209], v[190:193], v[28:31]
	v_mfma_f32_16x16x32_bf16 v[24:27], v[206:209], v[198:201], v[24:27]
	v_mfma_f32_16x16x32_bf16 v[20:23], v[214:217], v[190:193], v[20:23]
	v_mfma_f32_16x16x32_bf16 v[16:19], v[214:217], v[198:201], v[16:19]
	v_mfma_f32_16x16x32_bf16 v[12:15], v[222:225], v[190:193], v[12:15]
	v_mfma_f32_16x16x32_bf16 v[8:11], v[222:225], v[198:201], v[8:11]
	v_mfma_f32_16x16x32_bf16 v[4:7], v[230:233], v[190:193], v[4:7]
	v_mfma_f32_16x16x32_bf16 v[0:3], v[230:233], v[198:201], v[0:3]
	s_barrier
; #define STAGE(Pp, BASE, br, kt) do { const u16* _g = (BASE) + ((long)(br) * K + (long)(kt) * BK); \
;     __builtin_amdgcn_global_load_lds((const unsigned*)(_g + voff0), (unsigned*)((char*)(Pp) + tb16), 16, 0, 0); \
;     __builtin_amdgcn_global_load_lds((const unsigned*)(_g + voff1), (unsigned*)((char*)(Pp) + tb16 + 8192), 16, 0, 0); } while (0)
; #define LDA(dst, b, h) _Pragma("unroll") for (int m = 0; m < 4; ++m) _Pragma("unroll") for (int k = 0; k < 2; ++k) \
;     dst[m][k] = *reinterpret_cast<const bf16x8*>((const char*)shm + aB + (((b) * 2 + (h)) * 16384 + (m * 2 + k) * 1024))
; #define LDB(dst, b, h) _Pragma("unroll") for (int n = 0; n < 2; ++n) _Pragma("unroll") for (int k = 0; k < 2; ++k) \
;     dst[n][k] = *reinterpret_cast<const bf16x8*>((const char*)shm + bB + (((b) * 2 + (h)) * 16384 + (n * 2 + k) * 1024))
; #define WAIT_V(n) asm volatile("s_waitcnt vmcnt(" #n ")" ::: "memory")
; #define WAIT_L(n) asm volatile("s_waitcnt lgkmcnt(" #n ")" ::: "memory")
; #define BAR __builtin_amdgcn_s_barrier()
; #define SCHED __builtin_amdgcn_sched_barrier(0)
; template <int MODE> ...
;     ...
;       LDB(B0, 1, 0); LDB(B1, 1, 1); LDA(At, 1, 0); STAGE(SA(0, 1), A, brow + HALF, t + 2);
;       WAIT_L(0); BAR; MMA2(0, 0, 0, 1); BAR; SCHED;
;       LDA(At, 1, 1); STAGE(SB(1, 0), Bt, bcol, t + 3); STAGE(SB(1, 1), Bt, bcol + HALF, t + 3); STAGE(SA(1, 0), A, brow, t + 3);
;       WAIT_V(6); WAIT_L(0); BAR; MMA2(1, 0, 1, 1); BAR; SCHED;
	s_setprio 0
	s_add_u32 m0, s32, 0x4000
	s_add_u32 s88, s74, s50
	s_addc_u32 s89, s75, s51
	global_load_lds_dwordx4 v142, s[88:89]
	s_add_u32 m0, s32, 0x6000
	s_nop 0
	global_load_lds_dwordx4 v144, s[88:89]
	ds_read_b128 v[170:173], v149 offset:32768
	ds_read_b128 v[174:177], v149 offset:33792
	ds_read_b128 v[178:181], v149 offset:34816
	ds_read_b128 v[182:185], v149 offset:35840
	ds_read_b128 v[186:189], v149 offset:49152
	ds_read_b128 v[190:193], v149 offset:50176
	ds_read_b128 v[194:197], v149 offset:51200
	ds_read_b128 v[198:201], v149 offset:52224
	ds_read_b128 v[202:205], v151 offset:32768
	ds_read_b128 v[206:209], v151 offset:33792
	ds_read_b128 v[210:213], v151 offset:34816
	ds_read_b128 v[214:217], v151 offset:35840
	ds_read_b128 v[218:221], v151 offset:36864
	ds_read_b128 v[222:225], v151 offset:37888
	ds_read_b128 v[226:229], v151 offset:38912
	ds_read_b128 v[230:233], v151 offset:39936
	s_waitcnt vmcnt(8)
	s_waitcnt lgkmcnt(0)
	s_setprio 1
	s_barrier
	v_mfma_f32_16x16x32_bf16 v[124:127], v[202:205], v[170:173], v[124:127]
	v_mfma_f32_16x16x32_bf16 v[120:123], v[202:205], v[178:181], v[120:123]
	v_mfma_f32_16x16x32_bf16 v[116:119], v[210:213], v[170:173], v[116:119]
	v_mfma_f32_16x16x32_bf16 v[112:115], v[210:213], v[178:181], v[112:115]
	v_mfma_f32_16x16x32_bf16 v[108:111], v[218:221], v[170:173], v[108:111]
	v_mfma_f32_16x16x32_bf16 v[104:107], v[218:221], v[178:181], v[104:107]
	v_mfma_f32_16x16x32_bf16 v[100:103], v[226:229], v[170:173], v[100:103]
	v_mfma_f32_16x16x32_bf16 v[96:99], v[226:229], v[178:181], v[96:99]
	v_mfma_f32_16x16x32_bf16 v[92:95], v[202:205], v[186:189], v[92:95]
	v_mfma_f32_16x16x32_bf16 v[88:91], v[202:205], v[194:197], v[88:91]
	v_mfma_f32_16x16x32_bf16 v[84:87], v[210:213], v[186:189], v[84:87]
	v_mfma_f32_16x16x32_bf16 v[80:83], v[210:213], v[194:197], v[80:83]
	v_mfma_f32_16x16x32_bf16 v[76:79], v[218:221], v[186:189], v[76:79]
	v_mfma_f32_16x16x32_bf16 v[72:75], v[218:221], v[194:197], v[72:75]
	v_mfma_f32_16x16x32_bf16 v[68:71], v[226:229], v[186:189], v[68:71]
	v_mfma_f32_16x16x32_bf16 v[64:67], v[226:229], v[194:197], v[64:67]
	v_mfma_f32_16x16x32_bf16 v[124:127], v[206:209], v[174:177], v[124:127]
	v_mfma_f32_16x16x32_bf16 v[120:123], v[206:209], v[182:185], v[120:123]
	v_mfma_f32_16x16x32_bf16 v[116:119], v[214:217], v[174:177], v[116:119]
	v_mfma_f32_16x16x32_bf16 v[112:115], v[214:217], v[182:185], v[112:115]
	v_mfma_f32_16x16x32_bf16 v[108:111], v[222:225], v[174:177], v[108:111]
	v_mfma_f32_16x16x32_bf16 v[104:107], v[222:225], v[182:185], v[104:107]
	v_mfma_f32_16x16x32_bf16 v[100:103], v[230:233], v[174:177], v[100:103]
	v_mfma_f32_16x16x32_bf16 v[96:99], v[230:233], v[182:185], v[96:99]
	v_mfma_f32_16x16x32_bf16 v[92:95], v[206:209], v[190:193], v[92:95]
	v_mfma_f32_16x16x32_bf16 v[88:91], v[206:209], v[198:201], v[88:91]
	v_mfma_f32_16x16x32_bf16 v[84:87], v[214:217], v[190:193], v[84:87]
	v_mfma_f32_16x16x32_bf16 v[80:83], v[214:217], v[198:201], v[80:83]
	v_mfma_f32_16x16x32_bf16 v[76:79], v[222:225], v[190:193], v[76:79]
	v_mfma_f32_16x16x32_bf16 v[72:75], v[222:225], v[198:201], v[72:75]
	v_mfma_f32_16x16x32_bf16 v[68:71], v[230:233], v[190:193], v[68:71]
	v_mfma_f32_16x16x32_bf16 v[64:67], v[230:233], v[198:201], v[64:67]
	s_barrier
	s_setprio 0
	s_add_u32 m0, s32, 0x18000
	s_add_u32 s88, s74, s60
	s_addc_u32 s89, s75, s61
	global_load_lds_dwordx4 v138, s[88:89]
	s_add_u32 m0, s32, 0x1a000
	s_add_u32 s90, s74, s62
	s_addc_u32 s91, s75, s63
	global_load_lds_dwordx4 v140, s[88:89]
	s_add_u32 m0, s32, 0x1c000
	s_add_u32 s92, s74, s64
	s_addc_u32 s93, s75, s65
	global_load_lds_dwordx4 v138, s[90:91]
	s_add_u32 m0, s32, 0x1e000
	s_nop 0
	global_load_lds_dwordx4 v140, s[90:91]
	s_add_u32 m0, s32, 0x8000
	s_nop 0
	global_load_lds_dwordx4 v142, s[92:93]
	s_add_u32 m0, s32, 0xa000
	s_nop 0
	global_load_lds_dwordx4 v144, s[92:93]
	ds_read_b128 v[202:205], v151 offset:49152
	ds_read_b128 v[206:209], v151 offset:50176
	ds_read_b128 v[210:213], v151 offset:51200
	ds_read_b128 v[214:217], v151 offset:52224
	ds_read_b128 v[218:221], v151 offset:53248
	ds_read_b128 v[222:225], v151 offset:54272
	ds_read_b128 v[226:229], v151 offset:55296
	ds_read_b128 v[230:233], v151 offset:56320
	s_waitcnt vmcnt(8)
	s_waitcnt lgkmcnt(0)
	s_setprio 1
	s_barrier
	v_mfma_f32_16x16x32_bf16 v[60:63], v[202:205], v[170:173], v[60:63]
	v_mfma_f32_16x16x32_bf16 v[56:59], v[202:205], v[178:181], v[56:59]
	v_mfma_f32_16x16x32_bf16 v[52:55], v[210:213], v[170:173], v[52:55]
	v_mfma_f32_16x16x32_bf16 v[48:51], v[210:213], v[178:181], v[48:51]
	v_mfma_f32_16x16x32_bf16 v[44:47], v[218:221], v[170:173], v[44:47]
	v_mfma_f32_16x16x32_bf16 v[40:43], v[218:221], v[178:181], v[40:43]
	v_mfma_f32_16x16x32_bf16 v[36:39], v[226:229], v[170:173], v[36:39]
	v_mfma_f32_16x16x32_bf16 v[32:35], v[226:229], v[178:181], v[32:35]
	v_mfma_f32_16x16x32_bf16 v[28:31], v[202:205], v[186:189], v[28:31]
	v_mfma_f32_16x16x32_bf16 v[24:27], v[202:205], v[194:197], v[24:27]
	v_mfma_f32_16x16x32_bf16 v[20:23], v[210:213], v[186:189], v[20:23]
	v_mfma_f32_16x16x32_bf16 v[16:19], v[210:213], v[194:197], v[16:19]
	v_mfma_f32_16x16x32_bf16 v[12:15], v[218:221], v[186:189], v[12:15]
	v_mfma_f32_16x16x32_bf16 v[8:11], v[218:221], v[194:197], v[8:11]
	v_mfma_f32_16x16x32_bf16 v[4:7], v[226:229], v[186:189], v[4:7]
	v_mfma_f32_16x16x32_bf16 v[0:3], v[226:229], v[194:197], v[0:3]
	v_mfma_f32_16x16x32_bf16 v[60:63], v[206:209], v[174:177], v[60:63]
	v_mfma_f32_16x16x32_bf16 v[56:59], v[206:209], v[182:185], v[56:59]
	v_mfma_f32_16x16x32_bf16 v[52:55], v[214:217], v[174:177], v[52:55]
	v_mfma_f32_16x16x32_bf16 v[48:51], v[214:217], v[182:185], v[48:51]
	v_mfma_f32_16x16x32_bf16 v[44:47], v[222:225], v[174:177], v[44:47]
	v_mfma_f32_16x16x32_bf16 v[40:43], v[222:225], v[182:185], v[40:43]
	v_mfma_f32_16x16x32_bf16 v[36:39], v[230:233], v[174:177], v[36:39]
	v_mfma_f32_16x16x32_bf16 v[32:35], v[230:233], v[182:185], v[32:35]
	v_mfma_f32_16x16x32_bf16 v[28:31], v[206:209], v[190:193], v[28:31]
	v_mfma_f32_16x16x32_bf16 v[24:27], v[206:209], v[198:201], v[24:27]
	v_mfma_f32_16x16x32_bf16 v[20:23], v[214:217], v[190:193], v[20:23]
	v_mfma_f32_16x16x32_bf16 v[16:19], v[214:217], v[198:201], v[16:19]
	v_mfma_f32_16x16x32_bf16 v[12:15], v[222:225], v[190:193], v[12:15]
	v_mfma_f32_16x16x32_bf16 v[8:11], v[222:225], v[198:201], v[8:11]
	v_mfma_f32_16x16x32_bf16 v[4:7], v[230:233], v[190:193], v[4:7]
	v_mfma_f32_16x16x32_bf16 v[0:3], v[230:233], v[198:201], v[0:3]
	s_barrier
; #define STAGE(Pp, BASE, br, kt) do { const u16* _g = (BASE) + ((long)(br) * K + (long)(kt) * BK); \
;     __builtin_amdgcn_global_load_lds((const unsigned*)(_g + voff0), (unsigned*)((char*)(Pp) + tb16), 16, 0, 0); \
;     __builtin_amdgcn_global_load_lds((const unsigned*)(_g + voff1), (unsigned*)((char*)(Pp) + tb16 + 8192), 16, 0, 0); } while (0)
; #define LDA(dst, b, h) _Pragma("unroll") for (int m = 0; m < 4; ++m) _Pragma("unroll") for (int k = 0; k < 2; ++k) \
;     dst[m][k] = *reinterpret_cast<const bf16x8*>((const char*)shm + aB + (((b) * 2 + (h)) * 16384 + (m * 2 + k) * 1024))
; #define LDB(dst, b, h) _Pragma("unroll") for (int n = 0; n < 2; ++n) _Pragma("unroll") for (int k = 0; k < 2; ++k) \
;     dst[n][k] = *reinterpret_cast<const bf16x8*>((const char*)shm + bB + (((b) * 2 + (h)) * 16384 + (n * 2 + k) * 1024))
; #define WAIT_V(n) asm volatile("s_waitcnt vmcnt(" #n ")" ::: "memory")
; #define WAIT_L(n) asm volatile("s_waitcnt lgkmcnt(" #n ")" ::: "memory")
; #define BAR __builtin_amdgcn_s_barrier()
; #define SCHED __builtin_amdgcn_sched_barrier(0)
; template <int MODE> ...
;     ...
;       LDA(At, 1, 1); STAGE(SB(1, 0), Bt, bcol, t + 3); STAGE(SB(1, 1), Bt, bcol + HALF, t + 3); STAGE(SA(1, 0), A, brow, t + 3);
;       WAIT_V(6); WAIT_L(0); BAR; MMA2(1, 0, 1, 1); BAR; SCHED;
;     }
;     {
;       LDB(B0, 0, 0); LDB(B1, 0, 1); LDA(At, 0, 0); STAGE(SA(1, 1), A, brow + HALF, nt - 1);
;       WAIT_L(0); BAR; MMA2(0, 0, 0, 1); BAR; SCHED;
;       LDA(At, 0, 1); WAIT_V(0); WAIT_L(0); BAR; MMA2(1, 0, 1, 1); BAR; SCHED;
	s_setprio 0
	s_add_i32 s69, s69, 2
	s_add_u32 s74, s74, 0x100
	s_addc_u32 s75, s75, 0
	s_cmp_lt_u32 s69, 60
	s_cbranch_scc1 .LBB0_154
	s_add_u32 s72, s72, 0x1f80
	v_readfirstlane_b32 s69, v167
	s_addc_u32 s73, s73, 0
	s_mov_b32 m0, s69
	v_readfirstlane_b32 s69, v168
	ds_read_b128 v[138:141], v149
	ds_read_b128 v[142:145], v149 offset:1024
	ds_read_b128 v[170:173], v149 offset:2048
	ds_read_b128 v[174:177], v149 offset:3072
	ds_read_b128 v[178:181], v149 offset:16384
	ds_read_b128 v[182:185], v149 offset:17408
	ds_read_b128 v[186:189], v149 offset:18432
	ds_read_b128 v[190:193], v149 offset:19456
	ds_read_b128 v[194:197], v151
	ds_read_b128 v[198:201], v151 offset:1024
	ds_read_b128 v[202:205], v151 offset:2048
	ds_read_b128 v[206:209], v151 offset:3072
	ds_read_b128 v[210:213], v151 offset:4096
	ds_read_b128 v[214:217], v151 offset:5120
	ds_read_b128 v[218:221], v151 offset:6144
	ds_read_b128 v[222:225], v151 offset:7168
	global_load_lds_dwordx4 v134, s[72:73]
	s_mov_b32 m0, s69
	s_nop 0
	global_load_lds_dwordx4 v136, s[72:73]
	s_waitcnt vmcnt(8)
	s_waitcnt lgkmcnt(0)
	s_setprio 1
	s_barrier
	v_mfma_f32_16x16x32_bf16 v[124:127], v[194:197], v[138:141], v[124:127]
	v_mfma_f32_16x16x32_bf16 v[120:123], v[194:197], v[170:173], v[120:123]
	v_mfma_f32_16x16x32_bf16 v[116:119], v[202:205], v[138:141], v[116:119]
	v_mfma_f32_16x16x32_bf16 v[112:115], v[202:205], v[170:173], v[112:115]
	v_mfma_f32_16x16x32_bf16 v[108:111], v[210:213], v[138:141], v[108:111]
	v_mfma_f32_16x16x32_bf16 v[104:107], v[210:213], v[170:173], v[104:107]
	v_mfma_f32_16x16x32_bf16 v[100:103], v[218:221], v[138:141], v[100:103]
	v_mfma_f32_16x16x32_bf16 v[96:99], v[218:221], v[170:173], v[96:99]
	v_mfma_f32_16x16x32_bf16 v[92:95], v[194:197], v[178:181], v[92:95]
	v_mfma_f32_16x16x32_bf16 v[88:91], v[194:197], v[186:189], v[88:91]
	v_mfma_f32_16x16x32_bf16 v[84:87], v[202:205], v[178:181], v[84:87]
	v_mfma_f32_16x16x32_bf16 v[80:83], v[202:205], v[186:189], v[80:83]
	v_mfma_f32_16x16x32_bf16 v[76:79], v[210:213], v[178:181], v[76:79]
	v_mfma_f32_16x16x32_bf16 v[72:75], v[210:213], v[186:189], v[72:75]
	v_mfma_f32_16x16x32_bf16 v[68:71], v[218:221], v[178:181], v[68:71]
	v_mfma_f32_16x16x32_bf16 v[64:67], v[218:221], v[186:189], v[64:67]
	v_mfma_f32_16x16x32_bf16 v[124:127], v[198:201], v[142:145], v[124:127]
	v_mfma_f32_16x16x32_bf16 v[120:123], v[198:201], v[174:177], v[120:123]
	v_mfma_f32_16x16x32_bf16 v[116:119], v[206:209], v[142:145], v[116:119]
	v_mfma_f32_16x16x32_bf16 v[112:115], v[206:209], v[174:177], v[112:115]
	v_mfma_f32_16x16x32_bf16 v[108:111], v[214:217], v[142:145], v[108:111]
	v_mfma_f32_16x16x32_bf16 v[104:107], v[214:217], v[174:177], v[104:107]
	v_mfma_f32_16x16x32_bf16 v[100:103], v[222:225], v[142:145], v[100:103]
	v_mfma_f32_16x16x32_bf16 v[96:99], v[222:225], v[174:177], v[96:99]
	v_mfma_f32_16x16x32_bf16 v[92:95], v[198:201], v[182:185], v[92:95]
	v_mfma_f32_16x16x32_bf16 v[88:91], v[198:201], v[190:193], v[88:91]
	v_mfma_f32_16x16x32_bf16 v[84:87], v[206:209], v[182:185], v[84:87]
	v_mfma_f32_16x16x32_bf16 v[80:83], v[206:209], v[190:193], v[80:83]
	v_mfma_f32_16x16x32_bf16 v[76:79], v[214:217], v[182:185], v[76:79]
	v_mfma_f32_16x16x32_bf16 v[72:75], v[214:217], v[190:193], v[72:75]
	v_mfma_f32_16x16x32_bf16 v[68:71], v[222:225], v[182:185], v[68:71]
	v_mfma_f32_16x16x32_bf16 v[64:67], v[222:225], v[190:193], v[64:67]
	s_barrier
	s_setprio 0
	ds_read_b128 v[194:197], v151 offset:16384
	ds_read_b128 v[198:201], v151 offset:17408
	ds_read_b128 v[202:205], v151 offset:18432
	ds_read_b128 v[206:209], v151 offset:19456
	ds_read_b128 v[210:213], v151 offset:20480
	ds_read_b128 v[214:217], v151 offset:21504
	ds_read_b128 v[218:221], v151 offset:22528
	ds_read_b128 v[222:225], v151 offset:23552
	s_waitcnt vmcnt(0)
	s_waitcnt lgkmcnt(0)
	s_setprio 1
	s_barrier
	v_mfma_f32_16x16x32_bf16 v[56:59], v[194:197], v[170:173], v[56:59]
	v_mfma_f32_16x16x32_bf16 v[52:55], v[202:205], v[138:141], v[52:55]
	v_mfma_f32_16x16x32_bf16 v[48:51], v[202:205], v[170:173], v[48:51]
	v_mfma_f32_16x16x32_bf16 v[44:47], v[210:213], v[138:141], v[44:47]
	v_mfma_f32_16x16x32_bf16 v[40:43], v[210:213], v[170:173], v[40:43]
	v_mfma_f32_16x16x32_bf16 v[36:39], v[218:221], v[138:141], v[36:39]
	v_mfma_f32_16x16x32_bf16 v[32:35], v[218:221], v[170:173], v[32:35]
	v_mfma_f32_16x16x32_bf16 v[28:31], v[194:197], v[178:181], v[28:31]
	v_mfma_f32_16x16x32_bf16 v[24:27], v[194:197], v[186:189], v[24:27]
	v_mfma_f32_16x16x32_bf16 v[20:23], v[202:205], v[178:181], v[20:23]
	v_mfma_f32_16x16x32_bf16 v[16:19], v[202:205], v[186:189], v[16:19]
	v_mfma_f32_16x16x32_bf16 v[12:15], v[210:213], v[178:181], v[12:15]
	v_mfma_f32_16x16x32_bf16 v[8:11], v[210:213], v[186:189], v[8:11]
	v_mfma_f32_16x16x32_bf16 v[4:7], v[218:221], v[178:181], v[4:7]
	v_mfma_f32_16x16x32_bf16 v[0:3], v[218:221], v[186:189], v[0:3]
	v_mfma_f32_16x16x32_bf16 v[60:63], v[194:197], v[138:141], v[60:63]
	v_mfma_f32_16x16x32_bf16 v[56:59], v[198:201], v[174:177], v[56:59]
	v_mfma_f32_16x16x32_bf16 v[52:55], v[206:209], v[142:145], v[52:55]
	v_mfma_f32_16x16x32_bf16 v[48:51], v[206:209], v[174:177], v[48:51]
	v_mfma_f32_16x16x32_bf16 v[44:47], v[214:217], v[142:145], v[44:47]
	v_mfma_f32_16x16x32_bf16 v[40:43], v[214:217], v[174:177], v[40:43]
	v_mfma_f32_16x16x32_bf16 v[36:39], v[222:225], v[142:145], v[36:39]
	v_mfma_f32_16x16x32_bf16 v[32:35], v[222:225], v[174:177], v[32:35]
	v_mfma_f32_16x16x32_bf16 v[28:31], v[198:201], v[182:185], v[28:31]
	v_mfma_f32_16x16x32_bf16 v[24:27], v[198:201], v[190:193], v[24:27]
	v_mfma_f32_16x16x32_bf16 v[20:23], v[206:209], v[182:185], v[20:23]
	v_mfma_f32_16x16x32_bf16 v[16:19], v[206:209], v[190:193], v[16:19]
	v_mfma_f32_16x16x32_bf16 v[12:15], v[214:217], v[182:185], v[12:15]
	v_mfma_f32_16x16x32_bf16 v[8:11], v[214:217], v[190:193], v[8:11]
	v_mfma_f32_16x16x32_bf16 v[4:7], v[222:225], v[182:185], v[4:7]
	v_mfma_f32_16x16x32_bf16 v[0:3], v[222:225], v[190:193], v[0:3]
	v_mfma_f32_16x16x32_bf16 v[226:229], v[198:201], v[142:145], v[60:63]
	s_barrier
; #define LDA(dst, b, h) _Pragma("unroll") for (int m = 0; m < 4; ++m) _Pragma("unroll") for (int k = 0; k < 2; ++k) \
;     dst[m][k] = *reinterpret_cast<const bf16x8*>((const char*)shm + aB + (((b) * 2 + (h)) * 16384 + (m * 2 + k) * 1024))
; #define LDB(dst, b, h) _Pragma("unroll") for (int n = 0; n < 2; ++n) _Pragma("unroll") for (int k = 0; k < 2; ++k) \
;     dst[n][k] = *reinterpret_cast<const bf16x8*>((const char*)shm + bB + (((b) * 2 + (h)) * 16384 + (n * 2 + k) * 1024))
; #define WAIT_L(n) asm volatile("s_waitcnt lgkmcnt(" #n ")" ::: "memory")
; #define BAR __builtin_amdgcn_s_barrier()
; #define SCHED __builtin_amdgcn_sched_barrier(0)
; template <int MODE> ...
;     ...
;       LDB(B0, 1, 0); LDB(B1, 1, 1); LDA(At, 1, 0); WAIT_L(0); BAR; MMA2(0, 0, 0, 1); BAR; SCHED;
;       LDA(At, 1, 1); WAIT_L(0); BAR; MMA2(1, 0, 1, 1); BAR; SCHED;
;     }
;     ...
;     if (wr == 0) BAR;
	s_setprio 0
	ds_read_b128 v[138:141], v149 offset:32768
	ds_read_b128 v[142:145], v149 offset:33792
	ds_read_b128 v[170:173], v149 offset:34816
	ds_read_b128 v[174:177], v149 offset:35840
	ds_read_b128 v[178:181], v149 offset:49152
	ds_read_b128 v[182:185], v149 offset:50176
	ds_read_b128 v[186:189], v149 offset:51200
	ds_read_b128 v[190:193], v149 offset:52224
	ds_read_b128 v[60:63], v151 offset:32768
	ds_read_b128 v[194:197], v151 offset:33792
	ds_read_b128 v[198:201], v151 offset:34816
	ds_read_b128 v[202:205], v151 offset:35840
	ds_read_b128 v[206:209], v151 offset:36864
	ds_read_b128 v[210:213], v151 offset:37888
	ds_read_b128 v[214:217], v151 offset:38912
	ds_read_b128 v[218:221], v151 offset:39936
	s_waitcnt lgkmcnt(0)
	s_setprio 1
	s_barrier
	v_mfma_f32_16x16x32_bf16 v[124:127], v[60:63], v[138:141], v[124:127]
	v_mfma_f32_16x16x32_bf16 v[120:123], v[60:63], v[170:173], v[120:123]
	v_mfma_f32_16x16x32_bf16 v[92:95], v[60:63], v[178:181], v[92:95]
	v_mfma_f32_16x16x32_bf16 v[60:63], v[60:63], v[186:189], v[88:91]
	v_mfma_f32_16x16x32_bf16 v[88:91], v[194:197], v[190:193], v[60:63]
	v_mfma_f32_16x16x32_bf16 v[60:63], v[198:201], v[178:181], v[84:87]
	v_mfma_f32_16x16x32_bf16 v[84:87], v[202:205], v[182:185], v[60:63]
	v_mfma_f32_16x16x32_bf16 v[60:63], v[198:201], v[186:189], v[80:83]
	v_mfma_f32_16x16x32_bf16 v[80:83], v[202:205], v[190:193], v[60:63]
	v_mfma_f32_16x16x32_bf16 v[60:63], v[206:209], v[178:181], v[76:79]
	v_mfma_f32_16x16x32_bf16 v[76:79], v[210:213], v[182:185], v[60:63]
	v_mfma_f32_16x16x32_bf16 v[60:63], v[206:209], v[186:189], v[72:75]
	v_mfma_f32_16x16x32_bf16 v[72:75], v[210:213], v[190:193], v[60:63]
	v_mfma_f32_16x16x32_bf16 v[60:63], v[214:217], v[178:181], v[68:71]
	v_mfma_f32_16x16x32_bf16 v[116:119], v[198:201], v[138:141], v[116:119]
	v_mfma_f32_16x16x32_bf16 v[112:115], v[198:201], v[170:173], v[112:115]
	v_mfma_f32_16x16x32_bf16 v[108:111], v[206:209], v[138:141], v[108:111]
	v_mfma_f32_16x16x32_bf16 v[104:107], v[206:209], v[170:173], v[104:107]
	v_mfma_f32_16x16x32_bf16 v[100:103], v[214:217], v[138:141], v[100:103]
	v_mfma_f32_16x16x32_bf16 v[96:99], v[214:217], v[170:173], v[96:99]
	v_mfma_f32_16x16x32_bf16 v[68:71], v[218:221], v[182:185], v[60:63]
	v_mfma_f32_16x16x32_bf16 v[60:63], v[214:217], v[186:189], v[64:67]
	v_mfma_f32_16x16x32_bf16 v[124:127], v[194:197], v[142:145], v[124:127]
	v_mfma_f32_16x16x32_bf16 v[120:123], v[194:197], v[174:177], v[120:123]
	v_mfma_f32_16x16x32_bf16 v[116:119], v[202:205], v[142:145], v[116:119]
	v_mfma_f32_16x16x32_bf16 v[112:115], v[202:205], v[174:177], v[112:115]
	v_mfma_f32_16x16x32_bf16 v[108:111], v[210:213], v[142:145], v[108:111]
	v_mfma_f32_16x16x32_bf16 v[104:107], v[210:213], v[174:177], v[104:107]
	v_mfma_f32_16x16x32_bf16 v[100:103], v[218:221], v[142:145], v[100:103]
	v_mfma_f32_16x16x32_bf16 v[96:99], v[218:221], v[174:177], v[96:99]
	v_mfma_f32_16x16x32_bf16 v[92:95], v[194:197], v[182:185], v[92:95]
	v_mfma_f32_16x16x32_bf16 v[60:63], v[218:221], v[190:193], v[60:63]
	s_barrier
	s_setprio 0
	ds_read_b128 v[194:197], v151 offset:49152
	ds_read_b128 v[198:201], v151 offset:50176
	ds_read_b128 v[202:205], v151 offset:51200
	ds_read_b128 v[206:209], v151 offset:52224
	ds_read_b128 v[210:213], v151 offset:53248
	ds_read_b128 v[214:217], v151 offset:54272
	ds_read_b128 v[218:221], v151 offset:55296
	ds_read_b128 v[222:225], v151 offset:56320
	s_waitcnt lgkmcnt(0)
	s_setprio 1
	s_barrier
	v_mfma_f32_16x16x32_bf16 v[64:67], v[194:197], v[138:141], v[226:229]
	v_mfma_f32_16x16x32_bf16 v[56:59], v[194:197], v[170:173], v[56:59]
	v_mfma_f32_16x16x32_bf16 v[52:55], v[202:205], v[138:141], v[52:55]
	v_mfma_f32_16x16x32_bf16 v[48:51], v[202:205], v[170:173], v[48:51]
	v_mfma_f32_16x16x32_bf16 v[44:47], v[210:213], v[138:141], v[44:47]
	v_mfma_f32_16x16x32_bf16 v[40:43], v[210:213], v[170:173], v[40:43]
	v_mfma_f32_16x16x32_bf16 v[36:39], v[218:221], v[138:141], v[36:39]
	v_mfma_f32_16x16x32_bf16 v[32:35], v[218:221], v[170:173], v[32:35]
	v_mfma_f32_16x16x32_bf16 v[28:31], v[194:197], v[178:181], v[28:31]
	v_mfma_f32_16x16x32_bf16 v[24:27], v[194:197], v[186:189], v[24:27]
	v_mfma_f32_16x16x32_bf16 v[20:23], v[202:205], v[178:181], v[20:23]
	v_mfma_f32_16x16x32_bf16 v[16:19], v[202:205], v[186:189], v[16:19]
	v_mfma_f32_16x16x32_bf16 v[12:15], v[210:213], v[178:181], v[12:15]
	v_mfma_f32_16x16x32_bf16 v[8:11], v[210:213], v[186:189], v[8:11]
	v_mfma_f32_16x16x32_bf16 v[4:7], v[218:221], v[178:181], v[4:7]
	v_mfma_f32_16x16x32_bf16 v[0:3], v[218:221], v[186:189], v[0:3]
	v_mfma_f32_16x16x32_bf16 v[64:67], v[198:201], v[142:145], v[64:67]
	v_mfma_f32_16x16x32_bf16 v[56:59], v[198:201], v[174:177], v[56:59]
	v_mfma_f32_16x16x32_bf16 v[52:55], v[206:209], v[142:145], v[52:55]
	v_mfma_f32_16x16x32_bf16 v[48:51], v[206:209], v[174:177], v[48:51]
	v_mfma_f32_16x16x32_bf16 v[44:47], v[214:217], v[142:145], v[44:47]
	v_mfma_f32_16x16x32_bf16 v[40:43], v[214:217], v[174:177], v[40:43]
	v_mfma_f32_16x16x32_bf16 v[36:39], v[222:225], v[142:145], v[36:39]
	v_mfma_f32_16x16x32_bf16 v[32:35], v[222:225], v[174:177], v[32:35]
	v_mfma_f32_16x16x32_bf16 v[28:31], v[198:201], v[182:185], v[28:31]
	v_mfma_f32_16x16x32_bf16 v[24:27], v[198:201], v[190:193], v[24:27]
	v_mfma_f32_16x16x32_bf16 v[20:23], v[206:209], v[182:185], v[20:23]
	v_mfma_f32_16x16x32_bf16 v[16:19], v[206:209], v[190:193], v[16:19]
	v_mfma_f32_16x16x32_bf16 v[12:15], v[214:217], v[182:185], v[12:15]
	v_mfma_f32_16x16x32_bf16 v[8:11], v[214:217], v[190:193], v[8:11]
	v_mfma_f32_16x16x32_bf16 v[4:7], v[222:225], v[182:185], v[4:7]
	v_mfma_f32_16x16x32_bf16 v[0:3], v[222:225], v[190:193], v[0:3]
	s_barrier
	s_setprio 0
	s_and_saveexec_b64 s[72:73], s[6:7]
	s_cbranch_execz .LBB0_157
	s_barrier

; #define STAGE(Pp, BASE, br, kt) do { const u16* _g = (BASE) + ((long)(br) * K + (long)(kt) * BK); \
;     __builtin_amdgcn_global_load_lds((const unsigned*)(_g + voff0), (unsigned*)((char*)(Pp) + tb16), 16, 0, 0); \
;     __builtin_amdgcn_global_load_lds((const unsigned*)(_g + voff1), (unsigned*)((char*)(Pp) + tb16 + 8192), 16, 0, 0); } while (0)
; #define LDA(dst, b, h) _Pragma("unroll") for (int m = 0; m < 4; ++m) _Pragma("unroll") for (int k = 0; k < 2; ++k) \
;     dst[m][k] = *reinterpret_cast<const bf16x8*>((const char*)shm + aB + (((b) * 2 + (h)) * 16384 + (m * 2 + k) * 1024))
; #define LDB(dst, b, h) _Pragma("unroll") for (int n = 0; n < 2; ++n) _Pragma("unroll") for (int k = 0; k < 2; ++k) \
;     dst[n][k] = *reinterpret_cast<const bf16x8*>((const char*)shm + bB + (((b) * 2 + (h)) * 16384 + (n * 2 + k) * 1024))
; #define WAIT_V(n) asm volatile("s_waitcnt vmcnt(" #n ")" ::: "memory")
; #define WAIT_L(n) asm volatile("s_waitcnt lgkmcnt(" #n ")" ::: "memory")
; #define BAR __builtin_amdgcn_s_barrier()
; #define SCHED __builtin_amdgcn_sched_barrier(0)
; template <int MODE> ...
;     ...
;       LDB(B0, 0, 0); LDB(B1, 0, 1); LDA(At, 0, 0); STAGE(SA(1, 1), A, brow + HALF, t + 1);
;       WAIT_L(0); BAR; MMA2(0, 0, 0, 1); BAR; SCHED;
;       LDA(At, 0, 1); STAGE(SB(0, 0), Bt, bcol, t + 2); STAGE(SB(0, 1), Bt, bcol + HALF, t + 2); STAGE(SA(0, 0), A, brow, t + 2);
;       WAIT_V(6); WAIT_L(0); BAR; MMA2(1, 0, 1, 1); BAR; SCHED;
.LBB0_177:
	s_add_u32 m0, s32, 0xc000
	s_add_u32 s88, s68, s12
	s_addc_u32 s89, s69, s13
	global_load_lds_dwordx4 v142, s[88:89]
	s_add_u32 m0, s32, 0xe000
	s_nop 0
	global_load_lds_dwordx4 v144, s[88:89]
	ds_read_b128 v[168:171], v148
	ds_read_b128 v[172:175], v148 offset:1024
	ds_read_b128 v[176:179], v148 offset:2048
	ds_read_b128 v[180:183], v148 offset:3072
	ds_read_b128 v[184:187], v148 offset:16384
	ds_read_b128 v[188:191], v148 offset:17408
	ds_read_b128 v[192:195], v148 offset:18432
	ds_read_b128 v[196:199], v148 offset:19456
	ds_read_b128 v[200:203], v147
	ds_read_b128 v[204:207], v147 offset:1024
	ds_read_b128 v[208:211], v147 offset:2048
	ds_read_b128 v[212:215], v147 offset:3072
	ds_read_b128 v[216:219], v147 offset:4096
	ds_read_b128 v[220:223], v147 offset:5120
	ds_read_b128 v[224:227], v147 offset:6144
	ds_read_b128 v[228:231], v147 offset:7168
	s_waitcnt vmcnt(8)
	s_waitcnt lgkmcnt(0)
	s_setprio 1
	s_barrier
	v_mfma_f32_16x16x32_bf16 v[124:127], v[200:203], v[168:171], v[124:127]
	v_mfma_f32_16x16x32_bf16 v[120:123], v[200:203], v[176:179], v[120:123]
	v_mfma_f32_16x16x32_bf16 v[116:119], v[208:211], v[168:171], v[116:119]
	v_mfma_f32_16x16x32_bf16 v[112:115], v[208:211], v[176:179], v[112:115]
	v_mfma_f32_16x16x32_bf16 v[108:111], v[216:219], v[168:171], v[108:111]
	v_mfma_f32_16x16x32_bf16 v[104:107], v[216:219], v[176:179], v[104:107]
	v_mfma_f32_16x16x32_bf16 v[100:103], v[224:227], v[168:171], v[100:103]
	v_mfma_f32_16x16x32_bf16 v[96:99], v[224:227], v[176:179], v[96:99]
	v_mfma_f32_16x16x32_bf16 v[92:95], v[200:203], v[184:187], v[92:95]
	v_mfma_f32_16x16x32_bf16 v[88:91], v[200:203], v[192:195], v[88:91]
	v_mfma_f32_16x16x32_bf16 v[84:87], v[208:211], v[184:187], v[84:87]
	v_mfma_f32_16x16x32_bf16 v[80:83], v[208:211], v[192:195], v[80:83]
	v_mfma_f32_16x16x32_bf16 v[76:79], v[216:219], v[184:187], v[76:79]
	v_mfma_f32_16x16x32_bf16 v[72:75], v[216:219], v[192:195], v[72:75]
	v_mfma_f32_16x16x32_bf16 v[68:71], v[224:227], v[184:187], v[68:71]
	v_mfma_f32_16x16x32_bf16 v[64:67], v[224:227], v[192:195], v[64:67]
	v_mfma_f32_16x16x32_bf16 v[124:127], v[204:207], v[172:175], v[124:127]
	v_mfma_f32_16x16x32_bf16 v[120:123], v[204:207], v[180:183], v[120:123]
	v_mfma_f32_16x16x32_bf16 v[116:119], v[212:215], v[172:175], v[116:119]
	v_mfma_f32_16x16x32_bf16 v[112:115], v[212:215], v[180:183], v[112:115]
	v_mfma_f32_16x16x32_bf16 v[108:111], v[220:223], v[172:175], v[108:111]
	v_mfma_f32_16x16x32_bf16 v[104:107], v[220:223], v[180:183], v[104:107]
	v_mfma_f32_16x16x32_bf16 v[100:103], v[228:231], v[172:175], v[100:103]
	v_mfma_f32_16x16x32_bf16 v[96:99], v[228:231], v[180:183], v[96:99]
	v_mfma_f32_16x16x32_bf16 v[92:95], v[204:207], v[188:191], v[92:95]
	v_mfma_f32_16x16x32_bf16 v[88:91], v[204:207], v[196:199], v[88:91]
	v_mfma_f32_16x16x32_bf16 v[84:87], v[212:215], v[188:191], v[84:87]
	v_mfma_f32_16x16x32_bf16 v[80:83], v[212:215], v[196:199], v[80:83]
	v_mfma_f32_16x16x32_bf16 v[76:79], v[220:223], v[188:191], v[76:79]
	v_mfma_f32_16x16x32_bf16 v[72:75], v[220:223], v[196:199], v[72:75]
	v_mfma_f32_16x16x32_bf16 v[68:71], v[228:231], v[188:191], v[68:71]
	v_mfma_f32_16x16x32_bf16 v[64:67], v[228:231], v[196:199], v[64:67]
	s_barrier
	s_setprio 0
	s_add_u32 m0, s32, 0x10000
	s_add_u32 s88, s68, s38
	s_addc_u32 s89, s69, s39
	global_load_lds_dwordx4 v138, s[88:89]
	s_add_u32 m0, s32, 0x12000
	s_add_u32 s90, s68, s40
	s_addc_u32 s91, s69, s41
	global_load_lds_dwordx4 v140, s[88:89]
	s_add_u32 m0, s32, 0x14000
	s_add_u32 s92, s68, s42
	s_addc_u32 s93, s69, s43
	global_load_lds_dwordx4 v138, s[90:91]
	s_add_u32 m0, s32, 0x16000
	s_nop 0
	global_load_lds_dwordx4 v140, s[90:91]
	s_mov_b32 m0, s32
	s_nop 0
	global_load_lds_dwordx4 v142, s[92:93]
	s_add_u32 m0, s32, 0x2000
	s_nop 0
	global_load_lds_dwordx4 v144, s[92:93]
	ds_read_b128 v[200:203], v147 offset:16384
	ds_read_b128 v[204:207], v147 offset:17408
	ds_read_b128 v[208:211], v147 offset:18432
	ds_read_b128 v[212:215], v147 offset:19456
	ds_read_b128 v[216:219], v147 offset:20480
	ds_read_b128 v[220:223], v147 offset:21504
	ds_read_b128 v[224:227], v147 offset:22528
	ds_read_b128 v[228:231], v147 offset:23552
	s_waitcnt vmcnt(8)
	s_waitcnt lgkmcnt(0)
	s_setprio 1
	s_barrier
	v_mfma_f32_16x16x32_bf16 v[60:63], v[200:203], v[168:171], v[60:63]
	v_mfma_f32_16x16x32_bf16 v[56:59], v[200:203], v[176:179], v[56:59]
	v_mfma_f32_16x16x32_bf16 v[52:55], v[208:211], v[168:171], v[52:55]
	v_mfma_f32_16x16x32_bf16 v[48:51], v[208:211], v[176:179], v[48:51]
	v_mfma_f32_16x16x32_bf16 v[44:47], v[216:219], v[168:171], v[44:47]
	v_mfma_f32_16x16x32_bf16 v[40:43], v[216:219], v[176:179], v[40:43]
	v_mfma_f32_16x16x32_bf16 v[36:39], v[224:227], v[168:171], v[36:39]
	v_mfma_f32_16x16x32_bf16 v[32:35], v[224:227], v[176:179], v[32:35]
	v_mfma_f32_16x16x32_bf16 v[28:31], v[200:203], v[184:187], v[28:31]
	v_mfma_f32_16x16x32_bf16 v[24:27], v[200:203], v[192:195], v[24:27]
	v_mfma_f32_16x16x32_bf16 v[20:23], v[208:211], v[184:187], v[20:23]
	v_mfma_f32_16x16x32_bf16 v[16:19], v[208:211], v[192:195], v[16:19]
	v_mfma_f32_16x16x32_bf16 v[12:15], v[216:219], v[184:187], v[12:15]
	v_mfma_f32_16x16x32_bf16 v[8:11], v[216:219], v[192:195], v[8:11]
	v_mfma_f32_16x16x32_bf16 v[4:7], v[224:227], v[184:187], v[4:7]
	v_mfma_f32_16x16x32_bf16 v[0:3], v[224:227], v[192:195], v[0:3]
	v_mfma_f32_16x16x32_bf16 v[60:63], v[204:207], v[172:175], v[60:63]
	v_mfma_f32_16x16x32_bf16 v[56:59], v[204:207], v[180:183], v[56:59]
	v_mfma_f32_16x16x32_bf16 v[52:55], v[212:215], v[172:175], v[52:55]
	v_mfma_f32_16x16x32_bf16 v[48:51], v[212:215], v[180:183], v[48:51]
	v_mfma_f32_16x16x32_bf16 v[44:47], v[220:223], v[172:175], v[44:47]
	v_mfma_f32_16x16x32_bf16 v[40:43], v[220:223], v[180:183], v[40:43]
	v_mfma_f32_16x16x32_bf16 v[36:39], v[228:231], v[172:175], v[36:39]
	v_mfma_f32_16x16x32_bf16 v[32:35], v[228:231], v[180:183], v[32:35]
	v_mfma_f32_16x16x32_bf16 v[28:31], v[204:207], v[188:191], v[28:31]
	v_mfma_f32_16x16x32_bf16 v[24:27], v[204:207], v[196:199], v[24:27]
	v_mfma_f32_16x16x32_bf16 v[20:23], v[212:215], v[188:191], v[20:23]
	v_mfma_f32_16x16x32_bf16 v[16:19], v[212:215], v[196:199], v[16:19]
	v_mfma_f32_16x16x32_bf16 v[12:15], v[220:223], v[188:191], v[12:15]
	v_mfma_f32_16x16x32_bf16 v[8:11], v[220:223], v[196:199], v[8:11]
	v_mfma_f32_16x16x32_bf16 v[4:7], v[228:231], v[188:191], v[4:7]
	v_mfma_f32_16x16x32_bf16 v[0:3], v[228:231], v[196:199], v[0:3]
	s_barrier
; #define STAGE(Pp, BASE, br, kt) do { const u16* _g = (BASE) + ((long)(br) * K + (long)(kt) * BK); \
;     __builtin_amdgcn_global_load_lds((const unsigned*)(_g + voff0), (unsigned*)((char*)(Pp) + tb16), 16, 0, 0); \
;     __builtin_amdgcn_global_load_lds((const unsigned*)(_g + voff1), (unsigned*)((char*)(Pp) + tb16 + 8192), 16, 0, 0); } while (0)
; #define LDA(dst, b, h) _Pragma("unroll") for (int m = 0; m < 4; ++m) _Pragma("unroll") for (int k = 0; k < 2; ++k) \
;     dst[m][k] = *reinterpret_cast<const bf16x8*>((const char*)shm + aB + (((b) * 2 + (h)) * 16384 + (m * 2 + k) * 1024))
; #define LDB(dst, b, h) _Pragma("unroll") for (int n = 0; n < 2; ++n) _Pragma("unroll") for (int k = 0; k < 2; ++k) \
;     dst[n][k] = *reinterpret_cast<const bf16x8*>((const char*)shm + bB + (((b) * 2 + (h)) * 16384 + (n * 2 + k) * 1024))
; #define WAIT_V(n) asm volatile("s_waitcnt vmcnt(" #n ")" ::: "memory")
; #define WAIT_L(n) asm volatile("s_waitcnt lgkmcnt(" #n ")" ::: "memory")
; #define BAR __builtin_amdgcn_s_barrier()
; #define SCHED __builtin_amdgcn_sched_barrier(0)
; template <int MODE> ...
;     ...
;       LDB(B0, 1, 0); LDB(B1, 1, 1); LDA(At, 1, 0); STAGE(SA(0, 1), A, brow + HALF, t + 2);
;       WAIT_L(0); BAR; MMA2(0, 0, 0, 1); BAR; SCHED;
;       LDA(At, 1, 1); STAGE(SB(1, 0), Bt, bcol, t + 3); STAGE(SB(1, 1), Bt, bcol + HALF, t + 3); STAGE(SA(1, 0), A, brow, t + 3);
;       WAIT_V(6); WAIT_L(0); BAR; MMA2(1, 0, 1, 1); BAR; SCHED;
	s_setprio 0
	s_add_u32 m0, s32, 0x4000
	s_add_u32 s88, s68, s44
	s_addc_u32 s89, s69, s45
	global_load_lds_dwordx4 v142, s[88:89]
	s_add_u32 m0, s32, 0x6000
	s_nop 0
	global_load_lds_dwordx4 v144, s[88:89]
	ds_read_b128 v[168:171], v148 offset:32768
	ds_read_b128 v[172:175], v148 offset:33792
	ds_read_b128 v[176:179], v148 offset:34816
	ds_read_b128 v[180:183], v148 offset:35840
	ds_read_b128 v[184:187], v148 offset:49152
	ds_read_b128 v[188:191], v148 offset:50176
	ds_read_b128 v[192:195], v148 offset:51200
	ds_read_b128 v[196:199], v148 offset:52224
	ds_read_b128 v[200:203], v147 offset:32768
	ds_read_b128 v[204:207], v147 offset:33792
	ds_read_b128 v[208:211], v147 offset:34816
	ds_read_b128 v[212:215], v147 offset:35840
	ds_read_b128 v[216:219], v147 offset:36864
	ds_read_b128 v[220:223], v147 offset:37888
	ds_read_b128 v[224:227], v147 offset:38912
	ds_read_b128 v[228:231], v147 offset:39936
	s_waitcnt vmcnt(8)
	s_waitcnt lgkmcnt(0)
	s_setprio 1
	s_barrier
	v_mfma_f32_16x16x32_bf16 v[124:127], v[200:203], v[168:171], v[124:127]
	v_mfma_f32_16x16x32_bf16 v[120:123], v[200:203], v[176:179], v[120:123]
	v_mfma_f32_16x16x32_bf16 v[116:119], v[208:211], v[168:171], v[116:119]
	v_mfma_f32_16x16x32_bf16 v[112:115], v[208:211], v[176:179], v[112:115]
	v_mfma_f32_16x16x32_bf16 v[108:111], v[216:219], v[168:171], v[108:111]
	v_mfma_f32_16x16x32_bf16 v[104:107], v[216:219], v[176:179], v[104:107]
	v_mfma_f32_16x16x32_bf16 v[100:103], v[224:227], v[168:171], v[100:103]
	v_mfma_f32_16x16x32_bf16 v[96:99], v[224:227], v[176:179], v[96:99]
	v_mfma_f32_16x16x32_bf16 v[92:95], v[200:203], v[184:187], v[92:95]
	v_mfma_f32_16x16x32_bf16 v[88:91], v[200:203], v[192:195], v[88:91]
	v_mfma_f32_16x16x32_bf16 v[84:87], v[208:211], v[184:187], v[84:87]
	v_mfma_f32_16x16x32_bf16 v[80:83], v[208:211], v[192:195], v[80:83]
	v_mfma_f32_16x16x32_bf16 v[76:79], v[216:219], v[184:187], v[76:79]
	v_mfma_f32_16x16x32_bf16 v[72:75], v[216:219], v[192:195], v[72:75]
	v_mfma_f32_16x16x32_bf16 v[68:71], v[224:227], v[184:187], v[68:71]
	v_mfma_f32_16x16x32_bf16 v[64:67], v[224:227], v[192:195], v[64:67]
	v_mfma_f32_16x16x32_bf16 v[124:127], v[204:207], v[172:175], v[124:127]
	v_mfma_f32_16x16x32_bf16 v[120:123], v[204:207], v[180:183], v[120:123]
	v_mfma_f32_16x16x32_bf16 v[116:119], v[212:215], v[172:175], v[116:119]
	v_mfma_f32_16x16x32_bf16 v[112:115], v[212:215], v[180:183], v[112:115]
	v_mfma_f32_16x16x32_bf16 v[108:111], v[220:223], v[172:175], v[108:111]
	v_mfma_f32_16x16x32_bf16 v[104:107], v[220:223], v[180:183], v[104:107]
	v_mfma_f32_16x16x32_bf16 v[100:103], v[228:231], v[172:175], v[100:103]
	v_mfma_f32_16x16x32_bf16 v[96:99], v[228:231], v[180:183], v[96:99]
	v_mfma_f32_16x16x32_bf16 v[92:95], v[204:207], v[188:191], v[92:95]
	v_mfma_f32_16x16x32_bf16 v[88:91], v[204:207], v[196:199], v[88:91]
	v_mfma_f32_16x16x32_bf16 v[84:87], v[212:215], v[188:191], v[84:87]
	v_mfma_f32_16x16x32_bf16 v[80:83], v[212:215], v[196:199], v[80:83]
	v_mfma_f32_16x16x32_bf16 v[76:79], v[220:223], v[188:191], v[76:79]
	v_mfma_f32_16x16x32_bf16 v[72:75], v[220:223], v[196:199], v[72:75]
	v_mfma_f32_16x16x32_bf16 v[68:71], v[228:231], v[188:191], v[68:71]
	v_mfma_f32_16x16x32_bf16 v[64:67], v[228:231], v[196:199], v[64:67]
	s_barrier
	s_setprio 0
	s_add_u32 m0, s32, 0x18000
	s_add_u32 s88, s68, s48
	s_addc_u32 s89, s69, s49
	global_load_lds_dwordx4 v138, s[88:89]
	s_add_u32 m0, s32, 0x1a000
	s_add_u32 s90, s68, s50
	s_addc_u32 s91, s69, s51
	global_load_lds_dwordx4 v140, s[88:89]
	s_add_u32 m0, s32, 0x1c000
	s_add_u32 s92, s68, s60
	s_addc_u32 s93, s69, s61
	global_load_lds_dwordx4 v138, s[90:91]
	s_add_u32 m0, s32, 0x1e000
	s_nop 0
	global_load_lds_dwordx4 v140, s[90:91]
	s_add_u32 m0, s32, 0x8000
	s_nop 0
	global_load_lds_dwordx4 v142, s[92:93]
	s_add_u32 m0, s32, 0xa000
	s_nop 0
	global_load_lds_dwordx4 v144, s[92:93]
	ds_read_b128 v[200:203], v147 offset:49152
	ds_read_b128 v[204:207], v147 offset:50176
	ds_read_b128 v[208:211], v147 offset:51200
	ds_read_b128 v[212:215], v147 offset:52224
	ds_read_b128 v[216:219], v147 offset:53248
	ds_read_b128 v[220:223], v147 offset:54272
	ds_read_b128 v[224:227], v147 offset:55296
	ds_read_b128 v[228:231], v147 offset:56320
	s_waitcnt vmcnt(8)
	s_waitcnt lgkmcnt(0)
	s_setprio 1
	s_barrier
	v_mfma_f32_16x16x32_bf16 v[60:63], v[200:203], v[168:171], v[60:63]
	v_mfma_f32_16x16x32_bf16 v[56:59], v[200:203], v[176:179], v[56:59]
	v_mfma_f32_16x16x32_bf16 v[52:55], v[208:211], v[168:171], v[52:55]
	v_mfma_f32_16x16x32_bf16 v[48:51], v[208:211], v[176:179], v[48:51]
	v_mfma_f32_16x16x32_bf16 v[44:47], v[216:219], v[168:171], v[44:47]
	v_mfma_f32_16x16x32_bf16 v[40:43], v[216:219], v[176:179], v[40:43]
	v_mfma_f32_16x16x32_bf16 v[36:39], v[224:227], v[168:171], v[36:39]
	v_mfma_f32_16x16x32_bf16 v[32:35], v[224:227], v[176:179], v[32:35]
	v_mfma_f32_16x16x32_bf16 v[28:31], v[200:203], v[184:187], v[28:31]
	v_mfma_f32_16x16x32_bf16 v[24:27], v[200:203], v[192:195], v[24:27]
	v_mfma_f32_16x16x32_bf16 v[20:23], v[208:211], v[184:187], v[20:23]
	v_mfma_f32_16x16x32_bf16 v[16:19], v[208:211], v[192:195], v[16:19]
	v_mfma_f32_16x16x32_bf16 v[12:15], v[216:219], v[184:187], v[12:15]
	v_mfma_f32_16x16x32_bf16 v[8:11], v[216:219], v[192:195], v[8:11]
	v_mfma_f32_16x16x32_bf16 v[4:7], v[224:227], v[184:187], v[4:7]
	v_mfma_f32_16x16x32_bf16 v[0:3], v[224:227], v[192:195], v[0:3]
	v_mfma_f32_16x16x32_bf16 v[60:63], v[204:207], v[172:175], v[60:63]
	v_mfma_f32_16x16x32_bf16 v[56:59], v[204:207], v[180:183], v[56:59]
	v_mfma_f32_16x16x32_bf16 v[52:55], v[212:215], v[172:175], v[52:55]
	v_mfma_f32_16x16x32_bf16 v[48:51], v[212:215], v[180:183], v[48:51]
	v_mfma_f32_16x16x32_bf16 v[44:47], v[220:223], v[172:175], v[44:47]
	v_mfma_f32_16x16x32_bf16 v[40:43], v[220:223], v[180:183], v[40:43]
	v_mfma_f32_16x16x32_bf16 v[36:39], v[228:231], v[172:175], v[36:39]
	v_mfma_f32_16x16x32_bf16 v[32:35], v[228:231], v[180:183], v[32:35]
	v_mfma_f32_16x16x32_bf16 v[28:31], v[204:207], v[188:191], v[28:31]
	v_mfma_f32_16x16x32_bf16 v[24:27], v[204:207], v[196:199], v[24:27]
	v_mfma_f32_16x16x32_bf16 v[20:23], v[212:215], v[188:191], v[20:23]
	v_mfma_f32_16x16x32_bf16 v[16:19], v[212:215], v[196:199], v[16:19]
	v_mfma_f32_16x16x32_bf16 v[12:15], v[220:223], v[188:191], v[12:15]
	v_mfma_f32_16x16x32_bf16 v[8:11], v[220:223], v[196:199], v[8:11]
	v_mfma_f32_16x16x32_bf16 v[4:7], v[228:231], v[188:191], v[4:7]
	v_mfma_f32_16x16x32_bf16 v[0:3], v[228:231], v[196:199], v[0:3]
	s_barrier
; #define STAGE(Pp, BASE, br, kt) do { const u16* _g = (BASE) + ((long)(br) * K + (long)(kt) * BK); \
;     __builtin_amdgcn_global_load_lds((const unsigned*)(_g + voff0), (unsigned*)((char*)(Pp) + tb16), 16, 0, 0); \
;     __builtin_amdgcn_global_load_lds((const unsigned*)(_g + voff1), (unsigned*)((char*)(Pp) + tb16 + 8192), 16, 0, 0); } while (0)
; #define LDA(dst, b, h) _Pragma("unroll") for (int m = 0; m < 4; ++m) _Pragma("unroll") for (int k = 0; k < 2; ++k) \
;     dst[m][k] = *reinterpret_cast<const bf16x8*>((const char*)shm + aB + (((b) * 2 + (h)) * 16384 + (m * 2 + k) * 1024))
; #define LDB(dst, b, h) _Pragma("unroll") for (int n = 0; n < 2; ++n) _Pragma("unroll") for (int k = 0; k < 2; ++k) \
;     dst[n][k] = *reinterpret_cast<const bf16x8*>((const char*)shm + bB + (((b) * 2 + (h)) * 16384 + (n * 2 + k) * 1024))
; #define WAIT_V(n) asm volatile("s_waitcnt vmcnt(" #n ")" ::: "memory")
; #define WAIT_L(n) asm volatile("s_waitcnt lgkmcnt(" #n ")" ::: "memory")
; #define BAR __builtin_amdgcn_s_barrier()
; #define SCHED __builtin_amdgcn_sched_barrier(0)
; template <int MODE> ...
;     ...
;       WAIT_V(6); WAIT_L(0); BAR; MMA2(1, 0, 1, 1); BAR; SCHED;
;     }
;     {
;       LDB(B0, 0, 0); LDB(B1, 0, 1); LDA(At, 0, 0); STAGE(SA(1, 1), A, brow + HALF, nt - 1);
;       WAIT_L(0); BAR; MMA2(0, 0, 0, 1); BAR; SCHED;
;       LDA(At, 0, 1); WAIT_V(0); WAIT_L(0); BAR; MMA2(1, 0, 1, 1); BAR; SCHED;
	s_setprio 0
	s_add_i32 s70, s70, 2
	s_add_u32 s68, s68, 0x100
	s_addc_u32 s69, s69, 0
	s_cmp_lt_u32 s70, 60
	s_cbranch_scc1 .LBB0_177
	s_add_u32 s66, s66, 0x1f80
	v_readfirstlane_b32 s68, v165
	s_addc_u32 s67, s67, 0
	s_mov_b32 m0, s68
	v_readfirstlane_b32 s68, v166
	ds_read_b128 v[138:141], v148
	ds_read_b128 v[142:145], v148 offset:1024
	ds_read_b128 v[168:171], v148 offset:2048
	ds_read_b128 v[172:175], v148 offset:3072
	ds_read_b128 v[176:179], v148 offset:16384
	ds_read_b128 v[180:183], v148 offset:17408
	ds_read_b128 v[184:187], v148 offset:18432
	ds_read_b128 v[188:191], v148 offset:19456
	ds_read_b128 v[192:195], v147
	ds_read_b128 v[196:199], v147 offset:1024
	ds_read_b128 v[200:203], v147 offset:2048
	ds_read_b128 v[204:207], v147 offset:3072
	ds_read_b128 v[208:211], v147 offset:4096
	ds_read_b128 v[212:215], v147 offset:5120
	ds_read_b128 v[216:219], v147 offset:6144
	ds_read_b128 v[220:223], v147 offset:7168
	global_load_lds_dwordx4 v134, s[66:67]
	s_mov_b32 m0, s68
	s_nop 0
	global_load_lds_dwordx4 v136, s[66:67]
	s_waitcnt vmcnt(8)
	s_waitcnt lgkmcnt(0)
	s_setprio 1
	s_barrier
	v_mfma_f32_16x16x32_bf16 v[124:127], v[192:195], v[138:141], v[124:127]
	v_mfma_f32_16x16x32_bf16 v[120:123], v[192:195], v[168:171], v[120:123]
	v_mfma_f32_16x16x32_bf16 v[116:119], v[200:203], v[138:141], v[116:119]
	v_mfma_f32_16x16x32_bf16 v[112:115], v[200:203], v[168:171], v[112:115]
	v_mfma_f32_16x16x32_bf16 v[108:111], v[208:211], v[138:141], v[108:111]
	v_mfma_f32_16x16x32_bf16 v[104:107], v[208:211], v[168:171], v[104:107]
	v_mfma_f32_16x16x32_bf16 v[100:103], v[216:219], v[138:141], v[100:103]
	v_mfma_f32_16x16x32_bf16 v[96:99], v[216:219], v[168:171], v[96:99]
	v_mfma_f32_16x16x32_bf16 v[92:95], v[192:195], v[176:179], v[92:95]
	v_mfma_f32_16x16x32_bf16 v[88:91], v[192:195], v[184:187], v[88:91]
	v_mfma_f32_16x16x32_bf16 v[84:87], v[200:203], v[176:179], v[84:87]
	v_mfma_f32_16x16x32_bf16 v[80:83], v[200:203], v[184:187], v[80:83]
	v_mfma_f32_16x16x32_bf16 v[76:79], v[208:211], v[176:179], v[76:79]
	v_mfma_f32_16x16x32_bf16 v[72:75], v[208:211], v[184:187], v[72:75]
	v_mfma_f32_16x16x32_bf16 v[68:71], v[216:219], v[176:179], v[68:71]
	v_mfma_f32_16x16x32_bf16 v[64:67], v[216:219], v[184:187], v[64:67]
	v_mfma_f32_16x16x32_bf16 v[124:127], v[196:199], v[142:145], v[124:127]
	v_mfma_f32_16x16x32_bf16 v[120:123], v[196:199], v[172:175], v[120:123]
	v_mfma_f32_16x16x32_bf16 v[116:119], v[204:207], v[142:145], v[116:119]
	v_mfma_f32_16x16x32_bf16 v[112:115], v[204:207], v[172:175], v[112:115]
	v_mfma_f32_16x16x32_bf16 v[108:111], v[212:215], v[142:145], v[108:111]
	v_mfma_f32_16x16x32_bf16 v[104:107], v[212:215], v[172:175], v[104:107]
	v_mfma_f32_16x16x32_bf16 v[100:103], v[220:223], v[142:145], v[100:103]
	v_mfma_f32_16x16x32_bf16 v[96:99], v[220:223], v[172:175], v[96:99]
	v_mfma_f32_16x16x32_bf16 v[92:95], v[196:199], v[180:183], v[92:95]
	v_mfma_f32_16x16x32_bf16 v[88:91], v[196:199], v[188:191], v[88:91]
	v_mfma_f32_16x16x32_bf16 v[84:87], v[204:207], v[180:183], v[84:87]
	v_mfma_f32_16x16x32_bf16 v[80:83], v[204:207], v[188:191], v[80:83]
	v_mfma_f32_16x16x32_bf16 v[76:79], v[212:215], v[180:183], v[76:79]
	v_mfma_f32_16x16x32_bf16 v[72:75], v[212:215], v[188:191], v[72:75]
	v_mfma_f32_16x16x32_bf16 v[68:71], v[220:223], v[180:183], v[68:71]
	v_mfma_f32_16x16x32_bf16 v[64:67], v[220:223], v[188:191], v[64:67]
	s_barrier
	s_setprio 0
	ds_read_b128 v[192:195], v147 offset:16384
	ds_read_b128 v[196:199], v147 offset:17408
	ds_read_b128 v[200:203], v147 offset:18432
	ds_read_b128 v[204:207], v147 offset:19456
	ds_read_b128 v[208:211], v147 offset:20480
	ds_read_b128 v[212:215], v147 offset:21504
	ds_read_b128 v[216:219], v147 offset:22528
	ds_read_b128 v[220:223], v147 offset:23552
	s_waitcnt vmcnt(0)
	s_waitcnt lgkmcnt(0)
	s_setprio 1
	s_barrier
	v_mfma_f32_16x16x32_bf16 v[56:59], v[192:195], v[168:171], v[56:59]
	v_mfma_f32_16x16x32_bf16 v[52:55], v[200:203], v[138:141], v[52:55]
	v_mfma_f32_16x16x32_bf16 v[48:51], v[200:203], v[168:171], v[48:51]
	v_mfma_f32_16x16x32_bf16 v[44:47], v[208:211], v[138:141], v[44:47]
	v_mfma_f32_16x16x32_bf16 v[40:43], v[208:211], v[168:171], v[40:43]
	v_mfma_f32_16x16x32_bf16 v[36:39], v[216:219], v[138:141], v[36:39]
	v_mfma_f32_16x16x32_bf16 v[32:35], v[216:219], v[168:171], v[32:35]
	v_mfma_f32_16x16x32_bf16 v[28:31], v[192:195], v[176:179], v[28:31]
	v_mfma_f32_16x16x32_bf16 v[24:27], v[192:195], v[184:187], v[24:27]
	v_mfma_f32_16x16x32_bf16 v[20:23], v[200:203], v[176:179], v[20:23]
	v_mfma_f32_16x16x32_bf16 v[16:19], v[200:203], v[184:187], v[16:19]
	v_mfma_f32_16x16x32_bf16 v[12:15], v[208:211], v[176:179], v[12:15]
	v_mfma_f32_16x16x32_bf16 v[8:11], v[208:211], v[184:187], v[8:11]
	v_mfma_f32_16x16x32_bf16 v[4:7], v[216:219], v[176:179], v[4:7]
	v_mfma_f32_16x16x32_bf16 v[0:3], v[216:219], v[184:187], v[0:3]
	v_mfma_f32_16x16x32_bf16 v[60:63], v[192:195], v[138:141], v[60:63]
	v_mfma_f32_16x16x32_bf16 v[56:59], v[196:199], v[172:175], v[56:59]
	v_mfma_f32_16x16x32_bf16 v[52:55], v[204:207], v[142:145], v[52:55]
	v_mfma_f32_16x16x32_bf16 v[48:51], v[204:207], v[172:175], v[48:51]
	v_mfma_f32_16x16x32_bf16 v[44:47], v[212:215], v[142:145], v[44:47]
	v_mfma_f32_16x16x32_bf16 v[40:43], v[212:215], v[172:175], v[40:43]
	v_mfma_f32_16x16x32_bf16 v[36:39], v[220:223], v[142:145], v[36:39]
	v_mfma_f32_16x16x32_bf16 v[32:35], v[220:223], v[172:175], v[32:35]
	v_mfma_f32_16x16x32_bf16 v[28:31], v[196:199], v[180:183], v[28:31]
	v_mfma_f32_16x16x32_bf16 v[24:27], v[196:199], v[188:191], v[24:27]
	v_mfma_f32_16x16x32_bf16 v[20:23], v[204:207], v[180:183], v[20:23]
	v_mfma_f32_16x16x32_bf16 v[16:19], v[204:207], v[188:191], v[16:19]
	v_mfma_f32_16x16x32_bf16 v[12:15], v[212:215], v[180:183], v[12:15]
	v_mfma_f32_16x16x32_bf16 v[8:11], v[212:215], v[188:191], v[8:11]
	v_mfma_f32_16x16x32_bf16 v[4:7], v[220:223], v[180:183], v[4:7]
	v_mfma_f32_16x16x32_bf16 v[0:3], v[220:223], v[188:191], v[0:3]
	v_mfma_f32_16x16x32_bf16 v[224:227], v[196:199], v[142:145], v[60:63]
	s_barrier
; #define LDA(dst, b, h) _Pragma("unroll") for (int m = 0; m < 4; ++m) _Pragma("unroll") for (int k = 0; k < 2; ++k) \
;     dst[m][k] = *reinterpret_cast<const bf16x8*>((const char*)shm + aB + (((b) * 2 + (h)) * 16384 + (m * 2 + k) * 1024))
; #define LDB(dst, b, h) _Pragma("unroll") for (int n = 0; n < 2; ++n) _Pragma("unroll") for (int k = 0; k < 2; ++k) \
;     dst[n][k] = *reinterpret_cast<const bf16x8*>((const char*)shm + bB + (((b) * 2 + (h)) * 16384 + (n * 2 + k) * 1024))
; #define WAIT_L(n) asm volatile("s_waitcnt lgkmcnt(" #n ")" ::: "memory")
; #define BAR __builtin_amdgcn_s_barrier()
; #define SCHED __builtin_amdgcn_sched_barrier(0)
; template <int MODE> ...
;     ...
;       LDB(B0, 1, 0); LDB(B1, 1, 1); LDA(At, 1, 0); WAIT_L(0); BAR; MMA2(0, 0, 0, 1); BAR; SCHED;
;       LDA(At, 1, 1); WAIT_L(0); BAR; MMA2(1, 0, 1, 1); BAR; SCHED;
;     }
;     ...
;     if (wr == 0) BAR;
	s_setprio 0
	ds_read_b128 v[138:141], v148 offset:32768
	ds_read_b128 v[142:145], v148 offset:33792
	ds_read_b128 v[168:171], v148 offset:34816
	ds_read_b128 v[172:175], v148 offset:35840
	ds_read_b128 v[176:179], v148 offset:49152
	ds_read_b128 v[180:183], v148 offset:50176
	ds_read_b128 v[184:187], v148 offset:51200
	ds_read_b128 v[188:191], v148 offset:52224
	ds_read_b128 v[60:63], v147 offset:32768
	ds_read_b128 v[192:195], v147 offset:33792
	ds_read_b128 v[196:199], v147 offset:34816
	ds_read_b128 v[200:203], v147 offset:35840
	ds_read_b128 v[204:207], v147 offset:36864
	ds_read_b128 v[208:211], v147 offset:37888
	ds_read_b128 v[212:215], v147 offset:38912
	ds_read_b128 v[216:219], v147 offset:39936
	s_waitcnt lgkmcnt(0)
	s_setprio 1
	s_barrier
	v_mfma_f32_16x16x32_bf16 v[124:127], v[60:63], v[138:141], v[124:127]
	v_mfma_f32_16x16x32_bf16 v[120:123], v[60:63], v[168:171], v[120:123]
	v_mfma_f32_16x16x32_bf16 v[92:95], v[60:63], v[176:179], v[92:95]
	v_mfma_f32_16x16x32_bf16 v[60:63], v[60:63], v[184:187], v[88:91]
	v_mfma_f32_16x16x32_bf16 v[88:91], v[192:195], v[188:191], v[60:63]
	v_mfma_f32_16x16x32_bf16 v[60:63], v[196:199], v[176:179], v[84:87]
	v_mfma_f32_16x16x32_bf16 v[84:87], v[200:203], v[180:183], v[60:63]
	v_mfma_f32_16x16x32_bf16 v[60:63], v[196:199], v[184:187], v[80:83]
	v_mfma_f32_16x16x32_bf16 v[80:83], v[200:203], v[188:191], v[60:63]
	v_mfma_f32_16x16x32_bf16 v[60:63], v[204:207], v[176:179], v[76:79]
	v_mfma_f32_16x16x32_bf16 v[76:79], v[208:211], v[180:183], v[60:63]
	v_mfma_f32_16x16x32_bf16 v[60:63], v[204:207], v[184:187], v[72:75]
	v_mfma_f32_16x16x32_bf16 v[72:75], v[208:211], v[188:191], v[60:63]
	v_mfma_f32_16x16x32_bf16 v[60:63], v[212:215], v[176:179], v[68:71]
	v_mfma_f32_16x16x32_bf16 v[116:119], v[196:199], v[138:141], v[116:119]
	v_mfma_f32_16x16x32_bf16 v[112:115], v[196:199], v[168:171], v[112:115]
	v_mfma_f32_16x16x32_bf16 v[108:111], v[204:207], v[138:141], v[108:111]
	v_mfma_f32_16x16x32_bf16 v[104:107], v[204:207], v[168:171], v[104:107]
	v_mfma_f32_16x16x32_bf16 v[100:103], v[212:215], v[138:141], v[100:103]
	v_mfma_f32_16x16x32_bf16 v[96:99], v[212:215], v[168:171], v[96:99]
	v_mfma_f32_16x16x32_bf16 v[68:71], v[216:219], v[180:183], v[60:63]
	v_mfma_f32_16x16x32_bf16 v[60:63], v[212:215], v[184:187], v[64:67]
	v_mfma_f32_16x16x32_bf16 v[124:127], v[192:195], v[142:145], v[124:127]
	v_mfma_f32_16x16x32_bf16 v[120:123], v[192:195], v[172:175], v[120:123]
	v_mfma_f32_16x16x32_bf16 v[116:119], v[200:203], v[142:145], v[116:119]
	v_mfma_f32_16x16x32_bf16 v[112:115], v[200:203], v[172:175], v[112:115]
	v_mfma_f32_16x16x32_bf16 v[108:111], v[208:211], v[142:145], v[108:111]
	v_mfma_f32_16x16x32_bf16 v[104:107], v[208:211], v[172:175], v[104:107]
	v_mfma_f32_16x16x32_bf16 v[100:103], v[216:219], v[142:145], v[100:103]
	v_mfma_f32_16x16x32_bf16 v[96:99], v[216:219], v[172:175], v[96:99]
	v_mfma_f32_16x16x32_bf16 v[92:95], v[192:195], v[180:183], v[92:95]
	v_mfma_f32_16x16x32_bf16 v[60:63], v[216:219], v[188:191], v[60:63]
	s_barrier
	s_setprio 0
	ds_read_b128 v[192:195], v147 offset:49152
	ds_read_b128 v[196:199], v147 offset:50176
	ds_read_b128 v[200:203], v147 offset:51200
	ds_read_b128 v[204:207], v147 offset:52224
	ds_read_b128 v[208:211], v147 offset:53248
	ds_read_b128 v[212:215], v147 offset:54272
	ds_read_b128 v[216:219], v147 offset:55296
	ds_read_b128 v[220:223], v147 offset:56320
	s_waitcnt lgkmcnt(0)
	s_setprio 1
	s_barrier
	v_mfma_f32_16x16x32_bf16 v[64:67], v[192:195], v[138:141], v[224:227]
	v_mfma_f32_16x16x32_bf16 v[56:59], v[192:195], v[168:171], v[56:59]
	v_mfma_f32_16x16x32_bf16 v[52:55], v[200:203], v[138:141], v[52:55]
	v_mfma_f32_16x16x32_bf16 v[48:51], v[200:203], v[168:171], v[48:51]
	v_mfma_f32_16x16x32_bf16 v[44:47], v[208:211], v[138:141], v[44:47]
	v_mfma_f32_16x16x32_bf16 v[40:43], v[208:211], v[168:171], v[40:43]
	v_mfma_f32_16x16x32_bf16 v[36:39], v[216:219], v[138:141], v[36:39]
	v_mfma_f32_16x16x32_bf16 v[32:35], v[216:219], v[168:171], v[32:35]
	v_mfma_f32_16x16x32_bf16 v[28:31], v[192:195], v[176:179], v[28:31]
	v_mfma_f32_16x16x32_bf16 v[24:27], v[192:195], v[184:187], v[24:27]
	v_mfma_f32_16x16x32_bf16 v[20:23], v[200:203], v[176:179], v[20:23]
	v_mfma_f32_16x16x32_bf16 v[16:19], v[200:203], v[184:187], v[16:19]
	v_mfma_f32_16x16x32_bf16 v[12:15], v[208:211], v[176:179], v[12:15]
	v_mfma_f32_16x16x32_bf16 v[8:11], v[208:211], v[184:187], v[8:11]
	v_mfma_f32_16x16x32_bf16 v[4:7], v[216:219], v[176:179], v[4:7]
	v_mfma_f32_16x16x32_bf16 v[0:3], v[216:219], v[184:187], v[0:3]
	v_mfma_f32_16x16x32_bf16 v[64:67], v[196:199], v[142:145], v[64:67]
	v_mfma_f32_16x16x32_bf16 v[56:59], v[196:199], v[172:175], v[56:59]
	v_mfma_f32_16x16x32_bf16 v[52:55], v[204:207], v[142:145], v[52:55]
	v_mfma_f32_16x16x32_bf16 v[48:51], v[204:207], v[172:175], v[48:51]
	v_mfma_f32_16x16x32_bf16 v[44:47], v[212:215], v[142:145], v[44:47]
	v_mfma_f32_16x16x32_bf16 v[40:43], v[212:215], v[172:175], v[40:43]
	v_mfma_f32_16x16x32_bf16 v[36:39], v[220:223], v[142:145], v[36:39]
	v_mfma_f32_16x16x32_bf16 v[32:35], v[220:223], v[172:175], v[32:35]
	v_mfma_f32_16x16x32_bf16 v[28:31], v[196:199], v[180:183], v[28:31]
	v_mfma_f32_16x16x32_bf16 v[24:27], v[196:199], v[188:191], v[24:27]
	v_mfma_f32_16x16x32_bf16 v[20:23], v[204:207], v[180:183], v[20:23]
	v_mfma_f32_16x16x32_bf16 v[16:19], v[204:207], v[188:191], v[16:19]
	v_mfma_f32_16x16x32_bf16 v[12:15], v[212:215], v[180:183], v[12:15]
	v_mfma_f32_16x16x32_bf16 v[8:11], v[212:215], v[188:191], v[8:11]
	v_mfma_f32_16x16x32_bf16 v[4:7], v[220:223], v[180:183], v[4:7]
	v_mfma_f32_16x16x32_bf16 v[0:3], v[220:223], v[188:191], v[0:3]
	s_barrier
	s_setprio 0
	s_and_saveexec_b64 s[66:67], s[6:7]
	s_cbranch_execz .LBB0_180
	s_barrier

; #define STAGE(Pp, BASE, br, kt) do { const u16* _g = (BASE) + ((long)(br) * K + (long)(kt) * BK); \
;     __builtin_amdgcn_global_load_lds((const unsigned*)(_g + voff0), (unsigned*)((char*)(Pp) + tb16), 16, 0, 0); \
;     __builtin_amdgcn_global_load_lds((const unsigned*)(_g + voff1), (unsigned*)((char*)(Pp) + tb16 + 8192), 16, 0, 0); } while (0)
; #define LDA(dst, b, h) _Pragma("unroll") for (int m = 0; m < 4; ++m) _Pragma("unroll") for (int k = 0; k < 2; ++k) \
;     dst[m][k] = *reinterpret_cast<const bf16x8*>((const char*)shm + aB + (((b) * 2 + (h)) * 16384 + (m * 2 + k) * 1024))
; #define LDB(dst, b, h) _Pragma("unroll") for (int n = 0; n < 2; ++n) _Pragma("unroll") for (int k = 0; k < 2; ++k) \
;     dst[n][k] = *reinterpret_cast<const bf16x8*>((const char*)shm + bB + (((b) * 2 + (h)) * 16384 + (n * 2 + k) * 1024))
; #define WAIT_V(n) asm volatile("s_waitcnt vmcnt(" #n ")" ::: "memory")
; #define WAIT_L(n) asm volatile("s_waitcnt lgkmcnt(" #n ")" ::: "memory")
; #define BAR __builtin_amdgcn_s_barrier()
; #define SCHED __builtin_amdgcn_sched_barrier(0)
; template <int MODE> ...
;     ...
;       LDB(B0, 0, 0); LDB(B1, 0, 1); LDA(At, 0, 0); STAGE(SA(1, 1), A, brow + HALF, t + 1);
;       WAIT_L(0); BAR; MMA2(0, 0, 0, 1); BAR; SCHED;
;       LDA(At, 0, 1); STAGE(SB(0, 0), Bt, bcol, t + 2); STAGE(SB(0, 1), Bt, bcol + HALF, t + 2); STAGE(SA(0, 0), A, brow, t + 2);
;       WAIT_V(6); WAIT_L(0); BAR; MMA2(1, 0, 1, 1); BAR; SCHED;
.LBB0_486:
	s_add_u32 m0, s32, 0xc000
	s_add_u32 s88, s72, s16
	s_addc_u32 s89, s73, s17
	global_load_lds_dwordx4 v140, s[88:89]
	s_add_u32 m0, s32, 0xe000
	s_nop 0
	global_load_lds_dwordx4 v142, s[88:89]
	ds_read_b128 v[166:169], v145
	ds_read_b128 v[170:173], v145 offset:1024
	ds_read_b128 v[174:177], v145 offset:2048
	ds_read_b128 v[178:181], v145 offset:3072
	ds_read_b128 v[182:185], v145 offset:16384
	ds_read_b128 v[186:189], v145 offset:17408
	ds_read_b128 v[190:193], v145 offset:18432
	ds_read_b128 v[194:197], v145 offset:19456
	ds_read_b128 v[198:201], v144
	ds_read_b128 v[202:205], v144 offset:1024
	ds_read_b128 v[206:209], v144 offset:2048
	ds_read_b128 v[210:213], v144 offset:3072
	ds_read_b128 v[214:217], v144 offset:4096
	ds_read_b128 v[218:221], v144 offset:5120
	ds_read_b128 v[222:225], v144 offset:6144
	ds_read_b128 v[226:229], v144 offset:7168
	s_waitcnt vmcnt(8)
	s_waitcnt lgkmcnt(0)
	s_setprio 1
	s_barrier
	v_mfma_f32_16x16x32_bf16 v[124:127], v[198:201], v[166:169], v[124:127]
	v_mfma_f32_16x16x32_bf16 v[120:123], v[198:201], v[174:177], v[120:123]
	v_mfma_f32_16x16x32_bf16 v[116:119], v[206:209], v[166:169], v[116:119]
	v_mfma_f32_16x16x32_bf16 v[112:115], v[206:209], v[174:177], v[112:115]
	v_mfma_f32_16x16x32_bf16 v[108:111], v[214:217], v[166:169], v[108:111]
	v_mfma_f32_16x16x32_bf16 v[104:107], v[214:217], v[174:177], v[104:107]
	v_mfma_f32_16x16x32_bf16 v[100:103], v[222:225], v[166:169], v[100:103]
	v_mfma_f32_16x16x32_bf16 v[96:99], v[222:225], v[174:177], v[96:99]
	v_mfma_f32_16x16x32_bf16 v[92:95], v[198:201], v[182:185], v[92:95]
	v_mfma_f32_16x16x32_bf16 v[88:91], v[198:201], v[190:193], v[88:91]
	v_mfma_f32_16x16x32_bf16 v[84:87], v[206:209], v[182:185], v[84:87]
	v_mfma_f32_16x16x32_bf16 v[80:83], v[206:209], v[190:193], v[80:83]
	v_mfma_f32_16x16x32_bf16 v[76:79], v[214:217], v[182:185], v[76:79]
	v_mfma_f32_16x16x32_bf16 v[72:75], v[214:217], v[190:193], v[72:75]
	v_mfma_f32_16x16x32_bf16 v[68:71], v[222:225], v[182:185], v[68:71]
	v_mfma_f32_16x16x32_bf16 v[64:67], v[222:225], v[190:193], v[64:67]
	v_mfma_f32_16x16x32_bf16 v[124:127], v[202:205], v[170:173], v[124:127]
	v_mfma_f32_16x16x32_bf16 v[120:123], v[202:205], v[178:181], v[120:123]
	v_mfma_f32_16x16x32_bf16 v[116:119], v[210:213], v[170:173], v[116:119]
	v_mfma_f32_16x16x32_bf16 v[112:115], v[210:213], v[178:181], v[112:115]
	v_mfma_f32_16x16x32_bf16 v[108:111], v[218:221], v[170:173], v[108:111]
	v_mfma_f32_16x16x32_bf16 v[104:107], v[218:221], v[178:181], v[104:107]
	v_mfma_f32_16x16x32_bf16 v[100:103], v[226:229], v[170:173], v[100:103]
	v_mfma_f32_16x16x32_bf16 v[96:99], v[226:229], v[178:181], v[96:99]
	v_mfma_f32_16x16x32_bf16 v[92:95], v[202:205], v[186:189], v[92:95]
	v_mfma_f32_16x16x32_bf16 v[88:91], v[202:205], v[194:197], v[88:91]
	v_mfma_f32_16x16x32_bf16 v[84:87], v[210:213], v[186:189], v[84:87]
	v_mfma_f32_16x16x32_bf16 v[80:83], v[210:213], v[194:197], v[80:83]
	v_mfma_f32_16x16x32_bf16 v[76:79], v[218:221], v[186:189], v[76:79]
	v_mfma_f32_16x16x32_bf16 v[72:75], v[218:221], v[194:197], v[72:75]
	v_mfma_f32_16x16x32_bf16 v[68:71], v[226:229], v[186:189], v[68:71]
	v_mfma_f32_16x16x32_bf16 v[64:67], v[226:229], v[194:197], v[64:67]
	s_barrier
	s_setprio 0
	s_add_u32 m0, s32, 0x10000
	s_add_u32 s88, s72, s38
	s_addc_u32 s89, s73, s39
	global_load_lds_dwordx4 v136, s[88:89]
	s_add_u32 m0, s32, 0x12000
	s_add_u32 s90, s72, s40
	s_addc_u32 s91, s73, s41
	global_load_lds_dwordx4 v138, s[88:89]
	s_add_u32 m0, s32, 0x14000
	s_add_u32 s92, s72, s42
	s_addc_u32 s93, s73, s43
	global_load_lds_dwordx4 v136, s[90:91]
	s_add_u32 m0, s32, 0x16000
	s_nop 0
	global_load_lds_dwordx4 v138, s[90:91]
	s_mov_b32 m0, s32
	s_nop 0
	global_load_lds_dwordx4 v140, s[92:93]
	s_add_u32 m0, s32, 0x2000
	s_nop 0
	global_load_lds_dwordx4 v142, s[92:93]
	ds_read_b128 v[198:201], v144 offset:16384
	ds_read_b128 v[202:205], v144 offset:17408
	ds_read_b128 v[206:209], v144 offset:18432
	ds_read_b128 v[210:213], v144 offset:19456
	ds_read_b128 v[214:217], v144 offset:20480
	ds_read_b128 v[218:221], v144 offset:21504
	ds_read_b128 v[222:225], v144 offset:22528
	ds_read_b128 v[226:229], v144 offset:23552
	s_waitcnt vmcnt(8)
	s_waitcnt lgkmcnt(0)
	s_setprio 1
	s_barrier
	v_mfma_f32_16x16x32_bf16 v[60:63], v[198:201], v[166:169], v[60:63]
	v_mfma_f32_16x16x32_bf16 v[56:59], v[198:201], v[174:177], v[56:59]
	v_mfma_f32_16x16x32_bf16 v[52:55], v[206:209], v[166:169], v[52:55]
	v_mfma_f32_16x16x32_bf16 v[48:51], v[206:209], v[174:177], v[48:51]
	v_mfma_f32_16x16x32_bf16 v[44:47], v[214:217], v[166:169], v[44:47]
	v_mfma_f32_16x16x32_bf16 v[40:43], v[214:217], v[174:177], v[40:43]
	v_mfma_f32_16x16x32_bf16 v[36:39], v[222:225], v[166:169], v[36:39]
	v_mfma_f32_16x16x32_bf16 v[32:35], v[222:225], v[174:177], v[32:35]
	v_mfma_f32_16x16x32_bf16 v[28:31], v[198:201], v[182:185], v[28:31]
	v_mfma_f32_16x16x32_bf16 v[24:27], v[198:201], v[190:193], v[24:27]
	v_mfma_f32_16x16x32_bf16 v[20:23], v[206:209], v[182:185], v[20:23]
	v_mfma_f32_16x16x32_bf16 v[16:19], v[206:209], v[190:193], v[16:19]
	v_mfma_f32_16x16x32_bf16 v[12:15], v[214:217], v[182:185], v[12:15]
	v_mfma_f32_16x16x32_bf16 v[8:11], v[214:217], v[190:193], v[8:11]
	v_mfma_f32_16x16x32_bf16 v[4:7], v[222:225], v[182:185], v[4:7]
	v_mfma_f32_16x16x32_bf16 v[0:3], v[222:225], v[190:193], v[0:3]
	v_mfma_f32_16x16x32_bf16 v[60:63], v[202:205], v[170:173], v[60:63]
	v_mfma_f32_16x16x32_bf16 v[56:59], v[202:205], v[178:181], v[56:59]
	v_mfma_f32_16x16x32_bf16 v[52:55], v[210:213], v[170:173], v[52:55]
	v_mfma_f32_16x16x32_bf16 v[48:51], v[210:213], v[178:181], v[48:51]
	v_mfma_f32_16x16x32_bf16 v[44:47], v[218:221], v[170:173], v[44:47]
	v_mfma_f32_16x16x32_bf16 v[40:43], v[218:221], v[178:181], v[40:43]
	v_mfma_f32_16x16x32_bf16 v[36:39], v[226:229], v[170:173], v[36:39]
	v_mfma_f32_16x16x32_bf16 v[32:35], v[226:229], v[178:181], v[32:35]
	v_mfma_f32_16x16x32_bf16 v[28:31], v[202:205], v[186:189], v[28:31]
	v_mfma_f32_16x16x32_bf16 v[24:27], v[202:205], v[194:197], v[24:27]
	v_mfma_f32_16x16x32_bf16 v[20:23], v[210:213], v[186:189], v[20:23]
	v_mfma_f32_16x16x32_bf16 v[16:19], v[210:213], v[194:197], v[16:19]
	v_mfma_f32_16x16x32_bf16 v[12:15], v[218:221], v[186:189], v[12:15]
	v_mfma_f32_16x16x32_bf16 v[8:11], v[218:221], v[194:197], v[8:11]
	v_mfma_f32_16x16x32_bf16 v[4:7], v[226:229], v[186:189], v[4:7]
	v_mfma_f32_16x16x32_bf16 v[0:3], v[226:229], v[194:197], v[0:3]
	s_barrier
; #define STAGE(Pp, BASE, br, kt) do { const u16* _g = (BASE) + ((long)(br) * K + (long)(kt) * BK); \
;     __builtin_amdgcn_global_load_lds((const unsigned*)(_g + voff0), (unsigned*)((char*)(Pp) + tb16), 16, 0, 0); \
;     __builtin_amdgcn_global_load_lds((const unsigned*)(_g + voff1), (unsigned*)((char*)(Pp) + tb16 + 8192), 16, 0, 0); } while (0)
; #define LDA(dst, b, h) _Pragma("unroll") for (int m = 0; m < 4; ++m) _Pragma("unroll") for (int k = 0; k < 2; ++k) \
;     dst[m][k] = *reinterpret_cast<const bf16x8*>((const char*)shm + aB + (((b) * 2 + (h)) * 16384 + (m * 2 + k) * 1024))
; #define LDB(dst, b, h) _Pragma("unroll") for (int n = 0; n < 2; ++n) _Pragma("unroll") for (int k = 0; k < 2; ++k) \
;     dst[n][k] = *reinterpret_cast<const bf16x8*>((const char*)shm + bB + (((b) * 2 + (h)) * 16384 + (n * 2 + k) * 1024))
; #define WAIT_V(n) asm volatile("s_waitcnt vmcnt(" #n ")" ::: "memory")
; #define WAIT_L(n) asm volatile("s_waitcnt lgkmcnt(" #n ")" ::: "memory")
; #define BAR __builtin_amdgcn_s_barrier()
; #define SCHED __builtin_amdgcn_sched_barrier(0)
; template <int MODE> ...
;     ...
;       LDB(B0, 1, 0); LDB(B1, 1, 1); LDA(At, 1, 0); STAGE(SA(0, 1), A, brow + HALF, t + 2);
;       WAIT_L(0); BAR; MMA2(0, 0, 0, 1); BAR; SCHED;
;       LDA(At, 1, 1); STAGE(SB(1, 0), Bt, bcol, t + 3); STAGE(SB(1, 1), Bt, bcol + HALF, t + 3); STAGE(SA(1, 0), A, brow, t + 3);
;       WAIT_V(6); WAIT_L(0); BAR; MMA2(1, 0, 1, 1); BAR; SCHED;
	s_setprio 0
	s_add_u32 m0, s32, 0x4000
	s_add_u32 s88, s72, s44
	s_addc_u32 s89, s73, s45
	global_load_lds_dwordx4 v140, s[88:89]
	s_add_u32 m0, s32, 0x6000
	s_nop 0
	global_load_lds_dwordx4 v142, s[88:89]
	ds_read_b128 v[166:169], v145 offset:32768
	ds_read_b128 v[170:173], v145 offset:33792
	ds_read_b128 v[174:177], v145 offset:34816
	ds_read_b128 v[178:181], v145 offset:35840
	ds_read_b128 v[182:185], v145 offset:49152
	ds_read_b128 v[186:189], v145 offset:50176
	ds_read_b128 v[190:193], v145 offset:51200
	ds_read_b128 v[194:197], v145 offset:52224
	ds_read_b128 v[198:201], v144 offset:32768
	ds_read_b128 v[202:205], v144 offset:33792
	ds_read_b128 v[206:209], v144 offset:34816
	ds_read_b128 v[210:213], v144 offset:35840
	ds_read_b128 v[214:217], v144 offset:36864
	ds_read_b128 v[218:221], v144 offset:37888
	ds_read_b128 v[222:225], v144 offset:38912
	ds_read_b128 v[226:229], v144 offset:39936
	s_waitcnt vmcnt(8)
	s_waitcnt lgkmcnt(0)
	s_setprio 1
	s_barrier
	v_mfma_f32_16x16x32_bf16 v[124:127], v[198:201], v[166:169], v[124:127]
	v_mfma_f32_16x16x32_bf16 v[120:123], v[198:201], v[174:177], v[120:123]
	v_mfma_f32_16x16x32_bf16 v[116:119], v[206:209], v[166:169], v[116:119]
	v_mfma_f32_16x16x32_bf16 v[112:115], v[206:209], v[174:177], v[112:115]
	v_mfma_f32_16x16x32_bf16 v[108:111], v[214:217], v[166:169], v[108:111]
	v_mfma_f32_16x16x32_bf16 v[104:107], v[214:217], v[174:177], v[104:107]
	v_mfma_f32_16x16x32_bf16 v[100:103], v[222:225], v[166:169], v[100:103]
	v_mfma_f32_16x16x32_bf16 v[96:99], v[222:225], v[174:177], v[96:99]
	v_mfma_f32_16x16x32_bf16 v[92:95], v[198:201], v[182:185], v[92:95]
	v_mfma_f32_16x16x32_bf16 v[88:91], v[198:201], v[190:193], v[88:91]
	v_mfma_f32_16x16x32_bf16 v[84:87], v[206:209], v[182:185], v[84:87]
	v_mfma_f32_16x16x32_bf16 v[80:83], v[206:209], v[190:193], v[80:83]
	v_mfma_f32_16x16x32_bf16 v[76:79], v[214:217], v[182:185], v[76:79]
	v_mfma_f32_16x16x32_bf16 v[72:75], v[214:217], v[190:193], v[72:75]
	v_mfma_f32_16x16x32_bf16 v[68:71], v[222:225], v[182:185], v[68:71]
	v_mfma_f32_16x16x32_bf16 v[64:67], v[222:225], v[190:193], v[64:67]
	v_mfma_f32_16x16x32_bf16 v[124:127], v[202:205], v[170:173], v[124:127]
	v_mfma_f32_16x16x32_bf16 v[120:123], v[202:205], v[178:181], v[120:123]
	v_mfma_f32_16x16x32_bf16 v[116:119], v[210:213], v[170:173], v[116:119]
	v_mfma_f32_16x16x32_bf16 v[112:115], v[210:213], v[178:181], v[112:115]
	v_mfma_f32_16x16x32_bf16 v[108:111], v[218:221], v[170:173], v[108:111]
	v_mfma_f32_16x16x32_bf16 v[104:107], v[218:221], v[178:181], v[104:107]
	v_mfma_f32_16x16x32_bf16 v[100:103], v[226:229], v[170:173], v[100:103]
	v_mfma_f32_16x16x32_bf16 v[96:99], v[226:229], v[178:181], v[96:99]
	v_mfma_f32_16x16x32_bf16 v[92:95], v[202:205], v[186:189], v[92:95]
	v_mfma_f32_16x16x32_bf16 v[88:91], v[202:205], v[194:197], v[88:91]
	v_mfma_f32_16x16x32_bf16 v[84:87], v[210:213], v[186:189], v[84:87]
	v_mfma_f32_16x16x32_bf16 v[80:83], v[210:213], v[194:197], v[80:83]
	v_mfma_f32_16x16x32_bf16 v[76:79], v[218:221], v[186:189], v[76:79]
	v_mfma_f32_16x16x32_bf16 v[72:75], v[218:221], v[194:197], v[72:75]
	v_mfma_f32_16x16x32_bf16 v[68:71], v[226:229], v[186:189], v[68:71]
	v_mfma_f32_16x16x32_bf16 v[64:67], v[226:229], v[194:197], v[64:67]
	s_barrier
	s_setprio 0
	s_add_u32 m0, s32, 0x18000
	s_add_u32 s88, s72, s48
	s_addc_u32 s89, s73, s49
	global_load_lds_dwordx4 v136, s[88:89]
	s_add_u32 m0, s32, 0x1a000
	s_add_u32 s90, s72, s50
	s_addc_u32 s91, s73, s51
	global_load_lds_dwordx4 v138, s[88:89]
	s_add_u32 m0, s32, 0x1c000
	s_add_u32 s92, s72, s60
	s_addc_u32 s93, s73, s61
	global_load_lds_dwordx4 v136, s[90:91]
	s_add_u32 m0, s32, 0x1e000
	s_nop 0
	global_load_lds_dwordx4 v138, s[90:91]
	s_add_u32 m0, s32, 0x8000
	s_nop 0
	global_load_lds_dwordx4 v140, s[92:93]
	s_add_u32 m0, s32, 0xa000
	s_nop 0
	global_load_lds_dwordx4 v142, s[92:93]
	ds_read_b128 v[198:201], v144 offset:49152
	ds_read_b128 v[202:205], v144 offset:50176
	ds_read_b128 v[206:209], v144 offset:51200
	ds_read_b128 v[210:213], v144 offset:52224
	ds_read_b128 v[214:217], v144 offset:53248
	ds_read_b128 v[218:221], v144 offset:54272
	ds_read_b128 v[222:225], v144 offset:55296
	ds_read_b128 v[226:229], v144 offset:56320
	s_waitcnt vmcnt(8)
	s_waitcnt lgkmcnt(0)
	s_setprio 1
	s_barrier
	v_mfma_f32_16x16x32_bf16 v[60:63], v[198:201], v[166:169], v[60:63]
	v_mfma_f32_16x16x32_bf16 v[56:59], v[198:201], v[174:177], v[56:59]
	v_mfma_f32_16x16x32_bf16 v[52:55], v[206:209], v[166:169], v[52:55]
	v_mfma_f32_16x16x32_bf16 v[48:51], v[206:209], v[174:177], v[48:51]
	v_mfma_f32_16x16x32_bf16 v[44:47], v[214:217], v[166:169], v[44:47]
	v_mfma_f32_16x16x32_bf16 v[40:43], v[214:217], v[174:177], v[40:43]
	v_mfma_f32_16x16x32_bf16 v[36:39], v[222:225], v[166:169], v[36:39]
	v_mfma_f32_16x16x32_bf16 v[32:35], v[222:225], v[174:177], v[32:35]
	v_mfma_f32_16x16x32_bf16 v[28:31], v[198:201], v[182:185], v[28:31]
	v_mfma_f32_16x16x32_bf16 v[24:27], v[198:201], v[190:193], v[24:27]
	v_mfma_f32_16x16x32_bf16 v[20:23], v[206:209], v[182:185], v[20:23]
	v_mfma_f32_16x16x32_bf16 v[16:19], v[206:209], v[190:193], v[16:19]
	v_mfma_f32_16x16x32_bf16 v[12:15], v[214:217], v[182:185], v[12:15]
	v_mfma_f32_16x16x32_bf16 v[8:11], v[214:217], v[190:193], v[8:11]
	v_mfma_f32_16x16x32_bf16 v[4:7], v[222:225], v[182:185], v[4:7]
	v_mfma_f32_16x16x32_bf16 v[0:3], v[222:225], v[190:193], v[0:3]
	v_mfma_f32_16x16x32_bf16 v[60:63], v[202:205], v[170:173], v[60:63]
	v_mfma_f32_16x16x32_bf16 v[56:59], v[202:205], v[178:181], v[56:59]
	v_mfma_f32_16x16x32_bf16 v[52:55], v[210:213], v[170:173], v[52:55]
	v_mfma_f32_16x16x32_bf16 v[48:51], v[210:213], v[178:181], v[48:51]
	v_mfma_f32_16x16x32_bf16 v[44:47], v[218:221], v[170:173], v[44:47]
	v_mfma_f32_16x16x32_bf16 v[40:43], v[218:221], v[178:181], v[40:43]
	v_mfma_f32_16x16x32_bf16 v[36:39], v[226:229], v[170:173], v[36:39]
	v_mfma_f32_16x16x32_bf16 v[32:35], v[226:229], v[178:181], v[32:35]
	v_mfma_f32_16x16x32_bf16 v[28:31], v[202:205], v[186:189], v[28:31]
	v_mfma_f32_16x16x32_bf16 v[24:27], v[202:205], v[194:197], v[24:27]
	v_mfma_f32_16x16x32_bf16 v[20:23], v[210:213], v[186:189], v[20:23]
	v_mfma_f32_16x16x32_bf16 v[16:19], v[210:213], v[194:197], v[16:19]
	v_mfma_f32_16x16x32_bf16 v[12:15], v[218:221], v[186:189], v[12:15]
	v_mfma_f32_16x16x32_bf16 v[8:11], v[218:221], v[194:197], v[8:11]
	v_mfma_f32_16x16x32_bf16 v[4:7], v[226:229], v[186:189], v[4:7]
	v_mfma_f32_16x16x32_bf16 v[0:3], v[226:229], v[194:197], v[0:3]
	s_barrier
; #define STAGE(Pp, BASE, br, kt) do { const u16* _g = (BASE) + ((long)(br) * K + (long)(kt) * BK); \
;     __builtin_amdgcn_global_load_lds((const unsigned*)(_g + voff0), (unsigned*)((char*)(Pp) + tb16), 16, 0, 0); \
;     __builtin_amdgcn_global_load_lds((const unsigned*)(_g + voff1), (unsigned*)((char*)(Pp) + tb16 + 8192), 16, 0, 0); } while (0)
; #define LDA(dst, b, h) _Pragma("unroll") for (int m = 0; m < 4; ++m) _Pragma("unroll") for (int k = 0; k < 2; ++k) \
;     dst[m][k] = *reinterpret_cast<const bf16x8*>((const char*)shm + aB + (((b) * 2 + (h)) * 16384 + (m * 2 + k) * 1024))
; #define LDB(dst, b, h) _Pragma("unroll") for (int n = 0; n < 2; ++n) _Pragma("unroll") for (int k = 0; k < 2; ++k) \
;     dst[n][k] = *reinterpret_cast<const bf16x8*>((const char*)shm + bB + (((b) * 2 + (h)) * 16384 + (n * 2 + k) * 1024))
; #define WAIT_V(n) asm volatile("s_waitcnt vmcnt(" #n ")" ::: "memory")
; #define WAIT_L(n) asm volatile("s_waitcnt lgkmcnt(" #n ")" ::: "memory")
; #define BAR __builtin_amdgcn_s_barrier()
; #define SCHED __builtin_amdgcn_sched_barrier(0)
; template <int MODE> ...
;     ...
;       WAIT_V(6); WAIT_L(0); BAR; MMA2(1, 0, 1, 1); BAR; SCHED;
;     }
;     {
;       LDB(B0, 0, 0); LDB(B1, 0, 1); LDA(At, 0, 0); STAGE(SA(1, 1), A, brow + HALF, nt - 1);
;       WAIT_L(0); BAR; MMA2(0, 0, 0, 1); BAR; SCHED;
;       LDA(At, 0, 1); WAIT_V(0); WAIT_L(0); BAR; MMA2(1, 0, 1, 1); BAR; SCHED;
	s_setprio 0
	s_add_i32 s63, s63, 2
	s_add_u32 s72, s72, 0x100
	s_addc_u32 s73, s73, 0
	s_cmp_lt_u32 s63, 60
	s_cbranch_scc1 .LBB0_486
	s_add_u32 s70, s70, 0x1f80
	v_readfirstlane_b32 s63, v160
	s_addc_u32 s71, s71, 0
	s_mov_b32 m0, s63
	v_readfirstlane_b32 s63, v161
	ds_read_b128 v[136:139], v145
	ds_read_b128 v[140:143], v145 offset:1024
	ds_read_b128 v[166:169], v145 offset:2048
	ds_read_b128 v[170:173], v145 offset:3072
	ds_read_b128 v[174:177], v145 offset:16384
	ds_read_b128 v[178:181], v145 offset:17408
	ds_read_b128 v[182:185], v145 offset:18432
	ds_read_b128 v[186:189], v145 offset:19456
	ds_read_b128 v[190:193], v144
	ds_read_b128 v[194:197], v144 offset:1024
	ds_read_b128 v[198:201], v144 offset:2048
	ds_read_b128 v[202:205], v144 offset:3072
	ds_read_b128 v[206:209], v144 offset:4096
	ds_read_b128 v[210:213], v144 offset:5120
	ds_read_b128 v[214:217], v144 offset:6144
	ds_read_b128 v[218:221], v144 offset:7168
	global_load_lds_dwordx4 v132, s[70:71]
	s_mov_b32 m0, s63
	s_nop 0
	global_load_lds_dwordx4 v134, s[70:71]
	s_waitcnt vmcnt(8)
	s_waitcnt lgkmcnt(0)
	s_setprio 1
	s_barrier
	v_mfma_f32_16x16x32_bf16 v[124:127], v[190:193], v[136:139], v[124:127]
	v_mfma_f32_16x16x32_bf16 v[116:119], v[198:201], v[136:139], v[116:119]
	v_mfma_f32_16x16x32_bf16 v[108:111], v[206:209], v[136:139], v[108:111]
	v_mfma_f32_16x16x32_bf16 v[100:103], v[214:217], v[136:139], v[100:103]
	v_mfma_f32_16x16x32_bf16 v[96:99], v[214:217], v[166:169], v[96:99]
	v_mfma_f32_16x16x32_bf16 v[92:95], v[190:193], v[174:177], v[92:95]
	v_mfma_f32_16x16x32_bf16 v[88:91], v[190:193], v[182:185], v[88:91]
	v_mfma_f32_16x16x32_bf16 v[80:83], v[198:201], v[182:185], v[80:83]
	v_mfma_f32_16x16x32_bf16 v[76:79], v[206:209], v[174:177], v[76:79]
	v_mfma_f32_16x16x32_bf16 v[124:127], v[194:197], v[140:143], v[124:127]
	v_mfma_f32_16x16x32_bf16 v[120:123], v[190:193], v[166:169], v[120:123]
	v_mfma_f32_16x16x32_bf16 v[116:119], v[202:205], v[140:143], v[116:119]
	v_mfma_f32_16x16x32_bf16 v[112:115], v[198:201], v[166:169], v[112:115]
	v_mfma_f32_16x16x32_bf16 v[108:111], v[210:213], v[140:143], v[108:111]
	v_mfma_f32_16x16x32_bf16 v[104:107], v[206:209], v[166:169], v[104:107]
	v_mfma_f32_16x16x32_bf16 v[100:103], v[218:221], v[140:143], v[100:103]
	v_mfma_f32_16x16x32_bf16 v[96:99], v[218:221], v[170:173], v[96:99]
	v_mfma_f32_16x16x32_bf16 v[92:95], v[194:197], v[178:181], v[92:95]
	v_mfma_f32_16x16x32_bf16 v[88:91], v[194:197], v[186:189], v[88:91]
	v_mfma_f32_16x16x32_bf16 v[84:87], v[198:201], v[174:177], v[84:87]
	v_mfma_f32_16x16x32_bf16 v[80:83], v[202:205], v[186:189], v[80:83]
	v_mfma_f32_16x16x32_bf16 v[76:79], v[210:213], v[178:181], v[76:79]
	v_mfma_f32_16x16x32_bf16 v[72:75], v[206:209], v[182:185], v[72:75]
	v_mfma_f32_16x16x32_bf16 v[68:71], v[214:217], v[174:177], v[68:71]
	v_mfma_f32_16x16x32_bf16 v[64:67], v[214:217], v[182:185], v[64:67]
	v_mfma_f32_16x16x32_bf16 v[222:225], v[194:197], v[170:173], v[120:123]
	v_mfma_f32_16x16x32_bf16 v[226:229], v[202:205], v[170:173], v[112:115]
	v_mfma_f32_16x16x32_bf16 v[230:233], v[210:213], v[170:173], v[104:107]
	v_mfma_f32_16x16x32_bf16 v[190:193], v[202:205], v[178:181], v[84:87]
	v_mfma_f32_16x16x32_bf16 v[194:197], v[210:213], v[186:189], v[72:75]
	v_mfma_f32_16x16x32_bf16 v[198:201], v[218:221], v[178:181], v[68:71]
	v_mfma_f32_16x16x32_bf16 v[202:205], v[218:221], v[186:189], v[64:67]
	s_barrier
	s_setprio 0
	s_nop 0
	ds_read_b128 v[64:67], v144 offset:16384
	ds_read_b128 v[68:71], v144 offset:17408
	ds_read_b128 v[72:75], v144 offset:18432
	ds_read_b128 v[84:87], v144 offset:19456
	ds_read_b128 v[104:107], v144 offset:20480
	ds_read_b128 v[112:115], v144 offset:21504
	ds_read_b128 v[120:123], v144 offset:22528
	ds_read_b128 v[206:209], v144 offset:23552
	s_waitcnt vmcnt(0)
	s_waitcnt lgkmcnt(0)
	s_setprio 1
	s_barrier
	v_mfma_f32_16x16x32_bf16 v[60:63], v[64:67], v[136:139], v[60:63]
	v_mfma_f32_16x16x32_bf16 v[56:59], v[64:67], v[166:169], v[56:59]
	v_mfma_f32_16x16x32_bf16 v[52:55], v[72:75], v[136:139], v[52:55]
	v_mfma_f32_16x16x32_bf16 v[48:51], v[72:75], v[166:169], v[48:51]
	v_mfma_f32_16x16x32_bf16 v[44:47], v[104:107], v[136:139], v[44:47]
	v_mfma_f32_16x16x32_bf16 v[40:43], v[104:107], v[166:169], v[40:43]
	v_mfma_f32_16x16x32_bf16 v[28:31], v[64:67], v[174:177], v[28:31]
	v_mfma_f32_16x16x32_bf16 v[24:27], v[64:67], v[182:185], v[24:27]
	v_mfma_f32_16x16x32_bf16 v[20:23], v[72:75], v[174:177], v[20:23]
	v_mfma_f32_16x16x32_bf16 v[60:63], v[68:71], v[140:143], v[60:63]
	v_mfma_f32_16x16x32_bf16 v[56:59], v[68:71], v[170:173], v[56:59]
	v_mfma_f32_16x16x32_bf16 v[52:55], v[84:87], v[140:143], v[52:55]
	v_mfma_f32_16x16x32_bf16 v[48:51], v[84:87], v[170:173], v[48:51]
	v_mfma_f32_16x16x32_bf16 v[44:47], v[112:115], v[140:143], v[44:47]
	v_mfma_f32_16x16x32_bf16 v[40:43], v[112:115], v[170:173], v[40:43]
	v_mfma_f32_16x16x32_bf16 v[36:39], v[120:123], v[136:139], v[36:39]
	v_mfma_f32_16x16x32_bf16 v[32:35], v[120:123], v[166:169], v[32:35]
	v_mfma_f32_16x16x32_bf16 v[28:31], v[68:71], v[178:181], v[28:31]
	v_mfma_f32_16x16x32_bf16 v[24:27], v[68:71], v[186:189], v[24:27]
	v_mfma_f32_16x16x32_bf16 v[20:23], v[84:87], v[178:181], v[20:23]
	v_mfma_f32_16x16x32_bf16 v[16:19], v[72:75], v[182:185], v[16:19]
	v_mfma_f32_16x16x32_bf16 v[12:15], v[104:107], v[174:177], v[12:15]
	v_mfma_f32_16x16x32_bf16 v[8:11], v[104:107], v[182:185], v[8:11]
	v_mfma_f32_16x16x32_bf16 v[4:7], v[120:123], v[174:177], v[4:7]
	v_mfma_f32_16x16x32_bf16 v[0:3], v[120:123], v[182:185], v[0:3]
	v_mfma_f32_16x16x32_bf16 v[136:139], v[206:209], v[140:143], v[36:39]
	v_mfma_f32_16x16x32_bf16 v[140:143], v[206:209], v[170:173], v[32:35]
	v_mfma_f32_16x16x32_bf16 v[166:169], v[84:87], v[186:189], v[16:19]
	v_mfma_f32_16x16x32_bf16 v[170:173], v[112:115], v[178:181], v[12:15]
	v_mfma_f32_16x16x32_bf16 v[210:213], v[112:115], v[186:189], v[8:11]
	v_mfma_f32_16x16x32_bf16 v[174:177], v[206:209], v[178:181], v[4:7]
	v_mfma_f32_16x16x32_bf16 v[178:181], v[206:209], v[186:189], v[0:3]
	s_barrier
; #define LDA(dst, b, h) _Pragma("unroll") for (int m = 0; m < 4; ++m) _Pragma("unroll") for (int k = 0; k < 2; ++k) \
;     dst[m][k] = *reinterpret_cast<const bf16x8*>((const char*)shm + aB + (((b) * 2 + (h)) * 16384 + (m * 2 + k) * 1024))
; #define LDB(dst, b, h) _Pragma("unroll") for (int n = 0; n < 2; ++n) _Pragma("unroll") for (int k = 0; k < 2; ++k) \
;     dst[n][k] = *reinterpret_cast<const bf16x8*>((const char*)shm + bB + (((b) * 2 + (h)) * 16384 + (n * 2 + k) * 1024))
; #define WAIT_L(n) asm volatile("s_waitcnt lgkmcnt(" #n ")" ::: "memory")
; #define BAR __builtin_amdgcn_s_barrier()
; #define SCHED __builtin_amdgcn_sched_barrier(0)
; template <int MODE> ...
;     ...
;       LDB(B0, 1, 0); LDB(B1, 1, 1); LDA(At, 1, 0); WAIT_L(0); BAR; MMA2(0, 0, 0, 1); BAR; SCHED;
;       LDA(At, 1, 1); WAIT_L(0); BAR; MMA2(1, 0, 1, 1); BAR; SCHED;
;     }
;     ...
;     if (wr == 0) BAR;
	s_setprio 0
	ds_read_b128 v[12:15], v145 offset:32768
	ds_read_b128 v[16:19], v145 offset:33792
	ds_read_b128 v[182:185], v145 offset:34816
	ds_read_b128 v[186:189], v145 offset:35840
	ds_read_b128 v[206:209], v145 offset:49152
	ds_read_b128 v[214:217], v145 offset:50176
	ds_read_b128 v[218:221], v145 offset:51200
	ds_read_b128 v[234:237], v145 offset:52224
	ds_read_b128 v[0:3], v144 offset:32768
	ds_read_b128 v[4:7], v144 offset:33792
	ds_read_b128 v[8:11], v144 offset:34816
	ds_read_b128 v[32:35], v144 offset:35840
	ds_read_b128 v[36:39], v144 offset:36864
	ds_read_b128 v[238:241], v144 offset:37888
	ds_read_b128 v[242:245], v144 offset:38912
	ds_read_b128 v[246:249], v144 offset:39936
	s_waitcnt lgkmcnt(0)
	s_setprio 1
	s_barrier
	v_mfma_f32_16x16x32_bf16 v[64:67], v[0:3], v[12:15], v[124:127]
	v_mfma_f32_16x16x32_bf16 v[68:71], v[242:245], v[182:185], v[96:99]
	v_mfma_f32_16x16x32_bf16 v[120:123], v[4:7], v[16:19], v[64:67]
	v_mfma_f32_16x16x32_bf16 v[64:67], v[0:3], v[182:185], v[222:225]
	v_mfma_f32_16x16x32_bf16 v[84:87], v[246:249], v[186:189], v[68:71]
	v_mfma_f32_16x16x32_bf16 v[68:71], v[0:3], v[206:209], v[92:95]
	v_mfma_f32_16x16x32_bf16 v[0:3], v[0:3], v[218:221], v[88:91]
	v_mfma_f32_16x16x32_bf16 v[88:91], v[4:7], v[234:237], v[0:3]
	v_mfma_f32_16x16x32_bf16 v[0:3], v[8:11], v[206:209], v[190:193]
	v_mfma_f32_16x16x32_bf16 v[124:127], v[4:7], v[186:189], v[64:67]
	v_mfma_f32_16x16x32_bf16 v[64:67], v[8:11], v[12:15], v[116:119]
	v_mfma_f32_16x16x32_bf16 v[72:75], v[32:35], v[214:217], v[0:3]
	v_mfma_f32_16x16x32_bf16 v[0:3], v[8:11], v[218:221], v[80:83]
	v_mfma_f32_16x16x32_bf16 v[112:115], v[32:35], v[16:19], v[64:67]
	v_mfma_f32_16x16x32_bf16 v[64:67], v[8:11], v[182:185], v[226:229]
	v_mfma_f32_16x16x32_bf16 v[92:95], v[32:35], v[234:237], v[0:3]
	v_mfma_f32_16x16x32_bf16 v[0:3], v[36:39], v[206:209], v[76:79]
	v_mfma_f32_16x16x32_bf16 v[116:119], v[32:35], v[186:189], v[64:67]
	v_mfma_f32_16x16x32_bf16 v[64:67], v[36:39], v[12:15], v[108:111]
	v_mfma_f32_16x16x32_bf16 v[76:79], v[238:241], v[214:217], v[0:3]
	v_mfma_f32_16x16x32_bf16 v[0:3], v[36:39], v[218:221], v[194:197]
	v_mfma_f32_16x16x32_bf16 v[104:107], v[238:241], v[16:19], v[64:67]
	v_mfma_f32_16x16x32_bf16 v[64:67], v[36:39], v[182:185], v[230:233]
	v_mfma_f32_16x16x32_bf16 v[96:99], v[238:241], v[234:237], v[0:3]
	v_mfma_f32_16x16x32_bf16 v[0:3], v[242:245], v[206:209], v[198:201]
	v_mfma_f32_16x16x32_bf16 v[108:111], v[238:241], v[186:189], v[64:67]
	v_mfma_f32_16x16x32_bf16 v[64:67], v[242:245], v[12:15], v[100:103]
	v_mfma_f32_16x16x32_bf16 v[80:83], v[246:249], v[214:217], v[0:3]
	v_mfma_f32_16x16x32_bf16 v[0:3], v[242:245], v[218:221], v[202:205]
	v_mfma_f32_16x16x32_bf16 v[64:67], v[246:249], v[16:19], v[64:67]
	v_mfma_f32_16x16x32_bf16 v[68:71], v[4:7], v[214:217], v[68:71]
	v_mfma_f32_16x16x32_bf16 v[100:103], v[246:249], v[234:237], v[0:3]
	s_barrier
	s_setprio 0
	ds_read_b128 v[190:193], v144 offset:49152
	ds_read_b128 v[194:197], v144 offset:50176
	ds_read_b128 v[198:201], v144 offset:51200
	ds_read_b128 v[202:205], v144 offset:52224
	ds_read_b128 v[222:225], v144 offset:53248
	ds_read_b128 v[226:229], v144 offset:54272
	ds_read_b128 v[230:233], v144 offset:55296
	ds_read_b128 v[238:241], v144 offset:56320
	s_waitcnt lgkmcnt(0)
	s_setprio 1
	s_barrier
	v_mfma_f32_16x16x32_bf16 v[4:7], v[190:193], v[182:185], v[56:59]
	v_mfma_f32_16x16x32_bf16 v[8:11], v[198:201], v[182:185], v[48:51]
	v_mfma_f32_16x16x32_bf16 v[0:3], v[190:193], v[12:15], v[60:63]
	v_mfma_f32_16x16x32_bf16 v[32:35], v[194:197], v[186:189], v[4:7]
	v_mfma_f32_16x16x32_bf16 v[4:7], v[198:201], v[12:15], v[52:55]
	v_mfma_f32_16x16x32_bf16 v[36:39], v[202:205], v[186:189], v[8:11]
	v_mfma_f32_16x16x32_bf16 v[8:11], v[222:225], v[12:15], v[44:47]
	v_mfma_f32_16x16x32_bf16 v[12:15], v[230:233], v[12:15], v[136:139]
	v_mfma_f32_16x16x32_bf16 v[0:3], v[194:197], v[16:19], v[0:3]
	v_mfma_f32_16x16x32_bf16 v[4:7], v[202:205], v[16:19], v[4:7]
	v_mfma_f32_16x16x32_bf16 v[8:11], v[226:229], v[16:19], v[8:11]
	v_mfma_f32_16x16x32_bf16 v[12:15], v[238:241], v[16:19], v[12:15]
	v_mfma_f32_16x16x32_bf16 v[16:19], v[230:233], v[182:185], v[140:143]
	v_mfma_f32_16x16x32_bf16 v[24:27], v[190:193], v[218:221], v[24:27]
	v_mfma_f32_16x16x32_bf16 v[44:47], v[238:241], v[186:189], v[16:19]
	v_mfma_f32_16x16x32_bf16 v[16:19], v[190:193], v[206:209], v[28:31]
	v_mfma_f32_16x16x32_bf16 v[48:51], v[194:197], v[234:237], v[24:27]
	v_mfma_f32_16x16x32_bf16 v[24:27], v[198:201], v[218:221], v[166:169]
	v_mfma_f32_16x16x32_bf16 v[28:31], v[222:225], v[218:221], v[210:213]
	v_mfma_f32_16x16x32_bf16 v[40:43], v[222:225], v[182:185], v[40:43]
	v_mfma_f32_16x16x32_bf16 v[20:23], v[198:201], v[206:209], v[20:23]
	v_mfma_f32_16x16x32_bf16 v[52:55], v[202:205], v[234:237], v[24:27]
	v_mfma_f32_16x16x32_bf16 v[24:27], v[222:225], v[206:209], v[170:173]
	v_mfma_f32_16x16x32_bf16 v[56:59], v[226:229], v[234:237], v[28:31]
	v_mfma_f32_16x16x32_bf16 v[28:31], v[230:233], v[206:209], v[174:177]
	v_mfma_f32_16x16x32_bf16 v[60:63], v[230:233], v[218:221], v[178:181]
	v_mfma_f32_16x16x32_bf16 v[40:43], v[226:229], v[186:189], v[40:43]
	v_mfma_f32_16x16x32_bf16 v[16:19], v[194:197], v[214:217], v[16:19]
	v_mfma_f32_16x16x32_bf16 v[20:23], v[202:205], v[214:217], v[20:23]
	v_mfma_f32_16x16x32_bf16 v[24:27], v[226:229], v[214:217], v[24:27]
	v_mfma_f32_16x16x32_bf16 v[28:31], v[238:241], v[214:217], v[28:31]
	v_mfma_f32_16x16x32_bf16 v[60:63], v[238:241], v[234:237], v[60:63]
	s_barrier
	s_setprio 0
	s_and_saveexec_b64 s[70:71], s[6:7]
	s_cbranch_execz .LBB0_489
	s_barrier

; #define STAGE(Pp, BASE, br, kt) do { const u16* _g = (BASE) + ((long)(br) * K + (long)(kt) * BK); \
;     __builtin_amdgcn_global_load_lds((const unsigned*)(_g + voff0), (unsigned*)((char*)(Pp) + tb16), 16, 0, 0); \
;     __builtin_amdgcn_global_load_lds((const unsigned*)(_g + voff1), (unsigned*)((char*)(Pp) + tb16 + 8192), 16, 0, 0); } while (0)
; #define LDA(dst, b, h) _Pragma("unroll") for (int m = 0; m < 4; ++m) _Pragma("unroll") for (int k = 0; k < 2; ++k) \
;     dst[m][k] = *reinterpret_cast<const bf16x8*>((const char*)shm + aB + (((b) * 2 + (h)) * 16384 + (m * 2 + k) * 1024))
; #define LDB(dst, b, h) _Pragma("unroll") for (int n = 0; n < 2; ++n) _Pragma("unroll") for (int k = 0; k < 2; ++k) \
;     dst[n][k] = *reinterpret_cast<const bf16x8*>((const char*)shm + bB + (((b) * 2 + (h)) * 16384 + (n * 2 + k) * 1024))
; #define WAIT_V(n) asm volatile("s_waitcnt vmcnt(" #n ")" ::: "memory")
; #define WAIT_L(n) asm volatile("s_waitcnt lgkmcnt(" #n ")" ::: "memory")
; #define BAR __builtin_amdgcn_s_barrier()
; #define SCHED __builtin_amdgcn_sched_barrier(0)
; template <int MODE> ...
;     ...
;       LDB(B0, 0, 0); LDB(B1, 0, 1); LDA(At, 0, 0); STAGE(SA(1, 1), A, brow + HALF, t + 1);
;       WAIT_L(0); BAR; MMA2(0, 0, 0, 1); BAR; SCHED;
;       LDA(At, 0, 1); STAGE(SB(0, 0), Bt, bcol, t + 2); STAGE(SB(0, 1), Bt, bcol + HALF, t + 2); STAGE(SA(0, 0), A, brow, t + 2);
;       WAIT_V(6); WAIT_L(0); BAR; MMA2(1, 0, 1, 1); BAR; SCHED;
.LBB0_591:
	s_add_u32 m0, s32, 0xc000
	s_add_u32 s88, s10, s38
	s_addc_u32 s89, s11, s39
	global_load_lds_dwordx4 v142, s[88:89]
	s_add_u32 m0, s32, 0xe000
	s_nop 0
	global_load_lds_dwordx4 v144, s[88:89]
	ds_read_b128 v[168:171], v149
	ds_read_b128 v[172:175], v149 offset:1024
	ds_read_b128 v[176:179], v149 offset:2048
	ds_read_b128 v[180:183], v149 offset:3072
	ds_read_b128 v[184:187], v149 offset:16384
	ds_read_b128 v[188:191], v149 offset:17408
	ds_read_b128 v[192:195], v149 offset:18432
	ds_read_b128 v[196:199], v149 offset:19456
	ds_read_b128 v[200:203], v148
	ds_read_b128 v[204:207], v148 offset:1024
	ds_read_b128 v[208:211], v148 offset:2048
	ds_read_b128 v[212:215], v148 offset:3072
	ds_read_b128 v[216:219], v148 offset:4096
	ds_read_b128 v[220:223], v148 offset:5120
	ds_read_b128 v[224:227], v148 offset:6144
	ds_read_b128 v[228:231], v148 offset:7168
	s_waitcnt vmcnt(8)
	s_waitcnt lgkmcnt(0)
	s_setprio 1
	s_barrier
	v_mfma_f32_16x16x32_bf16 v[124:127], v[200:203], v[168:171], v[124:127]
	v_mfma_f32_16x16x32_bf16 v[120:123], v[200:203], v[176:179], v[120:123]
	v_mfma_f32_16x16x32_bf16 v[116:119], v[208:211], v[168:171], v[116:119]
	v_mfma_f32_16x16x32_bf16 v[112:115], v[208:211], v[176:179], v[112:115]
	v_mfma_f32_16x16x32_bf16 v[108:111], v[216:219], v[168:171], v[108:111]
	v_mfma_f32_16x16x32_bf16 v[104:107], v[216:219], v[176:179], v[104:107]
	v_mfma_f32_16x16x32_bf16 v[100:103], v[224:227], v[168:171], v[100:103]
	v_mfma_f32_16x16x32_bf16 v[96:99], v[224:227], v[176:179], v[96:99]
	v_mfma_f32_16x16x32_bf16 v[88:91], v[200:203], v[184:187], v[88:91]
	v_mfma_f32_16x16x32_bf16 v[72:75], v[200:203], v[192:195], v[72:75]
	v_mfma_f32_16x16x32_bf16 v[56:59], v[208:211], v[184:187], v[56:59]
	v_mfma_f32_16x16x32_bf16 v[48:51], v[208:211], v[192:195], v[48:51]
	v_mfma_f32_16x16x32_bf16 v[44:47], v[216:219], v[184:187], v[44:47]
	v_mfma_f32_16x16x32_bf16 v[40:43], v[216:219], v[192:195], v[40:43]
	v_mfma_f32_16x16x32_bf16 v[36:39], v[224:227], v[184:187], v[36:39]
	v_mfma_f32_16x16x32_bf16 v[32:35], v[224:227], v[192:195], v[32:35]
	v_mfma_f32_16x16x32_bf16 v[124:127], v[204:207], v[172:175], v[124:127]
	v_mfma_f32_16x16x32_bf16 v[120:123], v[204:207], v[180:183], v[120:123]
	v_mfma_f32_16x16x32_bf16 v[116:119], v[212:215], v[172:175], v[116:119]
	v_mfma_f32_16x16x32_bf16 v[112:115], v[212:215], v[180:183], v[112:115]
	v_mfma_f32_16x16x32_bf16 v[108:111], v[220:223], v[172:175], v[108:111]
	v_mfma_f32_16x16x32_bf16 v[104:107], v[220:223], v[180:183], v[104:107]
	v_mfma_f32_16x16x32_bf16 v[100:103], v[228:231], v[172:175], v[100:103]
	v_mfma_f32_16x16x32_bf16 v[96:99], v[228:231], v[180:183], v[96:99]
	v_mfma_f32_16x16x32_bf16 v[88:91], v[204:207], v[188:191], v[88:91]
	v_mfma_f32_16x16x32_bf16 v[72:75], v[204:207], v[196:199], v[72:75]
	v_mfma_f32_16x16x32_bf16 v[56:59], v[212:215], v[188:191], v[56:59]
	v_mfma_f32_16x16x32_bf16 v[48:51], v[212:215], v[196:199], v[48:51]
	v_mfma_f32_16x16x32_bf16 v[44:47], v[220:223], v[188:191], v[44:47]
	v_mfma_f32_16x16x32_bf16 v[40:43], v[220:223], v[196:199], v[40:43]
	v_mfma_f32_16x16x32_bf16 v[36:39], v[228:231], v[188:191], v[36:39]
	v_mfma_f32_16x16x32_bf16 v[32:35], v[228:231], v[196:199], v[32:35]
	s_barrier
	s_setprio 0
	s_add_u32 m0, s32, 0x10000
	s_add_u32 s88, s10, s40
	s_addc_u32 s89, s11, s41
	global_load_lds_dwordx4 v138, s[88:89]
	s_add_u32 m0, s32, 0x12000
	s_add_u32 s90, s10, s42
	s_addc_u32 s91, s11, s43
	global_load_lds_dwordx4 v140, s[88:89]
	s_add_u32 m0, s32, 0x14000
	s_add_u32 s92, s10, s44
	s_addc_u32 s93, s11, s45
	global_load_lds_dwordx4 v138, s[90:91]
	s_add_u32 m0, s32, 0x16000
	s_nop 0
	global_load_lds_dwordx4 v140, s[90:91]
	s_mov_b32 m0, s32
	s_nop 0
	global_load_lds_dwordx4 v142, s[92:93]
	s_add_u32 m0, s32, 0x2000
	s_nop 0
	global_load_lds_dwordx4 v144, s[92:93]
	ds_read_b128 v[200:203], v148 offset:16384
	ds_read_b128 v[204:207], v148 offset:17408
	ds_read_b128 v[208:211], v148 offset:18432
	ds_read_b128 v[212:215], v148 offset:19456
	ds_read_b128 v[216:219], v148 offset:20480
	ds_read_b128 v[220:223], v148 offset:21504
	ds_read_b128 v[224:227], v148 offset:22528
	ds_read_b128 v[228:231], v148 offset:23552
	s_waitcnt vmcnt(8)
	s_waitcnt lgkmcnt(0)
	s_setprio 1
	s_barrier
	v_mfma_f32_16x16x32_bf16 v[28:31], v[200:203], v[168:171], v[28:31]
	v_mfma_f32_16x16x32_bf16 v[24:27], v[200:203], v[176:179], v[24:27]
	v_mfma_f32_16x16x32_bf16 v[20:23], v[208:211], v[168:171], v[20:23]
	v_mfma_f32_16x16x32_bf16 v[16:19], v[208:211], v[176:179], v[16:19]
	v_mfma_f32_16x16x32_bf16 v[12:15], v[216:219], v[168:171], v[12:15]
	v_mfma_f32_16x16x32_bf16 v[8:11], v[216:219], v[176:179], v[8:11]
	v_mfma_f32_16x16x32_bf16 v[4:7], v[224:227], v[168:171], v[4:7]
	v_mfma_f32_16x16x32_bf16 v[0:3], v[224:227], v[176:179], v[0:3]
	v_mfma_f32_16x16x32_bf16 v[52:55], v[200:203], v[184:187], v[52:55]
	v_mfma_f32_16x16x32_bf16 v[60:63], v[200:203], v[192:195], v[60:63]
	v_mfma_f32_16x16x32_bf16 v[64:67], v[208:211], v[184:187], v[64:67]
	v_mfma_f32_16x16x32_bf16 v[68:71], v[208:211], v[192:195], v[68:71]
	v_mfma_f32_16x16x32_bf16 v[76:79], v[216:219], v[184:187], v[76:79]
	v_mfma_f32_16x16x32_bf16 v[80:83], v[216:219], v[192:195], v[80:83]
	v_mfma_f32_16x16x32_bf16 v[84:87], v[224:227], v[184:187], v[84:87]
	v_mfma_f32_16x16x32_bf16 v[92:95], v[224:227], v[192:195], v[92:95]
	v_mfma_f32_16x16x32_bf16 v[28:31], v[204:207], v[172:175], v[28:31]
	v_mfma_f32_16x16x32_bf16 v[24:27], v[204:207], v[180:183], v[24:27]
	v_mfma_f32_16x16x32_bf16 v[20:23], v[212:215], v[172:175], v[20:23]
	v_mfma_f32_16x16x32_bf16 v[16:19], v[212:215], v[180:183], v[16:19]
	v_mfma_f32_16x16x32_bf16 v[12:15], v[220:223], v[172:175], v[12:15]
	v_mfma_f32_16x16x32_bf16 v[8:11], v[220:223], v[180:183], v[8:11]
	v_mfma_f32_16x16x32_bf16 v[4:7], v[228:231], v[172:175], v[4:7]
	v_mfma_f32_16x16x32_bf16 v[0:3], v[228:231], v[180:183], v[0:3]
	v_mfma_f32_16x16x32_bf16 v[52:55], v[204:207], v[188:191], v[52:55]
	v_mfma_f32_16x16x32_bf16 v[60:63], v[204:207], v[196:199], v[60:63]
	v_mfma_f32_16x16x32_bf16 v[64:67], v[212:215], v[188:191], v[64:67]
	v_mfma_f32_16x16x32_bf16 v[68:71], v[212:215], v[196:199], v[68:71]
	v_mfma_f32_16x16x32_bf16 v[76:79], v[220:223], v[188:191], v[76:79]
	v_mfma_f32_16x16x32_bf16 v[80:83], v[220:223], v[196:199], v[80:83]
	v_mfma_f32_16x16x32_bf16 v[84:87], v[228:231], v[188:191], v[84:87]
	v_mfma_f32_16x16x32_bf16 v[92:95], v[228:231], v[196:199], v[92:95]
	s_barrier
; #define STAGE(Pp, BASE, br, kt) do { const u16* _g = (BASE) + ((long)(br) * K + (long)(kt) * BK); \
;     __builtin_amdgcn_global_load_lds((const unsigned*)(_g + voff0), (unsigned*)((char*)(Pp) + tb16), 16, 0, 0); \
;     __builtin_amdgcn_global_load_lds((const unsigned*)(_g + voff1), (unsigned*)((char*)(Pp) + tb16 + 8192), 16, 0, 0); } while (0)
; #define LDA(dst, b, h) _Pragma("unroll") for (int m = 0; m < 4; ++m) _Pragma("unroll") for (int k = 0; k < 2; ++k) \
;     dst[m][k] = *reinterpret_cast<const bf16x8*>((const char*)shm + aB + (((b) * 2 + (h)) * 16384 + (m * 2 + k) * 1024))
; #define LDB(dst, b, h) _Pragma("unroll") for (int n = 0; n < 2; ++n) _Pragma("unroll") for (int k = 0; k < 2; ++k) \
;     dst[n][k] = *reinterpret_cast<const bf16x8*>((const char*)shm + bB + (((b) * 2 + (h)) * 16384 + (n * 2 + k) * 1024))
; #define WAIT_V(n) asm volatile("s_waitcnt vmcnt(" #n ")" ::: "memory")
; #define WAIT_L(n) asm volatile("s_waitcnt lgkmcnt(" #n ")" ::: "memory")
; #define BAR __builtin_amdgcn_s_barrier()
; #define SCHED __builtin_amdgcn_sched_barrier(0)
; template <int MODE> ...
;     ...
;       LDB(B0, 1, 0); LDB(B1, 1, 1); LDA(At, 1, 0); STAGE(SA(0, 1), A, brow + HALF, t + 2);
;       WAIT_L(0); BAR; MMA2(0, 0, 0, 1); BAR; SCHED;
;       LDA(At, 1, 1); STAGE(SB(1, 0), Bt, bcol, t + 3); STAGE(SB(1, 1), Bt, bcol + HALF, t + 3); STAGE(SA(1, 0), A, brow, t + 3);
;       WAIT_V(6); WAIT_L(0); BAR; MMA2(1, 0, 1, 1); BAR; SCHED;
	s_setprio 0
	s_add_u32 m0, s32, 0x4000
	s_add_u32 s88, s10, s48
	s_addc_u32 s89, s11, s49
	global_load_lds_dwordx4 v142, s[88:89]
	s_add_u32 m0, s32, 0x6000
	s_nop 0
	global_load_lds_dwordx4 v144, s[88:89]
	ds_read_b128 v[168:171], v149 offset:32768
	ds_read_b128 v[172:175], v149 offset:33792
	ds_read_b128 v[176:179], v149 offset:34816
	ds_read_b128 v[180:183], v149 offset:35840
	ds_read_b128 v[184:187], v149 offset:49152
	ds_read_b128 v[188:191], v149 offset:50176
	ds_read_b128 v[192:195], v149 offset:51200
	ds_read_b128 v[196:199], v149 offset:52224
	ds_read_b128 v[200:203], v148 offset:32768
	ds_read_b128 v[204:207], v148 offset:33792
	ds_read_b128 v[208:211], v148 offset:34816
	ds_read_b128 v[212:215], v148 offset:35840
	ds_read_b128 v[216:219], v148 offset:36864
	ds_read_b128 v[220:223], v148 offset:37888
	ds_read_b128 v[224:227], v148 offset:38912
	ds_read_b128 v[228:231], v148 offset:39936
	s_waitcnt vmcnt(8)
	s_waitcnt lgkmcnt(0)
	s_setprio 1
	s_barrier
	v_mfma_f32_16x16x32_bf16 v[124:127], v[200:203], v[168:171], v[124:127]
	v_mfma_f32_16x16x32_bf16 v[120:123], v[200:203], v[176:179], v[120:123]
	v_mfma_f32_16x16x32_bf16 v[116:119], v[208:211], v[168:171], v[116:119]
	v_mfma_f32_16x16x32_bf16 v[112:115], v[208:211], v[176:179], v[112:115]
	v_mfma_f32_16x16x32_bf16 v[108:111], v[216:219], v[168:171], v[108:111]
	v_mfma_f32_16x16x32_bf16 v[104:107], v[216:219], v[176:179], v[104:107]
	v_mfma_f32_16x16x32_bf16 v[100:103], v[224:227], v[168:171], v[100:103]
	v_mfma_f32_16x16x32_bf16 v[96:99], v[224:227], v[176:179], v[96:99]
	v_mfma_f32_16x16x32_bf16 v[88:91], v[200:203], v[184:187], v[88:91]
	v_mfma_f32_16x16x32_bf16 v[72:75], v[200:203], v[192:195], v[72:75]
	v_mfma_f32_16x16x32_bf16 v[56:59], v[208:211], v[184:187], v[56:59]
	v_mfma_f32_16x16x32_bf16 v[48:51], v[208:211], v[192:195], v[48:51]
	v_mfma_f32_16x16x32_bf16 v[44:47], v[216:219], v[184:187], v[44:47]
	v_mfma_f32_16x16x32_bf16 v[40:43], v[216:219], v[192:195], v[40:43]
	v_mfma_f32_16x16x32_bf16 v[36:39], v[224:227], v[184:187], v[36:39]
	v_mfma_f32_16x16x32_bf16 v[32:35], v[224:227], v[192:195], v[32:35]
	v_mfma_f32_16x16x32_bf16 v[124:127], v[204:207], v[172:175], v[124:127]
	v_mfma_f32_16x16x32_bf16 v[120:123], v[204:207], v[180:183], v[120:123]
	v_mfma_f32_16x16x32_bf16 v[116:119], v[212:215], v[172:175], v[116:119]
	v_mfma_f32_16x16x32_bf16 v[112:115], v[212:215], v[180:183], v[112:115]
	v_mfma_f32_16x16x32_bf16 v[108:111], v[220:223], v[172:175], v[108:111]
	v_mfma_f32_16x16x32_bf16 v[104:107], v[220:223], v[180:183], v[104:107]
	v_mfma_f32_16x16x32_bf16 v[100:103], v[228:231], v[172:175], v[100:103]
	v_mfma_f32_16x16x32_bf16 v[96:99], v[228:231], v[180:183], v[96:99]
	v_mfma_f32_16x16x32_bf16 v[88:91], v[204:207], v[188:191], v[88:91]
	v_mfma_f32_16x16x32_bf16 v[72:75], v[204:207], v[196:199], v[72:75]
	v_mfma_f32_16x16x32_bf16 v[56:59], v[212:215], v[188:191], v[56:59]
	v_mfma_f32_16x16x32_bf16 v[48:51], v[212:215], v[196:199], v[48:51]
	v_mfma_f32_16x16x32_bf16 v[44:47], v[220:223], v[188:191], v[44:47]
	v_mfma_f32_16x16x32_bf16 v[40:43], v[220:223], v[196:199], v[40:43]
	v_mfma_f32_16x16x32_bf16 v[36:39], v[228:231], v[188:191], v[36:39]
	v_mfma_f32_16x16x32_bf16 v[32:35], v[228:231], v[196:199], v[32:35]
	s_barrier
	s_setprio 0
	s_add_u32 m0, s32, 0x18000
	s_add_u32 s88, s10, s50
	s_addc_u32 s89, s11, s51
	global_load_lds_dwordx4 v138, s[88:89]
	s_add_u32 m0, s32, 0x1a000
	s_add_u32 s90, s10, s60
	s_addc_u32 s91, s11, s61
	global_load_lds_dwordx4 v140, s[88:89]
	s_add_u32 m0, s32, 0x1c000
	s_add_u32 s92, s10, s62
	s_addc_u32 s93, s11, s63
	global_load_lds_dwordx4 v138, s[90:91]
	s_add_u32 m0, s32, 0x1e000
	s_nop 0
	global_load_lds_dwordx4 v140, s[90:91]
	s_add_u32 m0, s32, 0x8000
	s_nop 0
	global_load_lds_dwordx4 v142, s[92:93]
	s_add_u32 m0, s32, 0xa000
	s_nop 0
	global_load_lds_dwordx4 v144, s[92:93]
	ds_read_b128 v[200:203], v148 offset:49152
	ds_read_b128 v[204:207], v148 offset:50176
	ds_read_b128 v[208:211], v148 offset:51200
	ds_read_b128 v[212:215], v148 offset:52224
	ds_read_b128 v[216:219], v148 offset:53248
	ds_read_b128 v[220:223], v148 offset:54272
	ds_read_b128 v[224:227], v148 offset:55296
	ds_read_b128 v[228:231], v148 offset:56320
	s_waitcnt vmcnt(8)
	s_waitcnt lgkmcnt(0)
	s_setprio 1
	s_barrier
	v_mfma_f32_16x16x32_bf16 v[28:31], v[200:203], v[168:171], v[28:31]
	v_mfma_f32_16x16x32_bf16 v[24:27], v[200:203], v[176:179], v[24:27]
	v_mfma_f32_16x16x32_bf16 v[20:23], v[208:211], v[168:171], v[20:23]
	v_mfma_f32_16x16x32_bf16 v[16:19], v[208:211], v[176:179], v[16:19]
	v_mfma_f32_16x16x32_bf16 v[12:15], v[216:219], v[168:171], v[12:15]
	v_mfma_f32_16x16x32_bf16 v[8:11], v[216:219], v[176:179], v[8:11]
	v_mfma_f32_16x16x32_bf16 v[4:7], v[224:227], v[168:171], v[4:7]
	v_mfma_f32_16x16x32_bf16 v[0:3], v[224:227], v[176:179], v[0:3]
	v_mfma_f32_16x16x32_bf16 v[52:55], v[200:203], v[184:187], v[52:55]
	v_mfma_f32_16x16x32_bf16 v[60:63], v[200:203], v[192:195], v[60:63]
	v_mfma_f32_16x16x32_bf16 v[64:67], v[208:211], v[184:187], v[64:67]
	v_mfma_f32_16x16x32_bf16 v[68:71], v[208:211], v[192:195], v[68:71]
	v_mfma_f32_16x16x32_bf16 v[76:79], v[216:219], v[184:187], v[76:79]
	v_mfma_f32_16x16x32_bf16 v[80:83], v[216:219], v[192:195], v[80:83]
	v_mfma_f32_16x16x32_bf16 v[84:87], v[224:227], v[184:187], v[84:87]
	v_mfma_f32_16x16x32_bf16 v[92:95], v[224:227], v[192:195], v[92:95]
	v_mfma_f32_16x16x32_bf16 v[28:31], v[204:207], v[172:175], v[28:31]
	v_mfma_f32_16x16x32_bf16 v[24:27], v[204:207], v[180:183], v[24:27]
	v_mfma_f32_16x16x32_bf16 v[20:23], v[212:215], v[172:175], v[20:23]
	v_mfma_f32_16x16x32_bf16 v[16:19], v[212:215], v[180:183], v[16:19]
	v_mfma_f32_16x16x32_bf16 v[12:15], v[220:223], v[172:175], v[12:15]
	v_mfma_f32_16x16x32_bf16 v[8:11], v[220:223], v[180:183], v[8:11]
	v_mfma_f32_16x16x32_bf16 v[4:7], v[228:231], v[172:175], v[4:7]
	v_mfma_f32_16x16x32_bf16 v[0:3], v[228:231], v[180:183], v[0:3]
	v_mfma_f32_16x16x32_bf16 v[52:55], v[204:207], v[188:191], v[52:55]
	v_mfma_f32_16x16x32_bf16 v[60:63], v[204:207], v[196:199], v[60:63]
	v_mfma_f32_16x16x32_bf16 v[64:67], v[212:215], v[188:191], v[64:67]
	v_mfma_f32_16x16x32_bf16 v[68:71], v[212:215], v[196:199], v[68:71]
	v_mfma_f32_16x16x32_bf16 v[76:79], v[220:223], v[188:191], v[76:79]
	v_mfma_f32_16x16x32_bf16 v[80:83], v[220:223], v[196:199], v[80:83]
	v_mfma_f32_16x16x32_bf16 v[84:87], v[228:231], v[188:191], v[84:87]
	v_mfma_f32_16x16x32_bf16 v[92:95], v[228:231], v[196:199], v[92:95]
	s_barrier
; #define STAGE(Pp, BASE, br, kt) do { const u16* _g = (BASE) + ((long)(br) * K + (long)(kt) * BK); \
;     __builtin_amdgcn_global_load_lds((const unsigned*)(_g + voff0), (unsigned*)((char*)(Pp) + tb16), 16, 0, 0); \
;     __builtin_amdgcn_global_load_lds((const unsigned*)(_g + voff1), (unsigned*)((char*)(Pp) + tb16 + 8192), 16, 0, 0); } while (0)
; #define LDA(dst, b, h) _Pragma("unroll") for (int m = 0; m < 4; ++m) _Pragma("unroll") for (int k = 0; k < 2; ++k) \
;     dst[m][k] = *reinterpret_cast<const bf16x8*>((const char*)shm + aB + (((b) * 2 + (h)) * 16384 + (m * 2 + k) * 1024))
; #define LDB(dst, b, h) _Pragma("unroll") for (int n = 0; n < 2; ++n) _Pragma("unroll") for (int k = 0; k < 2; ++k) \
;     dst[n][k] = *reinterpret_cast<const bf16x8*>((const char*)shm + bB + (((b) * 2 + (h)) * 16384 + (n * 2 + k) * 1024))
; #define WAIT_V(n) asm volatile("s_waitcnt vmcnt(" #n ")" ::: "memory")
; #define WAIT_L(n) asm volatile("s_waitcnt lgkmcnt(" #n ")" ::: "memory")
; #define BAR __builtin_amdgcn_s_barrier()
; #define SCHED __builtin_amdgcn_sched_barrier(0)
; template <int MODE> ...
;     ...
;     }
;     {
;       LDB(B0, 0, 0); LDB(B1, 0, 1); LDA(At, 0, 0); STAGE(SA(1, 1), A, brow + HALF, nt - 1);
;       WAIT_L(0); BAR; MMA2(0, 0, 0, 1); BAR; SCHED;
;       LDA(At, 0, 1); WAIT_V(0); WAIT_L(0); BAR; MMA2(1, 0, 1, 1); BAR; SCHED;
	s_setprio 0
	s_add_i32 s35, s35, 2
	s_add_u32 s10, s10, 0x100
	s_addc_u32 s11, s11, 0
	s_cmp_lt_u32 s35, 60
	s_cbranch_scc1 .LBB0_591
	s_add_u32 s8, s8, 0x1f80
	v_readfirstlane_b32 s10, v165
	s_addc_u32 s9, s9, 0
	s_mov_b32 m0, s10
	v_readfirstlane_b32 s10, v166
	ds_read_b128 v[138:141], v149
	ds_read_b128 v[142:145], v149 offset:1024
	ds_read_b128 v[168:171], v149 offset:2048
	ds_read_b128 v[172:175], v149 offset:3072
	ds_read_b128 v[176:179], v149 offset:16384
	ds_read_b128 v[180:183], v149 offset:17408
	ds_read_b128 v[184:187], v149 offset:18432
	ds_read_b128 v[188:191], v149 offset:19456
	ds_read_b128 v[192:195], v148
	ds_read_b128 v[196:199], v148 offset:1024
	ds_read_b128 v[200:203], v148 offset:2048
	ds_read_b128 v[204:207], v148 offset:3072
	ds_read_b128 v[208:211], v148 offset:4096
	ds_read_b128 v[212:215], v148 offset:5120
	ds_read_b128 v[216:219], v148 offset:6144
	ds_read_b128 v[220:223], v148 offset:7168
	global_load_lds_dwordx4 v134, s[8:9]
	s_mov_b32 m0, s10
	s_nop 0
	global_load_lds_dwordx4 v136, s[8:9]
	s_waitcnt vmcnt(8)
	s_waitcnt lgkmcnt(0)
	s_setprio 1
	s_barrier
	v_mfma_f32_16x16x32_bf16 v[124:127], v[192:195], v[138:141], v[124:127]
	v_mfma_f32_16x16x32_bf16 v[120:123], v[192:195], v[168:171], v[120:123]
	v_mfma_f32_16x16x32_bf16 v[116:119], v[200:203], v[138:141], v[116:119]
	v_mfma_f32_16x16x32_bf16 v[112:115], v[200:203], v[168:171], v[112:115]
	v_mfma_f32_16x16x32_bf16 v[108:111], v[208:211], v[138:141], v[108:111]
	v_mfma_f32_16x16x32_bf16 v[104:107], v[208:211], v[168:171], v[104:107]
	v_mfma_f32_16x16x32_bf16 v[96:99], v[216:219], v[168:171], v[96:99]
	v_mfma_f32_16x16x32_bf16 v[88:91], v[192:195], v[176:179], v[88:91]
	v_mfma_f32_16x16x32_bf16 v[72:75], v[192:195], v[184:187], v[72:75]
	v_mfma_f32_16x16x32_bf16 v[56:59], v[200:203], v[176:179], v[56:59]
	v_mfma_f32_16x16x32_bf16 v[48:51], v[200:203], v[184:187], v[48:51]
	v_mfma_f32_16x16x32_bf16 v[44:47], v[208:211], v[176:179], v[44:47]
	v_mfma_f32_16x16x32_bf16 v[40:43], v[208:211], v[184:187], v[40:43]
	v_mfma_f32_16x16x32_bf16 v[36:39], v[216:219], v[176:179], v[36:39]
	v_mfma_f32_16x16x32_bf16 v[32:35], v[216:219], v[184:187], v[32:35]
	v_mfma_f32_16x16x32_bf16 v[124:127], v[196:199], v[142:145], v[124:127]
	v_mfma_f32_16x16x32_bf16 v[120:123], v[196:199], v[172:175], v[120:123]
	v_mfma_f32_16x16x32_bf16 v[116:119], v[204:207], v[142:145], v[116:119]
	v_mfma_f32_16x16x32_bf16 v[112:115], v[204:207], v[172:175], v[112:115]
	v_mfma_f32_16x16x32_bf16 v[108:111], v[212:215], v[142:145], v[108:111]
	v_mfma_f32_16x16x32_bf16 v[104:107], v[212:215], v[172:175], v[104:107]
	v_mfma_f32_16x16x32_bf16 v[100:103], v[216:219], v[138:141], v[100:103]
	v_mfma_f32_16x16x32_bf16 v[96:99], v[220:223], v[172:175], v[96:99]
	v_mfma_f32_16x16x32_bf16 v[88:91], v[196:199], v[180:183], v[88:91]
	v_mfma_f32_16x16x32_bf16 v[72:75], v[196:199], v[188:191], v[72:75]
	v_mfma_f32_16x16x32_bf16 v[56:59], v[204:207], v[180:183], v[56:59]
	v_mfma_f32_16x16x32_bf16 v[48:51], v[204:207], v[188:191], v[48:51]
	v_mfma_f32_16x16x32_bf16 v[44:47], v[212:215], v[180:183], v[44:47]
	v_mfma_f32_16x16x32_bf16 v[40:43], v[212:215], v[188:191], v[40:43]
	v_mfma_f32_16x16x32_bf16 v[36:39], v[220:223], v[180:183], v[36:39]
	v_mfma_f32_16x16x32_bf16 v[32:35], v[220:223], v[188:191], v[32:35]
	v_mfma_f32_16x16x32_bf16 v[224:227], v[220:223], v[142:145], v[100:103]
	s_barrier
	s_setprio 0
	s_nop 0
	ds_read_b128 v[100:103], v148 offset:16384
	ds_read_b128 v[192:195], v148 offset:17408
	ds_read_b128 v[196:199], v148 offset:18432
	ds_read_b128 v[200:203], v148 offset:19456
	ds_read_b128 v[204:207], v148 offset:20480
	ds_read_b128 v[208:211], v148 offset:21504
	ds_read_b128 v[212:215], v148 offset:22528
	ds_read_b128 v[216:219], v148 offset:23552
	s_waitcnt vmcnt(0)
	s_waitcnt lgkmcnt(0)
	s_setprio 1
	s_barrier
	v_mfma_f32_16x16x32_bf16 v[28:31], v[100:103], v[138:141], v[28:31]
	v_mfma_f32_16x16x32_bf16 v[20:23], v[196:199], v[138:141], v[20:23]
	v_mfma_f32_16x16x32_bf16 v[12:15], v[204:207], v[138:141], v[12:15]
	v_mfma_f32_16x16x32_bf16 v[4:7], v[212:215], v[138:141], v[4:7]
	v_mfma_f32_16x16x32_bf16 v[0:3], v[212:215], v[168:171], v[0:3]
	v_mfma_f32_16x16x32_bf16 v[28:31], v[192:195], v[142:145], v[28:31]
	v_mfma_f32_16x16x32_bf16 v[20:23], v[200:203], v[142:145], v[20:23]
	v_mfma_f32_16x16x32_bf16 v[220:223], v[208:211], v[142:145], v[12:15]
	v_mfma_f32_16x16x32_bf16 v[138:141], v[216:219], v[142:145], v[4:7]
	v_mfma_f32_16x16x32_bf16 v[142:145], v[216:219], v[172:175], v[0:3]
	v_mfma_f32_16x16x32_bf16 v[0:3], v[100:103], v[176:179], v[52:55]
	v_mfma_f32_16x16x32_bf16 v[24:27], v[100:103], v[168:171], v[24:27]
	v_mfma_f32_16x16x32_bf16 v[16:19], v[196:199], v[168:171], v[16:19]
	v_mfma_f32_16x16x32_bf16 v[8:11], v[204:207], v[168:171], v[8:11]
	v_mfma_f32_16x16x32_bf16 v[168:171], v[192:195], v[180:183], v[0:3]
	v_mfma_f32_16x16x32_bf16 v[0:3], v[100:103], v[184:187], v[60:63]
	v_mfma_f32_16x16x32_bf16 v[24:27], v[192:195], v[172:175], v[24:27]
	v_mfma_f32_16x16x32_bf16 v[16:19], v[200:203], v[172:175], v[16:19]
	v_mfma_f32_16x16x32_bf16 v[228:231], v[208:211], v[172:175], v[8:11]
	v_mfma_f32_16x16x32_bf16 v[172:175], v[192:195], v[188:191], v[0:3]
	v_mfma_f32_16x16x32_bf16 v[0:3], v[196:199], v[176:179], v[64:67]
	v_mfma_f32_16x16x32_bf16 v[192:195], v[200:203], v[180:183], v[0:3]
	v_mfma_f32_16x16x32_bf16 v[0:3], v[196:199], v[184:187], v[68:71]
	v_mfma_f32_16x16x32_bf16 v[196:199], v[200:203], v[188:191], v[0:3]
	v_mfma_f32_16x16x32_bf16 v[0:3], v[204:207], v[176:179], v[76:79]
	v_mfma_f32_16x16x32_bf16 v[200:203], v[208:211], v[180:183], v[0:3]
	v_mfma_f32_16x16x32_bf16 v[0:3], v[204:207], v[184:187], v[80:83]
	v_mfma_f32_16x16x32_bf16 v[204:207], v[208:211], v[188:191], v[0:3]
	v_mfma_f32_16x16x32_bf16 v[0:3], v[212:215], v[176:179], v[84:87]
	v_mfma_f32_16x16x32_bf16 v[176:179], v[216:219], v[180:183], v[0:3]
	v_mfma_f32_16x16x32_bf16 v[0:3], v[212:215], v[184:187], v[92:95]
	v_mfma_f32_16x16x32_bf16 v[180:183], v[216:219], v[188:191], v[0:3]
	s_barrier
; #define LDA(dst, b, h) _Pragma("unroll") for (int m = 0; m < 4; ++m) _Pragma("unroll") for (int k = 0; k < 2; ++k) \
;     dst[m][k] = *reinterpret_cast<const bf16x8*>((const char*)shm + aB + (((b) * 2 + (h)) * 16384 + (m * 2 + k) * 1024))
; #define LDB(dst, b, h) _Pragma("unroll") for (int n = 0; n < 2; ++n) _Pragma("unroll") for (int k = 0; k < 2; ++k) \
;     dst[n][k] = *reinterpret_cast<const bf16x8*>((const char*)shm + bB + (((b) * 2 + (h)) * 16384 + (n * 2 + k) * 1024))
; #define WAIT_L(n) asm volatile("s_waitcnt lgkmcnt(" #n ")" ::: "memory")
; #define BAR __builtin_amdgcn_s_barrier()
; #define SCHED __builtin_amdgcn_sched_barrier(0)
; template <int MODE> ...
;     ...
;       LDB(B0, 1, 0); LDB(B1, 1, 1); LDA(At, 1, 0); WAIT_L(0); BAR; MMA2(0, 0, 0, 1); BAR; SCHED;
;       LDA(At, 1, 1); WAIT_L(0); BAR; MMA2(1, 0, 1, 1); BAR; SCHED;
;     }
;     ...
;     if (wr == 0) BAR;
	s_setprio 0
	ds_read_b128 v[64:67], v149 offset:32768
	ds_read_b128 v[184:187], v149 offset:33792
	ds_read_b128 v[188:191], v149 offset:34816
	ds_read_b128 v[208:211], v149 offset:35840
	ds_read_b128 v[212:215], v149 offset:49152
	ds_read_b128 v[216:219], v149 offset:50176
	ds_read_b128 v[232:235], v149 offset:51200
	ds_read_b128 v[236:239], v149 offset:52224
	ds_read_b128 v[8:11], v148 offset:32768
	ds_read_b128 v[52:55], v148 offset:33792
	ds_read_b128 v[60:63], v148 offset:34816
	ds_read_b128 v[68:71], v148 offset:35840
	ds_read_b128 v[76:79], v148 offset:36864
	ds_read_b128 v[80:83], v148 offset:37888
	ds_read_b128 v[240:243], v148 offset:38912
	ds_read_b128 v[244:247], v148 offset:39936
	s_waitcnt lgkmcnt(0)
	s_setprio 1
	s_barrier
	v_mfma_f32_16x16x32_bf16 v[12:15], v[60:63], v[64:67], v[116:119]
	v_mfma_f32_16x16x32_bf16 v[0:3], v[8:11], v[64:67], v[124:127]
	v_mfma_f32_16x16x32_bf16 v[124:127], v[68:71], v[184:187], v[12:15]
	v_mfma_f32_16x16x32_bf16 v[12:15], v[60:63], v[188:191], v[112:115]
	v_mfma_f32_16x16x32_bf16 v[116:119], v[68:71], v[208:211], v[12:15]
	v_mfma_f32_16x16x32_bf16 v[12:15], v[76:79], v[64:67], v[108:111]
	v_mfma_f32_16x16x32_bf16 v[108:111], v[80:83], v[184:187], v[12:15]
	v_mfma_f32_16x16x32_bf16 v[12:15], v[76:79], v[188:191], v[104:107]
	v_mfma_f32_16x16x32_bf16 v[100:103], v[80:83], v[208:211], v[12:15]
	v_mfma_f32_16x16x32_bf16 v[12:15], v[240:243], v[64:67], v[224:227]
	v_mfma_f32_16x16x32_bf16 v[92:95], v[244:247], v[184:187], v[12:15]
	v_mfma_f32_16x16x32_bf16 v[12:15], v[240:243], v[188:191], v[96:99]
	v_mfma_f32_16x16x32_bf16 v[4:7], v[52:55], v[184:187], v[0:3]
	v_mfma_f32_16x16x32_bf16 v[0:3], v[8:11], v[188:191], v[120:123]
	v_mfma_f32_16x16x32_bf16 v[84:87], v[244:247], v[208:211], v[12:15]
	v_mfma_f32_16x16x32_bf16 v[12:15], v[8:11], v[212:215], v[88:91]
	v_mfma_f32_16x16x32_bf16 v[8:11], v[8:11], v[232:235], v[72:75]
	v_mfma_f32_16x16x32_bf16 v[0:3], v[52:55], v[208:211], v[0:3]
	v_mfma_f32_16x16x32_bf16 v[12:15], v[52:55], v[216:219], v[12:15]
	v_mfma_f32_16x16x32_bf16 v[8:11], v[52:55], v[236:239], v[8:11]
	v_mfma_f32_16x16x32_bf16 v[52:55], v[60:63], v[212:215], v[56:59]
	v_mfma_f32_16x16x32_bf16 v[48:51], v[60:63], v[232:235], v[48:51]
	v_mfma_f32_16x16x32_bf16 v[44:47], v[76:79], v[212:215], v[44:47]
	v_mfma_f32_16x16x32_bf16 v[40:43], v[76:79], v[232:235], v[40:43]
	v_mfma_f32_16x16x32_bf16 v[36:39], v[240:243], v[212:215], v[36:39]
	v_mfma_f32_16x16x32_bf16 v[32:35], v[240:243], v[232:235], v[32:35]
	v_mfma_f32_16x16x32_bf16 v[120:123], v[68:71], v[216:219], v[52:55]
	v_mfma_f32_16x16x32_bf16 v[112:115], v[68:71], v[236:239], v[48:51]
	v_mfma_f32_16x16x32_bf16 v[104:107], v[80:83], v[216:219], v[44:47]
	v_mfma_f32_16x16x32_bf16 v[96:99], v[80:83], v[236:239], v[40:43]
	v_mfma_f32_16x16x32_bf16 v[88:91], v[244:247], v[216:219], v[36:39]
	v_mfma_f32_16x16x32_bf16 v[80:83], v[244:247], v[236:239], v[32:35]
	s_barrier
	s_setprio 0
	s_nop 0
	ds_read_b128 v[32:35], v148 offset:49152
	ds_read_b128 v[40:43], v148 offset:50176
	ds_read_b128 v[48:51], v148 offset:51200
	ds_read_b128 v[224:227], v148 offset:52224
	ds_read_b128 v[240:243], v148 offset:53248
	ds_read_b128 v[244:247], v148 offset:54272
	ds_read_b128 v[248:251], v148 offset:55296
	ds_read_b128 v[130:133], v148 offset:56320
	s_waitcnt lgkmcnt(0)
	s_setprio 1
	s_barrier
	v_mfma_f32_16x16x32_bf16 v[24:27], v[32:35], v[188:191], v[24:27]
	v_mfma_f32_16x16x32_bf16 v[16:19], v[48:51], v[188:191], v[16:19]
	v_mfma_f32_16x16x32_bf16 v[68:71], v[40:43], v[208:211], v[24:27]
	v_mfma_f32_16x16x32_bf16 v[52:55], v[224:227], v[208:211], v[16:19]
	v_mfma_f32_16x16x32_bf16 v[16:19], v[240:243], v[64:67], v[220:223]
	v_mfma_f32_16x16x32_bf16 v[24:27], v[32:35], v[212:215], v[168:171]
	v_mfma_f32_16x16x32_bf16 v[44:47], v[244:247], v[184:187], v[16:19]
	v_mfma_f32_16x16x32_bf16 v[16:19], v[240:243], v[188:191], v[228:231]
	v_mfma_f32_16x16x32_bf16 v[72:75], v[40:43], v[216:219], v[24:27]
	v_mfma_f32_16x16x32_bf16 v[24:27], v[32:35], v[232:235], v[172:175]
	v_mfma_f32_16x16x32_bf16 v[28:31], v[32:35], v[64:67], v[28:31]
	v_mfma_f32_16x16x32_bf16 v[20:23], v[48:51], v[64:67], v[20:23]
	v_mfma_f32_16x16x32_bf16 v[36:39], v[244:247], v[208:211], v[16:19]
	v_mfma_f32_16x16x32_bf16 v[16:19], v[248:251], v[64:67], v[138:141]
	v_mfma_f32_16x16x32_bf16 v[64:67], v[40:43], v[236:239], v[24:27]
	v_mfma_f32_16x16x32_bf16 v[24:27], v[48:51], v[212:215], v[192:195]
	v_mfma_f32_16x16x32_bf16 v[56:59], v[224:227], v[216:219], v[24:27]
	v_mfma_f32_16x16x32_bf16 v[24:27], v[48:51], v[232:235], v[196:199]
	v_mfma_f32_16x16x32_bf16 v[48:51], v[224:227], v[236:239], v[24:27]
	v_mfma_f32_16x16x32_bf16 v[24:27], v[240:243], v[212:215], v[200:203]
	v_mfma_f32_16x16x32_bf16 v[76:79], v[40:43], v[184:187], v[28:31]
	v_mfma_f32_16x16x32_bf16 v[40:43], v[244:247], v[216:219], v[24:27]
	v_mfma_f32_16x16x32_bf16 v[24:27], v[240:243], v[232:235], v[204:207]
	v_mfma_f32_16x16x32_bf16 v[32:35], v[244:247], v[236:239], v[24:27]
	v_mfma_f32_16x16x32_bf16 v[24:27], v[248:251], v[212:215], v[176:179]
	v_mfma_f32_16x16x32_bf16 v[60:63], v[224:227], v[184:187], v[20:23]
	v_mfma_f32_16x16x32_bf16 v[20:23], v[130:133], v[184:187], v[16:19]
	v_mfma_f32_16x16x32_bf16 v[16:19], v[248:251], v[188:191], v[142:145]
	v_mfma_f32_16x16x32_bf16 v[28:31], v[130:133], v[216:219], v[24:27]
	v_mfma_f32_16x16x32_bf16 v[24:27], v[248:251], v[232:235], v[180:183]
	v_mfma_f32_16x16x32_bf16 v[16:19], v[130:133], v[208:211], v[16:19]
	v_mfma_f32_16x16x32_bf16 v[24:27], v[130:133], v[236:239], v[24:27]
	s_barrier
	s_setprio 0
	s_and_saveexec_b64 s[8:9], s[6:7]
	s_cbranch_execz .LBB0_594
	s_barrier

; #define STAGE(Pp, BASE, br, kt) do { const u16* _g = (BASE) + ((long)(br) * K + (long)(kt) * BK); \
;     __builtin_amdgcn_global_load_lds((const unsigned*)(_g + voff0), (unsigned*)((char*)(Pp) + tb16), 16, 0, 0); \
;     __builtin_amdgcn_global_load_lds((const unsigned*)(_g + voff1), (unsigned*)((char*)(Pp) + tb16 + 8192), 16, 0, 0); } while (0)
; #define LDA(dst, b, h) _Pragma("unroll") for (int m = 0; m < 4; ++m) _Pragma("unroll") for (int k = 0; k < 2; ++k) \
;     dst[m][k] = *reinterpret_cast<const bf16x8*>((const char*)shm + aB + (((b) * 2 + (h)) * 16384 + (m * 2 + k) * 1024))
; #define LDB(dst, b, h) _Pragma("unroll") for (int n = 0; n < 2; ++n) _Pragma("unroll") for (int k = 0; k < 2; ++k) \
;     dst[n][k] = *reinterpret_cast<const bf16x8*>((const char*)shm + bB + (((b) * 2 + (h)) * 16384 + (n * 2 + k) * 1024))
; #define WAIT_V(n) asm volatile("s_waitcnt vmcnt(" #n ")" ::: "memory")
; #define WAIT_L(n) asm volatile("s_waitcnt lgkmcnt(" #n ")" ::: "memory")
; #define BAR __builtin_amdgcn_s_barrier()
; #define SCHED __builtin_amdgcn_sched_barrier(0)
; template <int MODE> ...
;     ...
;       LDB(B0, 0, 0); LDB(B1, 0, 1); LDA(At, 0, 0); STAGE(SA(1, 1), A, brow + HALF, t + 1);
;       WAIT_L(0); BAR; MMA2(0, 0, 0, 1); BAR; SCHED;
;       LDA(At, 0, 1); STAGE(SB(0, 0), Bt, bcol, t + 2); STAGE(SB(0, 1), Bt, bcol + HALF, t + 2); STAGE(SA(0, 0), A, brow, t + 2);
;       WAIT_V(6); WAIT_L(0); BAR; MMA2(1, 0, 1, 1); BAR; SCHED;
.LBB0_848:
	s_add_u32 m0, s32, 0xc000
	s_add_u32 s88, s62, s22
	s_addc_u32 s89, s63, s23
	global_load_lds_dwordx4 v146, s[88:89]
	s_add_u32 m0, s32, 0xe000
	s_nop 0
	global_load_lds_dwordx4 v148, s[88:89]
	ds_read_b128 v[170:173], v151
	ds_read_b128 v[174:177], v151 offset:1024
	ds_read_b128 v[178:181], v151 offset:2048
	ds_read_b128 v[182:185], v151 offset:3072
	ds_read_b128 v[186:189], v151 offset:16384
	ds_read_b128 v[190:193], v151 offset:17408
	ds_read_b128 v[194:197], v151 offset:18432
	ds_read_b128 v[198:201], v151 offset:19456
	ds_read_b128 v[202:205], v150
	ds_read_b128 v[206:209], v150 offset:1024
	ds_read_b128 v[210:213], v150 offset:2048
	ds_read_b128 v[214:217], v150 offset:3072
	ds_read_b128 v[218:221], v150 offset:4096
	ds_read_b128 v[222:225], v150 offset:5120
	ds_read_b128 v[226:229], v150 offset:6144
	ds_read_b128 v[230:233], v150 offset:7168
	s_waitcnt vmcnt(8)
	s_waitcnt lgkmcnt(0)
	s_setprio 1
	s_barrier
	v_mfma_f32_16x16x32_bf16 v[124:127], v[202:205], v[170:173], v[124:127]
	v_mfma_f32_16x16x32_bf16 v[120:123], v[202:205], v[178:181], v[120:123]
	v_mfma_f32_16x16x32_bf16 v[116:119], v[210:213], v[170:173], v[116:119]
	v_mfma_f32_16x16x32_bf16 v[112:115], v[210:213], v[178:181], v[112:115]
	v_mfma_f32_16x16x32_bf16 v[108:111], v[218:221], v[170:173], v[108:111]
	v_mfma_f32_16x16x32_bf16 v[104:107], v[218:221], v[178:181], v[104:107]
	v_mfma_f32_16x16x32_bf16 v[100:103], v[226:229], v[170:173], v[100:103]
	v_mfma_f32_16x16x32_bf16 v[96:99], v[226:229], v[178:181], v[96:99]
	v_mfma_f32_16x16x32_bf16 v[92:95], v[202:205], v[186:189], v[92:95]
	v_mfma_f32_16x16x32_bf16 v[88:91], v[202:205], v[194:197], v[88:91]
	v_mfma_f32_16x16x32_bf16 v[84:87], v[210:213], v[186:189], v[84:87]
	v_mfma_f32_16x16x32_bf16 v[80:83], v[210:213], v[194:197], v[80:83]
	v_mfma_f32_16x16x32_bf16 v[76:79], v[218:221], v[186:189], v[76:79]
	v_mfma_f32_16x16x32_bf16 v[72:75], v[218:221], v[194:197], v[72:75]
	v_mfma_f32_16x16x32_bf16 v[68:71], v[226:229], v[186:189], v[68:71]
	v_mfma_f32_16x16x32_bf16 v[64:67], v[226:229], v[194:197], v[64:67]
	v_mfma_f32_16x16x32_bf16 v[124:127], v[206:209], v[174:177], v[124:127]
	v_mfma_f32_16x16x32_bf16 v[120:123], v[206:209], v[182:185], v[120:123]
	v_mfma_f32_16x16x32_bf16 v[116:119], v[214:217], v[174:177], v[116:119]
	v_mfma_f32_16x16x32_bf16 v[112:115], v[214:217], v[182:185], v[112:115]
	v_mfma_f32_16x16x32_bf16 v[108:111], v[222:225], v[174:177], v[108:111]
	v_mfma_f32_16x16x32_bf16 v[104:107], v[222:225], v[182:185], v[104:107]
	v_mfma_f32_16x16x32_bf16 v[100:103], v[230:233], v[174:177], v[100:103]
	v_mfma_f32_16x16x32_bf16 v[96:99], v[230:233], v[182:185], v[96:99]
	v_mfma_f32_16x16x32_bf16 v[92:95], v[206:209], v[190:193], v[92:95]
	v_mfma_f32_16x16x32_bf16 v[88:91], v[206:209], v[198:201], v[88:91]
	v_mfma_f32_16x16x32_bf16 v[84:87], v[214:217], v[190:193], v[84:87]
	v_mfma_f32_16x16x32_bf16 v[80:83], v[214:217], v[198:201], v[80:83]
	v_mfma_f32_16x16x32_bf16 v[76:79], v[222:225], v[190:193], v[76:79]
	v_mfma_f32_16x16x32_bf16 v[72:75], v[222:225], v[198:201], v[72:75]
	v_mfma_f32_16x16x32_bf16 v[68:71], v[230:233], v[190:193], v[68:71]
	v_mfma_f32_16x16x32_bf16 v[64:67], v[230:233], v[198:201], v[64:67]
	s_barrier
	s_setprio 0
	s_add_u32 m0, s32, 0x10000
	s_add_u32 s88, s62, s24
	s_addc_u32 s89, s63, s25
	global_load_lds_dwordx4 v138, s[88:89]
	s_add_u32 m0, s32, 0x12000
	s_add_u32 s90, s62, s26
	s_addc_u32 s91, s63, s27
	global_load_lds_dwordx4 v140, s[88:89]
	s_add_u32 m0, s32, 0x14000
	s_add_u32 s92, s62, s28
	s_addc_u32 s93, s63, s29
	global_load_lds_dwordx4 v142, s[90:91]
	s_add_u32 m0, s32, 0x16000
	s_nop 0
	global_load_lds_dwordx4 v144, s[90:91]
	s_mov_b32 m0, s32
	s_nop 0
	global_load_lds_dwordx4 v146, s[92:93]
	s_add_u32 m0, s32, 0x2000
	s_nop 0
	global_load_lds_dwordx4 v148, s[92:93]
	ds_read_b128 v[202:205], v150 offset:16384
	ds_read_b128 v[206:209], v150 offset:17408
	ds_read_b128 v[210:213], v150 offset:18432
	ds_read_b128 v[214:217], v150 offset:19456
	ds_read_b128 v[218:221], v150 offset:20480
	ds_read_b128 v[222:225], v150 offset:21504
	ds_read_b128 v[226:229], v150 offset:22528
	ds_read_b128 v[230:233], v150 offset:23552
	s_waitcnt vmcnt(8)
	s_waitcnt lgkmcnt(0)
	s_setprio 1
	s_barrier
	v_mfma_f32_16x16x32_bf16 v[60:63], v[202:205], v[170:173], v[60:63]
	v_mfma_f32_16x16x32_bf16 v[56:59], v[202:205], v[178:181], v[56:59]
	v_mfma_f32_16x16x32_bf16 v[52:55], v[210:213], v[170:173], v[52:55]
	v_mfma_f32_16x16x32_bf16 v[48:51], v[210:213], v[178:181], v[48:51]
	v_mfma_f32_16x16x32_bf16 v[44:47], v[218:221], v[170:173], v[44:47]
	v_mfma_f32_16x16x32_bf16 v[40:43], v[218:221], v[178:181], v[40:43]
	v_mfma_f32_16x16x32_bf16 v[36:39], v[226:229], v[170:173], v[36:39]
	v_mfma_f32_16x16x32_bf16 v[32:35], v[226:229], v[178:181], v[32:35]
	v_mfma_f32_16x16x32_bf16 v[28:31], v[202:205], v[186:189], v[28:31]
	v_mfma_f32_16x16x32_bf16 v[24:27], v[202:205], v[194:197], v[24:27]
	v_mfma_f32_16x16x32_bf16 v[20:23], v[210:213], v[186:189], v[20:23]
	v_mfma_f32_16x16x32_bf16 v[16:19], v[210:213], v[194:197], v[16:19]
	v_mfma_f32_16x16x32_bf16 v[12:15], v[218:221], v[186:189], v[12:15]
	v_mfma_f32_16x16x32_bf16 v[8:11], v[218:221], v[194:197], v[8:11]
	v_mfma_f32_16x16x32_bf16 v[4:7], v[226:229], v[186:189], v[4:7]
	v_mfma_f32_16x16x32_bf16 v[0:3], v[226:229], v[194:197], v[0:3]
	v_mfma_f32_16x16x32_bf16 v[60:63], v[206:209], v[174:177], v[60:63]
	v_mfma_f32_16x16x32_bf16 v[56:59], v[206:209], v[182:185], v[56:59]
	v_mfma_f32_16x16x32_bf16 v[52:55], v[214:217], v[174:177], v[52:55]
	v_mfma_f32_16x16x32_bf16 v[48:51], v[214:217], v[182:185], v[48:51]
	v_mfma_f32_16x16x32_bf16 v[44:47], v[222:225], v[174:177], v[44:47]
	v_mfma_f32_16x16x32_bf16 v[40:43], v[222:225], v[182:185], v[40:43]
	v_mfma_f32_16x16x32_bf16 v[36:39], v[230:233], v[174:177], v[36:39]
	v_mfma_f32_16x16x32_bf16 v[32:35], v[230:233], v[182:185], v[32:35]
	v_mfma_f32_16x16x32_bf16 v[28:31], v[206:209], v[190:193], v[28:31]
	v_mfma_f32_16x16x32_bf16 v[24:27], v[206:209], v[198:201], v[24:27]
	v_mfma_f32_16x16x32_bf16 v[20:23], v[214:217], v[190:193], v[20:23]
	v_mfma_f32_16x16x32_bf16 v[16:19], v[214:217], v[198:201], v[16:19]
	v_mfma_f32_16x16x32_bf16 v[12:15], v[222:225], v[190:193], v[12:15]
	v_mfma_f32_16x16x32_bf16 v[8:11], v[222:225], v[198:201], v[8:11]
	v_mfma_f32_16x16x32_bf16 v[4:7], v[230:233], v[190:193], v[4:7]
	v_mfma_f32_16x16x32_bf16 v[0:3], v[230:233], v[198:201], v[0:3]
	s_barrier
; #define STAGE(Pp, BASE, br, kt) do { const u16* _g = (BASE) + ((long)(br) * K + (long)(kt) * BK); \
;     __builtin_amdgcn_global_load_lds((const unsigned*)(_g + voff0), (unsigned*)((char*)(Pp) + tb16), 16, 0, 0); \
;     __builtin_amdgcn_global_load_lds((const unsigned*)(_g + voff1), (unsigned*)((char*)(Pp) + tb16 + 8192), 16, 0, 0); } while (0)
; #define LDA(dst, b, h) _Pragma("unroll") for (int m = 0; m < 4; ++m) _Pragma("unroll") for (int k = 0; k < 2; ++k) \
;     dst[m][k] = *reinterpret_cast<const bf16x8*>((const char*)shm + aB + (((b) * 2 + (h)) * 16384 + (m * 2 + k) * 1024))
; #define LDB(dst, b, h) _Pragma("unroll") for (int n = 0; n < 2; ++n) _Pragma("unroll") for (int k = 0; k < 2; ++k) \
;     dst[n][k] = *reinterpret_cast<const bf16x8*>((const char*)shm + bB + (((b) * 2 + (h)) * 16384 + (n * 2 + k) * 1024))
; #define WAIT_V(n) asm volatile("s_waitcnt vmcnt(" #n ")" ::: "memory")
; #define WAIT_L(n) asm volatile("s_waitcnt lgkmcnt(" #n ")" ::: "memory")
; #define BAR __builtin_amdgcn_s_barrier()
; #define SCHED __builtin_amdgcn_sched_barrier(0)
; template <int MODE> ...
;     ...
;       LDB(B0, 1, 0); LDB(B1, 1, 1); LDA(At, 1, 0); STAGE(SA(0, 1), A, brow + HALF, t + 2);
;       WAIT_L(0); BAR; MMA2(0, 0, 0, 1); BAR; SCHED;
;       LDA(At, 1, 1); STAGE(SB(1, 0), Bt, bcol, t + 3); STAGE(SB(1, 1), Bt, bcol + HALF, t + 3); STAGE(SA(1, 0), A, brow, t + 3);
;       WAIT_V(6); WAIT_L(0); BAR; MMA2(1, 0, 1, 1); BAR; SCHED;
	s_setprio 0
	s_add_u32 m0, s32, 0x4000
	s_add_u32 s88, s62, s36
	s_addc_u32 s89, s63, s37
	global_load_lds_dwordx4 v146, s[88:89]
	s_add_u32 m0, s32, 0x6000
	s_nop 0
	global_load_lds_dwordx4 v148, s[88:89]
	ds_read_b128 v[170:173], v151 offset:32768
	ds_read_b128 v[174:177], v151 offset:33792
	ds_read_b128 v[178:181], v151 offset:34816
	ds_read_b128 v[182:185], v151 offset:35840
	ds_read_b128 v[186:189], v151 offset:49152
	ds_read_b128 v[190:193], v151 offset:50176
	ds_read_b128 v[194:197], v151 offset:51200
	ds_read_b128 v[198:201], v151 offset:52224
	ds_read_b128 v[202:205], v150 offset:32768
	ds_read_b128 v[206:209], v150 offset:33792
	ds_read_b128 v[210:213], v150 offset:34816
	ds_read_b128 v[214:217], v150 offset:35840
	ds_read_b128 v[218:221], v150 offset:36864
	ds_read_b128 v[222:225], v150 offset:37888
	ds_read_b128 v[226:229], v150 offset:38912
	ds_read_b128 v[230:233], v150 offset:39936
	s_waitcnt vmcnt(8)
	s_waitcnt lgkmcnt(0)
	s_setprio 1
	s_barrier
	v_mfma_f32_16x16x32_bf16 v[124:127], v[202:205], v[170:173], v[124:127]
	v_mfma_f32_16x16x32_bf16 v[120:123], v[202:205], v[178:181], v[120:123]
	v_mfma_f32_16x16x32_bf16 v[116:119], v[210:213], v[170:173], v[116:119]
	v_mfma_f32_16x16x32_bf16 v[112:115], v[210:213], v[178:181], v[112:115]
	v_mfma_f32_16x16x32_bf16 v[108:111], v[218:221], v[170:173], v[108:111]
	v_mfma_f32_16x16x32_bf16 v[104:107], v[218:221], v[178:181], v[104:107]
	v_mfma_f32_16x16x32_bf16 v[100:103], v[226:229], v[170:173], v[100:103]
	v_mfma_f32_16x16x32_bf16 v[96:99], v[226:229], v[178:181], v[96:99]
	v_mfma_f32_16x16x32_bf16 v[92:95], v[202:205], v[186:189], v[92:95]
	v_mfma_f32_16x16x32_bf16 v[88:91], v[202:205], v[194:197], v[88:91]
	v_mfma_f32_16x16x32_bf16 v[84:87], v[210:213], v[186:189], v[84:87]
	v_mfma_f32_16x16x32_bf16 v[80:83], v[210:213], v[194:197], v[80:83]
	v_mfma_f32_16x16x32_bf16 v[76:79], v[218:221], v[186:189], v[76:79]
	v_mfma_f32_16x16x32_bf16 v[72:75], v[218:221], v[194:197], v[72:75]
	v_mfma_f32_16x16x32_bf16 v[68:71], v[226:229], v[186:189], v[68:71]
	v_mfma_f32_16x16x32_bf16 v[64:67], v[226:229], v[194:197], v[64:67]
	v_mfma_f32_16x16x32_bf16 v[124:127], v[206:209], v[174:177], v[124:127]
	v_mfma_f32_16x16x32_bf16 v[120:123], v[206:209], v[182:185], v[120:123]
	v_mfma_f32_16x16x32_bf16 v[116:119], v[214:217], v[174:177], v[116:119]
	v_mfma_f32_16x16x32_bf16 v[112:115], v[214:217], v[182:185], v[112:115]
	v_mfma_f32_16x16x32_bf16 v[108:111], v[222:225], v[174:177], v[108:111]
	v_mfma_f32_16x16x32_bf16 v[104:107], v[222:225], v[182:185], v[104:107]
	v_mfma_f32_16x16x32_bf16 v[100:103], v[230:233], v[174:177], v[100:103]
	v_mfma_f32_16x16x32_bf16 v[96:99], v[230:233], v[182:185], v[96:99]
	v_mfma_f32_16x16x32_bf16 v[92:95], v[206:209], v[190:193], v[92:95]
	v_mfma_f32_16x16x32_bf16 v[88:91], v[206:209], v[198:201], v[88:91]
	v_mfma_f32_16x16x32_bf16 v[84:87], v[214:217], v[190:193], v[84:87]
	v_mfma_f32_16x16x32_bf16 v[80:83], v[214:217], v[198:201], v[80:83]
	v_mfma_f32_16x16x32_bf16 v[76:79], v[222:225], v[190:193], v[76:79]
	v_mfma_f32_16x16x32_bf16 v[72:75], v[222:225], v[198:201], v[72:75]
	v_mfma_f32_16x16x32_bf16 v[68:71], v[230:233], v[190:193], v[68:71]
	v_mfma_f32_16x16x32_bf16 v[64:67], v[230:233], v[198:201], v[64:67]
	s_barrier
	s_setprio 0
	s_add_u32 m0, s32, 0x18000
	s_add_u32 s88, s62, s38
	s_addc_u32 s89, s63, s39
	global_load_lds_dwordx4 v138, s[88:89]
	s_add_u32 m0, s32, 0x1a000
	s_add_u32 s90, s62, s40
	s_addc_u32 s91, s63, s41
	global_load_lds_dwordx4 v140, s[88:89]
	s_add_u32 m0, s32, 0x1c000
	s_add_u32 s92, s62, s42
	s_addc_u32 s93, s63, s43
	global_load_lds_dwordx4 v142, s[90:91]
	s_add_u32 m0, s32, 0x1e000
	s_nop 0
	global_load_lds_dwordx4 v144, s[90:91]
	s_add_u32 m0, s32, 0x8000
	s_nop 0
	global_load_lds_dwordx4 v146, s[92:93]
	s_add_u32 m0, s32, 0xa000
	s_nop 0
	global_load_lds_dwordx4 v148, s[92:93]
	ds_read_b128 v[202:205], v150 offset:49152
	ds_read_b128 v[206:209], v150 offset:50176
	ds_read_b128 v[210:213], v150 offset:51200
	ds_read_b128 v[214:217], v150 offset:52224
	ds_read_b128 v[218:221], v150 offset:53248
	ds_read_b128 v[222:225], v150 offset:54272
	ds_read_b128 v[226:229], v150 offset:55296
	ds_read_b128 v[230:233], v150 offset:56320
	s_waitcnt vmcnt(8)
	s_waitcnt lgkmcnt(0)
	s_setprio 1
	s_barrier
	v_mfma_f32_16x16x32_bf16 v[60:63], v[202:205], v[170:173], v[60:63]
	v_mfma_f32_16x16x32_bf16 v[56:59], v[202:205], v[178:181], v[56:59]
	v_mfma_f32_16x16x32_bf16 v[52:55], v[210:213], v[170:173], v[52:55]
	v_mfma_f32_16x16x32_bf16 v[48:51], v[210:213], v[178:181], v[48:51]
	v_mfma_f32_16x16x32_bf16 v[44:47], v[218:221], v[170:173], v[44:47]
	v_mfma_f32_16x16x32_bf16 v[40:43], v[218:221], v[178:181], v[40:43]
	v_mfma_f32_16x16x32_bf16 v[36:39], v[226:229], v[170:173], v[36:39]
	v_mfma_f32_16x16x32_bf16 v[32:35], v[226:229], v[178:181], v[32:35]
	v_mfma_f32_16x16x32_bf16 v[28:31], v[202:205], v[186:189], v[28:31]
	v_mfma_f32_16x16x32_bf16 v[24:27], v[202:205], v[194:197], v[24:27]
	v_mfma_f32_16x16x32_bf16 v[20:23], v[210:213], v[186:189], v[20:23]
	v_mfma_f32_16x16x32_bf16 v[16:19], v[210:213], v[194:197], v[16:19]
	v_mfma_f32_16x16x32_bf16 v[12:15], v[218:221], v[186:189], v[12:15]
	v_mfma_f32_16x16x32_bf16 v[8:11], v[218:221], v[194:197], v[8:11]
	v_mfma_f32_16x16x32_bf16 v[4:7], v[226:229], v[186:189], v[4:7]
	v_mfma_f32_16x16x32_bf16 v[0:3], v[226:229], v[194:197], v[0:3]
	v_mfma_f32_16x16x32_bf16 v[60:63], v[206:209], v[174:177], v[60:63]
	v_mfma_f32_16x16x32_bf16 v[56:59], v[206:209], v[182:185], v[56:59]
	v_mfma_f32_16x16x32_bf16 v[52:55], v[214:217], v[174:177], v[52:55]
	v_mfma_f32_16x16x32_bf16 v[48:51], v[214:217], v[182:185], v[48:51]
	v_mfma_f32_16x16x32_bf16 v[44:47], v[222:225], v[174:177], v[44:47]
	v_mfma_f32_16x16x32_bf16 v[40:43], v[222:225], v[182:185], v[40:43]
	v_mfma_f32_16x16x32_bf16 v[36:39], v[230:233], v[174:177], v[36:39]
	v_mfma_f32_16x16x32_bf16 v[32:35], v[230:233], v[182:185], v[32:35]
	v_mfma_f32_16x16x32_bf16 v[28:31], v[206:209], v[190:193], v[28:31]
	v_mfma_f32_16x16x32_bf16 v[24:27], v[206:209], v[198:201], v[24:27]
	v_mfma_f32_16x16x32_bf16 v[20:23], v[214:217], v[190:193], v[20:23]
	v_mfma_f32_16x16x32_bf16 v[16:19], v[214:217], v[198:201], v[16:19]
	v_mfma_f32_16x16x32_bf16 v[12:15], v[222:225], v[190:193], v[12:15]
	v_mfma_f32_16x16x32_bf16 v[8:11], v[222:225], v[198:201], v[8:11]
	v_mfma_f32_16x16x32_bf16 v[4:7], v[230:233], v[190:193], v[4:7]
	v_mfma_f32_16x16x32_bf16 v[0:3], v[230:233], v[198:201], v[0:3]
	s_barrier
; #define STAGE(Pp, BASE, br, kt) do { const u16* _g = (BASE) + ((long)(br) * K + (long)(kt) * BK); \
;     __builtin_amdgcn_global_load_lds((const unsigned*)(_g + voff0), (unsigned*)((char*)(Pp) + tb16), 16, 0, 0); \
;     __builtin_amdgcn_global_load_lds((const unsigned*)(_g + voff1), (unsigned*)((char*)(Pp) + tb16 + 8192), 16, 0, 0); } while (0)
; #define LDA(dst, b, h) _Pragma("unroll") for (int m = 0; m < 4; ++m) _Pragma("unroll") for (int k = 0; k < 2; ++k) \
;     dst[m][k] = *reinterpret_cast<const bf16x8*>((const char*)shm + aB + (((b) * 2 + (h)) * 16384 + (m * 2 + k) * 1024))
; #define LDB(dst, b, h) _Pragma("unroll") for (int n = 0; n < 2; ++n) _Pragma("unroll") for (int k = 0; k < 2; ++k) \
;     dst[n][k] = *reinterpret_cast<const bf16x8*>((const char*)shm + bB + (((b) * 2 + (h)) * 16384 + (n * 2 + k) * 1024))
; #define WAIT_V(n) asm volatile("s_waitcnt vmcnt(" #n ")" ::: "memory")
; #define WAIT_L(n) asm volatile("s_waitcnt lgkmcnt(" #n ")" ::: "memory")
; #define BAR __builtin_amdgcn_s_barrier()
; #define SCHED __builtin_amdgcn_sched_barrier(0)
; template <int MODE> ...
;     ...
;     }
;     {
;       LDB(B0, 0, 0); LDB(B1, 0, 1); LDA(At, 0, 0); STAGE(SA(1, 1), A, brow + HALF, nt - 1);
;       WAIT_L(0); BAR; MMA2(0, 0, 0, 1); BAR; SCHED;
;       LDA(At, 0, 1); WAIT_V(0); WAIT_L(0); BAR; MMA2(1, 0, 1, 1); BAR; SCHED;
	s_setprio 0
	s_add_i32 s45, s45, 2
	s_add_u32 s62, s62, 0x100
	s_addc_u32 s63, s63, 0
	s_cmpk_lt_u32 s45, 0xa8
	s_cbranch_scc1 .LBB0_848
	s_add_u32 s60, s60, 0x5580
	v_readfirstlane_b32 s45, v167
	s_addc_u32 s61, s61, 0
	s_mov_b32 m0, s45
	v_readfirstlane_b32 s45, v168
	ds_read_b128 v[138:141], v151
	ds_read_b128 v[142:145], v151 offset:1024
	ds_read_b128 v[146:149], v151 offset:2048
	ds_read_b128 v[170:173], v151 offset:3072
	ds_read_b128 v[174:177], v151 offset:16384
	ds_read_b128 v[178:181], v151 offset:17408
	ds_read_b128 v[182:185], v151 offset:18432
	ds_read_b128 v[186:189], v151 offset:19456
	ds_read_b128 v[190:193], v150
	ds_read_b128 v[194:197], v150 offset:1024
	ds_read_b128 v[198:201], v150 offset:2048
	ds_read_b128 v[202:205], v150 offset:3072
	ds_read_b128 v[206:209], v150 offset:4096
	ds_read_b128 v[210:213], v150 offset:5120
	ds_read_b128 v[214:217], v150 offset:6144
	ds_read_b128 v[218:221], v150 offset:7168
	global_load_lds_dwordx4 v134, s[60:61]
	s_mov_b32 m0, s45
	s_nop 0
	global_load_lds_dwordx4 v136, s[60:61]
	s_waitcnt vmcnt(8)
	s_waitcnt lgkmcnt(0)
	s_setprio 1
	s_barrier
	v_mfma_f32_16x16x32_bf16 v[124:127], v[190:193], v[138:141], v[124:127]
	v_mfma_f32_16x16x32_bf16 v[116:119], v[198:201], v[138:141], v[116:119]
	v_mfma_f32_16x16x32_bf16 v[108:111], v[206:209], v[138:141], v[108:111]
	v_mfma_f32_16x16x32_bf16 v[100:103], v[214:217], v[138:141], v[100:103]
	v_mfma_f32_16x16x32_bf16 v[96:99], v[214:217], v[146:149], v[96:99]
	v_mfma_f32_16x16x32_bf16 v[92:95], v[190:193], v[174:177], v[92:95]
	v_mfma_f32_16x16x32_bf16 v[88:91], v[190:193], v[182:185], v[88:91]
	v_mfma_f32_16x16x32_bf16 v[80:83], v[198:201], v[182:185], v[80:83]
	v_mfma_f32_16x16x32_bf16 v[76:79], v[206:209], v[174:177], v[76:79]
	v_mfma_f32_16x16x32_bf16 v[124:127], v[194:197], v[142:145], v[124:127]
	v_mfma_f32_16x16x32_bf16 v[120:123], v[190:193], v[146:149], v[120:123]
	v_mfma_f32_16x16x32_bf16 v[116:119], v[202:205], v[142:145], v[116:119]
	v_mfma_f32_16x16x32_bf16 v[112:115], v[198:201], v[146:149], v[112:115]
	v_mfma_f32_16x16x32_bf16 v[108:111], v[210:213], v[142:145], v[108:111]
	v_mfma_f32_16x16x32_bf16 v[104:107], v[206:209], v[146:149], v[104:107]
	v_mfma_f32_16x16x32_bf16 v[100:103], v[218:221], v[142:145], v[100:103]
	v_mfma_f32_16x16x32_bf16 v[96:99], v[218:221], v[170:173], v[96:99]
	v_mfma_f32_16x16x32_bf16 v[92:95], v[194:197], v[178:181], v[92:95]
	v_mfma_f32_16x16x32_bf16 v[88:91], v[194:197], v[186:189], v[88:91]
	v_mfma_f32_16x16x32_bf16 v[84:87], v[198:201], v[174:177], v[84:87]
	v_mfma_f32_16x16x32_bf16 v[80:83], v[202:205], v[186:189], v[80:83]
	v_mfma_f32_16x16x32_bf16 v[76:79], v[210:213], v[178:181], v[76:79]
	v_mfma_f32_16x16x32_bf16 v[72:75], v[206:209], v[182:185], v[72:75]
	v_mfma_f32_16x16x32_bf16 v[68:71], v[214:217], v[174:177], v[68:71]
	v_mfma_f32_16x16x32_bf16 v[64:67], v[214:217], v[182:185], v[64:67]
	v_mfma_f32_16x16x32_bf16 v[222:225], v[194:197], v[170:173], v[120:123]
	v_mfma_f32_16x16x32_bf16 v[226:229], v[202:205], v[170:173], v[112:115]
	v_mfma_f32_16x16x32_bf16 v[230:233], v[210:213], v[170:173], v[104:107]
	v_mfma_f32_16x16x32_bf16 v[190:193], v[202:205], v[178:181], v[84:87]
	v_mfma_f32_16x16x32_bf16 v[194:197], v[210:213], v[186:189], v[72:75]
	v_mfma_f32_16x16x32_bf16 v[198:201], v[218:221], v[178:181], v[68:71]
	v_mfma_f32_16x16x32_bf16 v[202:205], v[218:221], v[186:189], v[64:67]
	s_barrier
	s_setprio 0
	s_nop 0
	ds_read_b128 v[64:67], v150 offset:16384
	ds_read_b128 v[68:71], v150 offset:17408
	ds_read_b128 v[72:75], v150 offset:18432
	ds_read_b128 v[84:87], v150 offset:19456
	ds_read_b128 v[104:107], v150 offset:20480
	ds_read_b128 v[112:115], v150 offset:21504
	ds_read_b128 v[120:123], v150 offset:22528
	ds_read_b128 v[206:209], v150 offset:23552
	s_waitcnt vmcnt(0)
	s_waitcnt lgkmcnt(0)
	s_setprio 1
	s_barrier
	v_mfma_f32_16x16x32_bf16 v[60:63], v[64:67], v[138:141], v[60:63]
	v_mfma_f32_16x16x32_bf16 v[56:59], v[64:67], v[146:149], v[56:59]
	v_mfma_f32_16x16x32_bf16 v[52:55], v[72:75], v[138:141], v[52:55]
	v_mfma_f32_16x16x32_bf16 v[48:51], v[72:75], v[146:149], v[48:51]
	v_mfma_f32_16x16x32_bf16 v[44:47], v[104:107], v[138:141], v[44:47]
	v_mfma_f32_16x16x32_bf16 v[40:43], v[104:107], v[146:149], v[40:43]
	v_mfma_f32_16x16x32_bf16 v[28:31], v[64:67], v[174:177], v[28:31]
	v_mfma_f32_16x16x32_bf16 v[24:27], v[64:67], v[182:185], v[24:27]
	v_mfma_f32_16x16x32_bf16 v[20:23], v[72:75], v[174:177], v[20:23]
	v_mfma_f32_16x16x32_bf16 v[60:63], v[68:71], v[142:145], v[60:63]
	v_mfma_f32_16x16x32_bf16 v[56:59], v[68:71], v[170:173], v[56:59]
	v_mfma_f32_16x16x32_bf16 v[52:55], v[84:87], v[142:145], v[52:55]
	v_mfma_f32_16x16x32_bf16 v[48:51], v[84:87], v[170:173], v[48:51]
	v_mfma_f32_16x16x32_bf16 v[44:47], v[112:115], v[142:145], v[44:47]
	v_mfma_f32_16x16x32_bf16 v[40:43], v[112:115], v[170:173], v[40:43]
	v_mfma_f32_16x16x32_bf16 v[36:39], v[120:123], v[138:141], v[36:39]
	v_mfma_f32_16x16x32_bf16 v[32:35], v[120:123], v[146:149], v[32:35]
	v_mfma_f32_16x16x32_bf16 v[28:31], v[68:71], v[178:181], v[28:31]
	v_mfma_f32_16x16x32_bf16 v[24:27], v[68:71], v[186:189], v[24:27]
	v_mfma_f32_16x16x32_bf16 v[20:23], v[84:87], v[178:181], v[20:23]
	v_mfma_f32_16x16x32_bf16 v[16:19], v[72:75], v[182:185], v[16:19]
	v_mfma_f32_16x16x32_bf16 v[12:15], v[104:107], v[174:177], v[12:15]
	v_mfma_f32_16x16x32_bf16 v[8:11], v[104:107], v[182:185], v[8:11]
	v_mfma_f32_16x16x32_bf16 v[4:7], v[120:123], v[174:177], v[4:7]
	v_mfma_f32_16x16x32_bf16 v[0:3], v[120:123], v[182:185], v[0:3]
	v_mfma_f32_16x16x32_bf16 v[138:141], v[206:209], v[142:145], v[36:39]
	v_mfma_f32_16x16x32_bf16 v[142:145], v[206:209], v[170:173], v[32:35]
	v_mfma_f32_16x16x32_bf16 v[146:149], v[84:87], v[186:189], v[16:19]
	v_mfma_f32_16x16x32_bf16 v[170:173], v[112:115], v[178:181], v[12:15]
	v_mfma_f32_16x16x32_bf16 v[210:213], v[112:115], v[186:189], v[8:11]
	v_mfma_f32_16x16x32_bf16 v[174:177], v[206:209], v[178:181], v[4:7]
	v_mfma_f32_16x16x32_bf16 v[178:181], v[206:209], v[186:189], v[0:3]
	s_barrier
; #define LDA(dst, b, h) _Pragma("unroll") for (int m = 0; m < 4; ++m) _Pragma("unroll") for (int k = 0; k < 2; ++k) \
;     dst[m][k] = *reinterpret_cast<const bf16x8*>((const char*)shm + aB + (((b) * 2 + (h)) * 16384 + (m * 2 + k) * 1024))
; #define LDB(dst, b, h) _Pragma("unroll") for (int n = 0; n < 2; ++n) _Pragma("unroll") for (int k = 0; k < 2; ++k) \
;     dst[n][k] = *reinterpret_cast<const bf16x8*>((const char*)shm + bB + (((b) * 2 + (h)) * 16384 + (n * 2 + k) * 1024))
; #define WAIT_L(n) asm volatile("s_waitcnt lgkmcnt(" #n ")" ::: "memory")
; #define BAR __builtin_amdgcn_s_barrier()
; #define SCHED __builtin_amdgcn_sched_barrier(0)
; template <int MODE> ...
;     ...
;       LDB(B0, 1, 0); LDB(B1, 1, 1); LDA(At, 1, 0); WAIT_L(0); BAR; MMA2(0, 0, 0, 1); BAR; SCHED;
;       LDA(At, 1, 1); WAIT_L(0); BAR; MMA2(1, 0, 1, 1); BAR; SCHED;
;     }
;     ...
;     if (wr == 0) BAR;
	s_setprio 0
	ds_read_b128 v[12:15], v151 offset:32768
	ds_read_b128 v[16:19], v151 offset:33792
	ds_read_b128 v[182:185], v151 offset:34816
	ds_read_b128 v[186:189], v151 offset:35840
	ds_read_b128 v[206:209], v151 offset:49152
	ds_read_b128 v[214:217], v151 offset:50176
	ds_read_b128 v[218:221], v151 offset:51200
	ds_read_b128 v[234:237], v151 offset:52224
	ds_read_b128 v[0:3], v150 offset:32768
	ds_read_b128 v[4:7], v150 offset:33792
	ds_read_b128 v[8:11], v150 offset:34816
	ds_read_b128 v[32:35], v150 offset:35840
	ds_read_b128 v[36:39], v150 offset:36864
	ds_read_b128 v[238:241], v150 offset:37888
	ds_read_b128 v[242:245], v150 offset:38912
	ds_read_b128 v[246:249], v150 offset:39936
	s_waitcnt lgkmcnt(0)
	s_setprio 1
	s_barrier
	v_mfma_f32_16x16x32_bf16 v[64:67], v[0:3], v[12:15], v[124:127]
	v_mfma_f32_16x16x32_bf16 v[68:71], v[242:245], v[182:185], v[96:99]
	v_mfma_f32_16x16x32_bf16 v[120:123], v[4:7], v[16:19], v[64:67]
	v_mfma_f32_16x16x32_bf16 v[64:67], v[0:3], v[182:185], v[222:225]
	v_mfma_f32_16x16x32_bf16 v[84:87], v[246:249], v[186:189], v[68:71]
	v_mfma_f32_16x16x32_bf16 v[68:71], v[0:3], v[206:209], v[92:95]
	v_mfma_f32_16x16x32_bf16 v[0:3], v[0:3], v[218:221], v[88:91]
	v_mfma_f32_16x16x32_bf16 v[88:91], v[4:7], v[234:237], v[0:3]
	v_mfma_f32_16x16x32_bf16 v[0:3], v[8:11], v[206:209], v[190:193]
	v_mfma_f32_16x16x32_bf16 v[124:127], v[4:7], v[186:189], v[64:67]
	v_mfma_f32_16x16x32_bf16 v[64:67], v[8:11], v[12:15], v[116:119]
	v_mfma_f32_16x16x32_bf16 v[72:75], v[32:35], v[214:217], v[0:3]
	v_mfma_f32_16x16x32_bf16 v[0:3], v[8:11], v[218:221], v[80:83]
	v_mfma_f32_16x16x32_bf16 v[112:115], v[32:35], v[16:19], v[64:67]
	v_mfma_f32_16x16x32_bf16 v[64:67], v[8:11], v[182:185], v[226:229]
	v_mfma_f32_16x16x32_bf16 v[92:95], v[32:35], v[234:237], v[0:3]
	v_mfma_f32_16x16x32_bf16 v[0:3], v[36:39], v[206:209], v[76:79]
	v_mfma_f32_16x16x32_bf16 v[116:119], v[32:35], v[186:189], v[64:67]
	v_mfma_f32_16x16x32_bf16 v[64:67], v[36:39], v[12:15], v[108:111]
	v_mfma_f32_16x16x32_bf16 v[76:79], v[238:241], v[214:217], v[0:3]
	v_mfma_f32_16x16x32_bf16 v[0:3], v[36:39], v[218:221], v[194:197]
	v_mfma_f32_16x16x32_bf16 v[104:107], v[238:241], v[16:19], v[64:67]
	v_mfma_f32_16x16x32_bf16 v[64:67], v[36:39], v[182:185], v[230:233]
	v_mfma_f32_16x16x32_bf16 v[96:99], v[238:241], v[234:237], v[0:3]
	v_mfma_f32_16x16x32_bf16 v[0:3], v[242:245], v[206:209], v[198:201]
	v_mfma_f32_16x16x32_bf16 v[108:111], v[238:241], v[186:189], v[64:67]
	v_mfma_f32_16x16x32_bf16 v[64:67], v[242:245], v[12:15], v[100:103]
	v_mfma_f32_16x16x32_bf16 v[80:83], v[246:249], v[214:217], v[0:3]
	v_mfma_f32_16x16x32_bf16 v[0:3], v[242:245], v[218:221], v[202:205]
	v_mfma_f32_16x16x32_bf16 v[64:67], v[246:249], v[16:19], v[64:67]
	v_mfma_f32_16x16x32_bf16 v[68:71], v[4:7], v[214:217], v[68:71]
	v_mfma_f32_16x16x32_bf16 v[100:103], v[246:249], v[234:237], v[0:3]
	s_barrier
	s_setprio 0
	ds_read_b128 v[190:193], v150 offset:49152
	ds_read_b128 v[194:197], v150 offset:50176
	ds_read_b128 v[198:201], v150 offset:51200
	ds_read_b128 v[202:205], v150 offset:52224
	ds_read_b128 v[222:225], v150 offset:53248
	ds_read_b128 v[226:229], v150 offset:54272
	ds_read_b128 v[230:233], v150 offset:55296
	ds_read_b128 v[238:241], v150 offset:56320
	s_waitcnt lgkmcnt(0)
	s_setprio 1
	s_barrier
	v_mfma_f32_16x16x32_bf16 v[4:7], v[190:193], v[182:185], v[56:59]
	v_mfma_f32_16x16x32_bf16 v[8:11], v[198:201], v[182:185], v[48:51]
	v_mfma_f32_16x16x32_bf16 v[0:3], v[190:193], v[12:15], v[60:63]
	v_mfma_f32_16x16x32_bf16 v[32:35], v[194:197], v[186:189], v[4:7]
	v_mfma_f32_16x16x32_bf16 v[4:7], v[198:201], v[12:15], v[52:55]
	v_mfma_f32_16x16x32_bf16 v[36:39], v[202:205], v[186:189], v[8:11]
	v_mfma_f32_16x16x32_bf16 v[8:11], v[222:225], v[12:15], v[44:47]
	v_mfma_f32_16x16x32_bf16 v[12:15], v[230:233], v[12:15], v[138:141]
	v_mfma_f32_16x16x32_bf16 v[0:3], v[194:197], v[16:19], v[0:3]
	v_mfma_f32_16x16x32_bf16 v[4:7], v[202:205], v[16:19], v[4:7]
	v_mfma_f32_16x16x32_bf16 v[8:11], v[226:229], v[16:19], v[8:11]
	v_mfma_f32_16x16x32_bf16 v[12:15], v[238:241], v[16:19], v[12:15]
	v_mfma_f32_16x16x32_bf16 v[16:19], v[230:233], v[182:185], v[142:145]
	v_mfma_f32_16x16x32_bf16 v[24:27], v[190:193], v[218:221], v[24:27]
	v_mfma_f32_16x16x32_bf16 v[44:47], v[238:241], v[186:189], v[16:19]
	v_mfma_f32_16x16x32_bf16 v[16:19], v[190:193], v[206:209], v[28:31]
	v_mfma_f32_16x16x32_bf16 v[48:51], v[194:197], v[234:237], v[24:27]
	v_mfma_f32_16x16x32_bf16 v[24:27], v[198:201], v[218:221], v[146:149]
	v_mfma_f32_16x16x32_bf16 v[28:31], v[222:225], v[218:221], v[210:213]
	v_mfma_f32_16x16x32_bf16 v[40:43], v[222:225], v[182:185], v[40:43]
	v_mfma_f32_16x16x32_bf16 v[20:23], v[198:201], v[206:209], v[20:23]
	v_mfma_f32_16x16x32_bf16 v[52:55], v[202:205], v[234:237], v[24:27]
	v_mfma_f32_16x16x32_bf16 v[24:27], v[222:225], v[206:209], v[170:173]
	v_mfma_f32_16x16x32_bf16 v[56:59], v[226:229], v[234:237], v[28:31]
	v_mfma_f32_16x16x32_bf16 v[28:31], v[230:233], v[206:209], v[174:177]
	v_mfma_f32_16x16x32_bf16 v[60:63], v[230:233], v[218:221], v[178:181]
	v_mfma_f32_16x16x32_bf16 v[40:43], v[226:229], v[186:189], v[40:43]
	v_mfma_f32_16x16x32_bf16 v[16:19], v[194:197], v[214:217], v[16:19]
	v_mfma_f32_16x16x32_bf16 v[20:23], v[202:205], v[214:217], v[20:23]
	v_mfma_f32_16x16x32_bf16 v[24:27], v[226:229], v[214:217], v[24:27]
	v_mfma_f32_16x16x32_bf16 v[28:31], v[238:241], v[214:217], v[28:31]
	v_mfma_f32_16x16x32_bf16 v[60:63], v[238:241], v[234:237], v[60:63]
	s_barrier
	s_setprio 0
	s_and_saveexec_b64 s[60:61], s[6:7]
	s_cbranch_execz .LBB0_851
	s_barrier
